# v33 + merged vmcnt/lgkmcnt wait before each GEMM-loop barrier, redundant post-barrier lgkmcnt(0) dropped
# speedup vs baseline: 1.0097x; 1.0097x over previous
.LBB0_80:
	s_add_u32 s2, s14, 0x100
	v_mov_b32_e32 v0, 0
	s_addc_u32 s8, s15, 0
	s_mov_b32 s9, -2
	v_mov_b32_e32 v1, v0
	v_mov_b32_e32 v2, v0
	v_mov_b32_e32 v3, v0
	v_mov_b32_e32 v6, v0
	s_waitcnt lgkmcnt(0)
	v_mov_b32_e32 v7, v0
	v_mov_b32_e32 v8, v0
	v_mov_b32_e32 v9, v0
	v_mov_b32_e32 v18, v0
	v_mov_b32_e32 v19, v0
	v_mov_b32_e32 v20, v0
	v_mov_b32_e32 v21, v0
	v_mov_b32_e32 v22, v0
	v_mov_b32_e32 v23, v0
	v_mov_b32_e32 v24, v0
	v_mov_b32_e32 v25, v0
	v_mov_b32_e32 v34, v0
	v_mov_b32_e32 v35, v0
	v_mov_b32_e32 v36, v0
	v_mov_b32_e32 v37, v0
	v_mov_b32_e32 v38, v0
	v_mov_b32_e32 v39, v0
	v_mov_b32_e32 v40, v0
	v_mov_b32_e32 v41, v0
	v_mov_b32_e32 v50, v0
	v_mov_b32_e32 v51, v0
	v_mov_b32_e32 v52, v0
	v_mov_b32_e32 v53, v0
	v_mov_b32_e32 v54, v0
	v_mov_b32_e32 v55, v0
	v_mov_b32_e32 v56, v0
	v_mov_b32_e32 v57, v0
	v_mov_b32_e32 v10, v0
	v_mov_b32_e32 v11, v0
	v_mov_b32_e32 v12, v0
	v_mov_b32_e32 v13, v0
	v_mov_b32_e32 v14, v0
	v_mov_b32_e32 v15, v0
	v_mov_b32_e32 v16, v0
	v_mov_b32_e32 v17, v0
	v_mov_b32_e32 v26, v0
	v_mov_b32_e32 v27, v0
	v_mov_b32_e32 v28, v0
	v_mov_b32_e32 v29, v0
	v_mov_b32_e32 v30, v0
	v_mov_b32_e32 v31, v0
	v_mov_b32_e32 v32, v0
	v_mov_b32_e32 v33, v0
	v_mov_b32_e32 v42, v0
	v_mov_b32_e32 v43, v0
	v_mov_b32_e32 v44, v0
	v_mov_b32_e32 v45, v0
	v_mov_b32_e32 v46, v0
	v_mov_b32_e32 v47, v0
	v_mov_b32_e32 v48, v0
	v_mov_b32_e32 v49, v0
	v_mov_b32_e32 v58, v0
	v_mov_b32_e32 v59, v0
	v_mov_b32_e32 v60, v0
	v_mov_b32_e32 v61, v0
	v_mov_b32_e32 v62, v0
	v_mov_b32_e32 v63, v0
	v_mov_b32_e32 v64, v0
	v_mov_b32_e32 v65, v0
	v_mov_b32_e32 v66, v0
	v_mov_b32_e32 v67, v0
	v_mov_b32_e32 v68, v0
	v_mov_b32_e32 v69, v0
	v_mov_b32_e32 v70, v0
	v_mov_b32_e32 v71, v0
	v_mov_b32_e32 v72, v0
	v_mov_b32_e32 v73, v0
	v_mov_b32_e32 v82, v0
	v_mov_b32_e32 v83, v0
	v_mov_b32_e32 v84, v0
	v_mov_b32_e32 v85, v0
	v_mov_b32_e32 v86, v0
	v_mov_b32_e32 v87, v0
	v_mov_b32_e32 v88, v0
	v_mov_b32_e32 v89, v0
	v_mov_b32_e32 v98, v0
	v_mov_b32_e32 v99, v0
	v_mov_b32_e32 v100, v0
	v_mov_b32_e32 v101, v0
	v_mov_b32_e32 v102, v0
	v_mov_b32_e32 v103, v0
	v_mov_b32_e32 v104, v0
	v_mov_b32_e32 v105, v0
	v_mov_b32_e32 v114, v0
	v_mov_b32_e32 v115, v0
	v_mov_b32_e32 v116, v0
	v_mov_b32_e32 v117, v0
	v_mov_b32_e32 v118, v0
	v_mov_b32_e32 v119, v0
	v_mov_b32_e32 v120, v0
	v_mov_b32_e32 v121, v0
	v_mov_b32_e32 v74, v0
	v_mov_b32_e32 v75, v0
	v_mov_b32_e32 v76, v0
	v_mov_b32_e32 v77, v0
	v_mov_b32_e32 v78, v0
	v_mov_b32_e32 v79, v0
	v_mov_b32_e32 v80, v0
	v_mov_b32_e32 v81, v0
	v_mov_b32_e32 v90, v0
	v_mov_b32_e32 v91, v0
	v_mov_b32_e32 v92, v0
	v_mov_b32_e32 v93, v0
	v_mov_b32_e32 v94, v0
	v_mov_b32_e32 v95, v0
	v_mov_b32_e32 v96, v0
	v_mov_b32_e32 v97, v0
	v_mov_b32_e32 v106, v0
	v_mov_b32_e32 v107, v0
	v_mov_b32_e32 v108, v0
	v_mov_b32_e32 v109, v0
	v_mov_b32_e32 v110, v0
	v_mov_b32_e32 v111, v0
	v_mov_b32_e32 v112, v0
	v_mov_b32_e32 v113, v0
	v_mov_b32_e32 v122, v0
	v_mov_b32_e32 v123, v0
	v_mov_b32_e32 v124, v0
	v_mov_b32_e32 v125, v0
	v_mov_b32_e32 v126, v0
	v_mov_b32_e32 v127, v0
	v_mov_b32_e32 v128, v0
	v_mov_b32_e32 v129, v0
	s_cmp_eq_u32 s36, 1
	s_cbranch_scc1 .LBB0_81
	s_add_u32 s14, s0, 0x100
	s_addc_u32 s15, s1, 0
	s_add_i32 s3, 0, 0x10000
	s_cmpk_eq_i32 s9, 0x7c
	s_cselect_b32 s27, s43, s15
	s_cselect_b32 s26, s42, s14
	v_add_u32_e32 v162, s3, v145
	s_cselect_b32 s23, s79, s8
	s_cselect_b32 s22, s78, s2
	s_add_i32 s4, 0, 0x14000
	ds_read_b128 v[140:143], v162
	ds_read_b128 v[148:151], v162 offset:1024
	ds_read_b128 v[172:175], v162 offset:2048
	ds_read_b128 v[190:193], v162 offset:3072
	v_add_u32_e32 v162, s4, v145
	ds_read_b128 v[194:197], v162
	ds_read_b128 v[198:201], v162 offset:1024
	ds_read_b128 v[202:205], v162 offset:2048
	ds_read_b128 v[206:209], v162 offset:3072
	s_add_i32 m0, s30, 0xc000
	ds_read_b128 v[210:213], v147
	ds_read_b128 v[214:217], v147 offset:1024
	ds_read_b128 v[218:221], v147 offset:2048
	ds_read_b128 v[222:225], v147 offset:3072
	ds_read_b128 v[226:229], v147 offset:4096
	ds_read_b128 v[230:233], v147 offset:5120
	ds_read_b128 v[234:237], v147 offset:6144
	ds_read_b128 v[238:241], v147 offset:7168
	global_load_lds_dwordx4 v136, s[0:1]
	s_add_i32 m0, s30, 0xe000
	s_nop 0
	global_load_lds_dwordx4 v138, s[0:1]
	s_waitcnt vmcnt(24) lgkmcnt(0)
	s_barrier
	v_mfma_f32_16x16x32_bf16 v[126:129], v[140:143], v[210:213], v[126:129]
	v_mfma_f32_16x16x32_bf16 v[122:125], v[172:175], v[210:213], v[122:125]
	v_mfma_f32_16x16x32_bf16 v[110:113], v[140:143], v[218:221], v[110:113]
	v_mfma_f32_16x16x32_bf16 v[106:109], v[172:175], v[218:221], v[106:109]
	v_mfma_f32_16x16x32_bf16 v[94:97], v[140:143], v[226:229], v[94:97]
	v_mfma_f32_16x16x32_bf16 v[90:93], v[172:175], v[226:229], v[90:93]
	v_mfma_f32_16x16x32_bf16 v[78:81], v[140:143], v[234:237], v[78:81]
	v_mfma_f32_16x16x32_bf16 v[74:77], v[172:175], v[234:237], v[74:77]
	v_mfma_f32_16x16x32_bf16 v[126:129], v[148:151], v[214:217], v[126:129]
	v_mfma_f32_16x16x32_bf16 v[122:125], v[190:193], v[214:217], v[122:125]
	v_mfma_f32_16x16x32_bf16 v[110:113], v[148:151], v[222:225], v[110:113]
	v_mfma_f32_16x16x32_bf16 v[106:109], v[190:193], v[222:225], v[106:109]
	v_mfma_f32_16x16x32_bf16 v[94:97], v[148:151], v[230:233], v[94:97]
	v_mfma_f32_16x16x32_bf16 v[90:93], v[190:193], v[230:233], v[90:93]
	v_mfma_f32_16x16x32_bf16 v[78:81], v[148:151], v[238:241], v[78:81]
	v_mfma_f32_16x16x32_bf16 v[74:77], v[190:193], v[238:241], v[74:77]
	v_mfma_f32_16x16x32_bf16 v[118:121], v[194:197], v[210:213], v[118:121]
	v_mfma_f32_16x16x32_bf16 v[114:117], v[202:205], v[210:213], v[114:117]
	v_mfma_f32_16x16x32_bf16 v[102:105], v[194:197], v[218:221], v[102:105]
	v_mfma_f32_16x16x32_bf16 v[98:101], v[202:205], v[218:221], v[98:101]
	v_mfma_f32_16x16x32_bf16 v[86:89], v[194:197], v[226:229], v[86:89]
	v_mfma_f32_16x16x32_bf16 v[82:85], v[202:205], v[226:229], v[82:85]
	v_mfma_f32_16x16x32_bf16 v[70:73], v[194:197], v[234:237], v[70:73]
	v_mfma_f32_16x16x32_bf16 v[66:69], v[202:205], v[234:237], v[66:69]
	v_mfma_f32_16x16x32_bf16 v[118:121], v[198:201], v[214:217], v[118:121]
	v_mfma_f32_16x16x32_bf16 v[114:117], v[206:209], v[214:217], v[114:117]
	v_mfma_f32_16x16x32_bf16 v[102:105], v[198:201], v[222:225], v[102:105]
	v_mfma_f32_16x16x32_bf16 v[98:101], v[206:209], v[222:225], v[98:101]
	v_mfma_f32_16x16x32_bf16 v[86:89], v[198:201], v[230:233], v[86:89]
	v_mfma_f32_16x16x32_bf16 v[82:85], v[206:209], v[230:233], v[82:85]
	v_mfma_f32_16x16x32_bf16 v[70:73], v[198:201], v[238:241], v[70:73]
	v_mfma_f32_16x16x32_bf16 v[66:69], v[206:209], v[238:241], v[66:69]
	s_barrier
	s_add_i32 s0, s3, s11
	v_lshl_add_u64 v[162:163], s[22:23], 0, v[4:5]
	s_mov_b32 m0, s0
	ds_read_b128 v[210:213], v147 offset:16384
	ds_read_b128 v[214:217], v147 offset:17408
	ds_read_b128 v[218:221], v147 offset:18432
	ds_read_b128 v[222:225], v147 offset:19456
	ds_read_b128 v[226:229], v147 offset:20480
	ds_read_b128 v[230:233], v147 offset:21504
	ds_read_b128 v[234:237], v147 offset:22528
	ds_read_b128 v[238:241], v147 offset:23552
	global_load_lds_dwordx4 v4, s[22:23]
	s_add_i32 m0, s0, 0x2000
	s_add_u32 s0, s22, 0x208000
	v_lshl_add_u64 v[166:167], s[22:23], 0, v[130:131]
	s_addc_u32 s1, s23, 0
	s_add_i32 s3, s4, s11
	global_load_lds_dwordx4 v130, s[22:23]
	s_mov_b32 m0, s3
	v_lshl_add_u64 v[180:181], s[26:27], 0, v[132:133]
	global_load_lds_dwordx4 v4, s[0:1]
	s_add_i32 m0, s3, 0x2000
	s_nop 0
	global_load_lds_dwordx4 v130, s[0:1]
	v_lshl_add_u64 v[176:177], s[26:27], 0, v[134:135]
	s_mov_b32 m0, s30
	s_nop 0
	global_load_lds_dwordx4 v134, s[26:27]
	s_mov_b32 m0, s31
	s_nop 0
	global_load_lds_dwordx4 v132, s[26:27]
	s_waitcnt vmcnt(24) lgkmcnt(0)
	s_barrier
	v_mfma_f32_16x16x32_bf16 v[62:65], v[140:143], v[210:213], v[62:65]
	v_mfma_f32_16x16x32_bf16 v[58:61], v[172:175], v[210:213], v[58:61]
	v_mfma_f32_16x16x32_bf16 v[46:49], v[140:143], v[218:221], v[46:49]
	v_mfma_f32_16x16x32_bf16 v[42:45], v[172:175], v[218:221], v[42:45]
	v_mfma_f32_16x16x32_bf16 v[30:33], v[140:143], v[226:229], v[30:33]
	v_mfma_f32_16x16x32_bf16 v[26:29], v[172:175], v[226:229], v[26:29]
	v_mfma_f32_16x16x32_bf16 v[14:17], v[140:143], v[234:237], v[14:17]
	v_mfma_f32_16x16x32_bf16 v[10:13], v[172:175], v[234:237], v[10:13]
	v_mfma_f32_16x16x32_bf16 v[62:65], v[148:151], v[214:217], v[62:65]
	v_mfma_f32_16x16x32_bf16 v[58:61], v[190:193], v[214:217], v[58:61]
	v_mfma_f32_16x16x32_bf16 v[46:49], v[148:151], v[222:225], v[46:49]
	v_mfma_f32_16x16x32_bf16 v[42:45], v[190:193], v[222:225], v[42:45]
	v_mfma_f32_16x16x32_bf16 v[30:33], v[148:151], v[230:233], v[30:33]
	v_mfma_f32_16x16x32_bf16 v[26:29], v[190:193], v[230:233], v[26:29]
	v_mfma_f32_16x16x32_bf16 v[14:17], v[148:151], v[238:241], v[14:17]
	v_mfma_f32_16x16x32_bf16 v[10:13], v[190:193], v[238:241], v[10:13]
	v_mfma_f32_16x16x32_bf16 v[54:57], v[194:197], v[210:213], v[54:57]
	v_mfma_f32_16x16x32_bf16 v[50:53], v[202:205], v[210:213], v[50:53]
	v_mfma_f32_16x16x32_bf16 v[38:41], v[194:197], v[218:221], v[38:41]
	v_mfma_f32_16x16x32_bf16 v[34:37], v[202:205], v[218:221], v[34:37]
	v_mfma_f32_16x16x32_bf16 v[22:25], v[194:197], v[226:229], v[22:25]
	v_mfma_f32_16x16x32_bf16 v[18:21], v[202:205], v[226:229], v[18:21]
	v_mfma_f32_16x16x32_bf16 v[6:9], v[194:197], v[234:237], v[6:9]
	v_mfma_f32_16x16x32_bf16 v[0:3], v[202:205], v[234:237], v[0:3]
	v_mfma_f32_16x16x32_bf16 v[54:57], v[198:201], v[214:217], v[54:57]
	v_mfma_f32_16x16x32_bf16 v[50:53], v[206:209], v[214:217], v[50:53]
	v_mfma_f32_16x16x32_bf16 v[38:41], v[198:201], v[222:225], v[38:41]
	v_mfma_f32_16x16x32_bf16 v[34:37], v[206:209], v[222:225], v[34:37]
	v_mfma_f32_16x16x32_bf16 v[22:25], v[198:201], v[230:233], v[22:25]
	v_mfma_f32_16x16x32_bf16 v[18:21], v[206:209], v[230:233], v[18:21]
	v_mfma_f32_16x16x32_bf16 v[6:9], v[198:201], v[238:241], v[6:9]
	v_mfma_f32_16x16x32_bf16 v[0:3], v[206:209], v[238:241], v[0:3]
	s_barrier
	s_branch .Lpeelmid_81
.LBB0_81:
	s_add_u32 s14, s0, 0x100
	s_addc_u32 s15, s1, 0
	s_add_i32 s3, 0, 0x10000
	s_cmpk_eq_i32 s9, 0x7c
	s_cselect_b32 s27, s43, s15
	s_cselect_b32 s26, s42, s14
	v_add_u32_e32 v162, s3, v145
	s_cselect_b32 s23, s79, s8
	s_cselect_b32 s22, s78, s2
	s_add_i32 s4, 0, 0x14000
	ds_read_b128 v[140:143], v162
	ds_read_b128 v[148:151], v162 offset:1024
	ds_read_b128 v[172:175], v162 offset:2048
	ds_read_b128 v[190:193], v162 offset:3072
	v_add_u32_e32 v162, s4, v145
	ds_read_b128 v[194:197], v162
	ds_read_b128 v[198:201], v162 offset:1024
	ds_read_b128 v[202:205], v162 offset:2048
	ds_read_b128 v[206:209], v162 offset:3072
	s_add_i32 m0, s30, 0xc000
	ds_read_b128 v[210:213], v147
	ds_read_b128 v[214:217], v147 offset:1024
	ds_read_b128 v[218:221], v147 offset:2048
	ds_read_b128 v[222:225], v147 offset:3072
	ds_read_b128 v[226:229], v147 offset:4096
	ds_read_b128 v[230:233], v147 offset:5120
	ds_read_b128 v[234:237], v147 offset:6144
	ds_read_b128 v[238:241], v147 offset:7168
	global_load_lds_dwordx4 v136, s[0:1]
	s_add_i32 m0, s30, 0xe000
	s_nop 0
	global_load_lds_dwordx4 v138, s[0:1]
	s_waitcnt vmcnt(8) lgkmcnt(0)
	s_barrier
	v_mfma_f32_16x16x32_bf16 v[126:129], v[140:143], v[210:213], v[126:129]
	v_mfma_f32_16x16x32_bf16 v[122:125], v[172:175], v[210:213], v[122:125]
	v_mfma_f32_16x16x32_bf16 v[110:113], v[140:143], v[218:221], v[110:113]
	v_mfma_f32_16x16x32_bf16 v[106:109], v[172:175], v[218:221], v[106:109]
	v_mfma_f32_16x16x32_bf16 v[94:97], v[140:143], v[226:229], v[94:97]
	v_mfma_f32_16x16x32_bf16 v[90:93], v[172:175], v[226:229], v[90:93]
	v_mfma_f32_16x16x32_bf16 v[78:81], v[140:143], v[234:237], v[78:81]
	v_mfma_f32_16x16x32_bf16 v[74:77], v[172:175], v[234:237], v[74:77]
	v_mfma_f32_16x16x32_bf16 v[126:129], v[148:151], v[214:217], v[126:129]
	v_mfma_f32_16x16x32_bf16 v[122:125], v[190:193], v[214:217], v[122:125]
	v_mfma_f32_16x16x32_bf16 v[110:113], v[148:151], v[222:225], v[110:113]
	v_mfma_f32_16x16x32_bf16 v[106:109], v[190:193], v[222:225], v[106:109]
	v_mfma_f32_16x16x32_bf16 v[94:97], v[148:151], v[230:233], v[94:97]
	v_mfma_f32_16x16x32_bf16 v[90:93], v[190:193], v[230:233], v[90:93]
	v_mfma_f32_16x16x32_bf16 v[78:81], v[148:151], v[238:241], v[78:81]
	v_mfma_f32_16x16x32_bf16 v[74:77], v[190:193], v[238:241], v[74:77]
	v_mfma_f32_16x16x32_bf16 v[118:121], v[194:197], v[210:213], v[118:121]
	v_mfma_f32_16x16x32_bf16 v[114:117], v[202:205], v[210:213], v[114:117]
	v_mfma_f32_16x16x32_bf16 v[102:105], v[194:197], v[218:221], v[102:105]
	v_mfma_f32_16x16x32_bf16 v[98:101], v[202:205], v[218:221], v[98:101]
	v_mfma_f32_16x16x32_bf16 v[86:89], v[194:197], v[226:229], v[86:89]
	v_mfma_f32_16x16x32_bf16 v[82:85], v[202:205], v[226:229], v[82:85]
	v_mfma_f32_16x16x32_bf16 v[70:73], v[194:197], v[234:237], v[70:73]
	v_mfma_f32_16x16x32_bf16 v[66:69], v[202:205], v[234:237], v[66:69]
	v_mfma_f32_16x16x32_bf16 v[118:121], v[198:201], v[214:217], v[118:121]
	v_mfma_f32_16x16x32_bf16 v[114:117], v[206:209], v[214:217], v[114:117]
	v_mfma_f32_16x16x32_bf16 v[102:105], v[198:201], v[222:225], v[102:105]
	v_mfma_f32_16x16x32_bf16 v[98:101], v[206:209], v[222:225], v[98:101]
	v_mfma_f32_16x16x32_bf16 v[86:89], v[198:201], v[230:233], v[86:89]
	v_mfma_f32_16x16x32_bf16 v[82:85], v[206:209], v[230:233], v[82:85]
	v_mfma_f32_16x16x32_bf16 v[70:73], v[198:201], v[238:241], v[70:73]
	v_mfma_f32_16x16x32_bf16 v[66:69], v[206:209], v[238:241], v[66:69]
	s_barrier
	s_add_i32 s0, s3, s11
	v_lshl_add_u64 v[162:163], s[22:23], 0, v[4:5]
	s_mov_b32 m0, s0
	ds_read_b128 v[210:213], v147 offset:16384
	ds_read_b128 v[214:217], v147 offset:17408
	ds_read_b128 v[218:221], v147 offset:18432
	ds_read_b128 v[222:225], v147 offset:19456
	ds_read_b128 v[226:229], v147 offset:20480
	ds_read_b128 v[230:233], v147 offset:21504
	ds_read_b128 v[234:237], v147 offset:22528
	ds_read_b128 v[238:241], v147 offset:23552
	global_load_lds_dwordx4 v4, s[22:23]
	s_add_i32 m0, s0, 0x2000
	s_add_u32 s0, s22, 0x208000
	v_lshl_add_u64 v[166:167], s[22:23], 0, v[130:131]
	s_addc_u32 s1, s23, 0
	s_add_i32 s3, s4, s11
	global_load_lds_dwordx4 v130, s[22:23]
	s_mov_b32 m0, s3
	v_lshl_add_u64 v[180:181], s[26:27], 0, v[132:133]
	global_load_lds_dwordx4 v4, s[0:1]
	s_add_i32 m0, s3, 0x2000
	s_nop 0
	global_load_lds_dwordx4 v130, s[0:1]
	v_lshl_add_u64 v[176:177], s[26:27], 0, v[134:135]
	s_mov_b32 m0, s30
	s_nop 0
	global_load_lds_dwordx4 v134, s[26:27]
	s_mov_b32 m0, s31
	s_nop 0
	global_load_lds_dwordx4 v132, s[26:27]
	s_waitcnt vmcnt(8) lgkmcnt(0)
	s_barrier
	v_mfma_f32_16x16x32_bf16 v[62:65], v[140:143], v[210:213], v[62:65]
	v_mfma_f32_16x16x32_bf16 v[58:61], v[172:175], v[210:213], v[58:61]
	v_mfma_f32_16x16x32_bf16 v[46:49], v[140:143], v[218:221], v[46:49]
	v_mfma_f32_16x16x32_bf16 v[42:45], v[172:175], v[218:221], v[42:45]
	v_mfma_f32_16x16x32_bf16 v[30:33], v[140:143], v[226:229], v[30:33]
	v_mfma_f32_16x16x32_bf16 v[26:29], v[172:175], v[226:229], v[26:29]
	v_mfma_f32_16x16x32_bf16 v[14:17], v[140:143], v[234:237], v[14:17]
	v_mfma_f32_16x16x32_bf16 v[10:13], v[172:175], v[234:237], v[10:13]
	v_mfma_f32_16x16x32_bf16 v[62:65], v[148:151], v[214:217], v[62:65]
	v_mfma_f32_16x16x32_bf16 v[58:61], v[190:193], v[214:217], v[58:61]
	v_mfma_f32_16x16x32_bf16 v[46:49], v[148:151], v[222:225], v[46:49]
	v_mfma_f32_16x16x32_bf16 v[42:45], v[190:193], v[222:225], v[42:45]
	v_mfma_f32_16x16x32_bf16 v[30:33], v[148:151], v[230:233], v[30:33]
	v_mfma_f32_16x16x32_bf16 v[26:29], v[190:193], v[230:233], v[26:29]
	v_mfma_f32_16x16x32_bf16 v[14:17], v[148:151], v[238:241], v[14:17]
	v_mfma_f32_16x16x32_bf16 v[10:13], v[190:193], v[238:241], v[10:13]
	v_mfma_f32_16x16x32_bf16 v[54:57], v[194:197], v[210:213], v[54:57]
	v_mfma_f32_16x16x32_bf16 v[50:53], v[202:205], v[210:213], v[50:53]
	v_mfma_f32_16x16x32_bf16 v[38:41], v[194:197], v[218:221], v[38:41]
	v_mfma_f32_16x16x32_bf16 v[34:37], v[202:205], v[218:221], v[34:37]
	v_mfma_f32_16x16x32_bf16 v[22:25], v[194:197], v[226:229], v[22:25]
	v_mfma_f32_16x16x32_bf16 v[18:21], v[202:205], v[226:229], v[18:21]
	v_mfma_f32_16x16x32_bf16 v[6:9], v[194:197], v[234:237], v[6:9]
	v_mfma_f32_16x16x32_bf16 v[0:3], v[202:205], v[234:237], v[0:3]
	v_mfma_f32_16x16x32_bf16 v[54:57], v[198:201], v[214:217], v[54:57]
	v_mfma_f32_16x16x32_bf16 v[50:53], v[206:209], v[214:217], v[50:53]
	v_mfma_f32_16x16x32_bf16 v[38:41], v[198:201], v[222:225], v[38:41]
	v_mfma_f32_16x16x32_bf16 v[34:37], v[206:209], v[222:225], v[34:37]
	v_mfma_f32_16x16x32_bf16 v[22:25], v[198:201], v[230:233], v[22:25]
	v_mfma_f32_16x16x32_bf16 v[18:21], v[206:209], v[230:233], v[18:21]
	v_mfma_f32_16x16x32_bf16 v[6:9], v[198:201], v[238:241], v[6:9]
	v_mfma_f32_16x16x32_bf16 v[0:3], v[206:209], v[238:241], v[0:3]
	s_barrier
.Lpeelmid_81:
	s_add_i32 s3, 0, 0x18000
	v_add_u32_e32 v164, s3, v145
	s_add_i32 s4, 0, 0x1c000
	ds_read_b128 v[140:143], v164
	ds_read_b128 v[148:151], v164 offset:1024
	ds_read_b128 v[172:175], v164 offset:2048
	ds_read_b128 v[190:193], v164 offset:3072
	v_add_u32_e32 v164, s4, v145
	ds_read_b128 v[194:197], v164
	ds_read_b128 v[198:201], v164 offset:1024
	ds_read_b128 v[202:205], v164 offset:2048
	ds_read_b128 v[206:209], v164 offset:3072
	s_add_u32 s0, s26, 0x208000
	s_addc_u32 s1, s27, 0
	s_mov_b32 m0, s34
	ds_read_b128 v[210:213], v147 offset:32768
	ds_read_b128 v[214:217], v147 offset:33792
	ds_read_b128 v[218:221], v147 offset:34816
	ds_read_b128 v[222:225], v147 offset:35840
	ds_read_b128 v[226:229], v147 offset:36864
	ds_read_b128 v[230:233], v147 offset:37888
	ds_read_b128 v[234:237], v147 offset:38912
	ds_read_b128 v[238:241], v147 offset:39936
	global_load_lds_dwordx4 v134, s[0:1]
	v_lshl_add_u64 v[242:243], s[0:1], 0, v[132:133]
	s_mov_b32 m0, s35
	s_nop 0
	global_load_lds_dwordx4 v132, s[0:1]
	s_waitcnt vmcnt(8) lgkmcnt(0)
	s_barrier
	v_mfma_f32_16x16x32_bf16 v[126:129], v[140:143], v[210:213], v[126:129]
	v_mfma_f32_16x16x32_bf16 v[122:125], v[172:175], v[210:213], v[122:125]
	v_mfma_f32_16x16x32_bf16 v[110:113], v[140:143], v[218:221], v[110:113]
	v_mfma_f32_16x16x32_bf16 v[106:109], v[172:175], v[218:221], v[106:109]
	v_mfma_f32_16x16x32_bf16 v[94:97], v[140:143], v[226:229], v[94:97]
	v_mfma_f32_16x16x32_bf16 v[90:93], v[172:175], v[226:229], v[90:93]
	v_mfma_f32_16x16x32_bf16 v[78:81], v[140:143], v[234:237], v[78:81]
	v_mfma_f32_16x16x32_bf16 v[74:77], v[172:175], v[234:237], v[74:77]
	v_mfma_f32_16x16x32_bf16 v[126:129], v[148:151], v[214:217], v[126:129]
	v_mfma_f32_16x16x32_bf16 v[122:125], v[190:193], v[214:217], v[122:125]
	v_mfma_f32_16x16x32_bf16 v[110:113], v[148:151], v[222:225], v[110:113]
	v_mfma_f32_16x16x32_bf16 v[106:109], v[190:193], v[222:225], v[106:109]
	v_mfma_f32_16x16x32_bf16 v[94:97], v[148:151], v[230:233], v[94:97]
	v_mfma_f32_16x16x32_bf16 v[90:93], v[190:193], v[230:233], v[90:93]
	v_mfma_f32_16x16x32_bf16 v[78:81], v[148:151], v[238:241], v[78:81]
	v_mfma_f32_16x16x32_bf16 v[74:77], v[190:193], v[238:241], v[74:77]
	v_mfma_f32_16x16x32_bf16 v[118:121], v[194:197], v[210:213], v[118:121]
	v_mfma_f32_16x16x32_bf16 v[114:117], v[202:205], v[210:213], v[114:117]
	v_mfma_f32_16x16x32_bf16 v[102:105], v[194:197], v[218:221], v[102:105]
	v_mfma_f32_16x16x32_bf16 v[98:101], v[202:205], v[218:221], v[98:101]
	v_mfma_f32_16x16x32_bf16 v[86:89], v[194:197], v[226:229], v[86:89]
	v_mfma_f32_16x16x32_bf16 v[82:85], v[202:205], v[226:229], v[82:85]
	v_mfma_f32_16x16x32_bf16 v[70:73], v[194:197], v[234:237], v[70:73]
	v_mfma_f32_16x16x32_bf16 v[66:69], v[202:205], v[234:237], v[66:69]
	v_mfma_f32_16x16x32_bf16 v[118:121], v[198:201], v[214:217], v[118:121]
	v_mfma_f32_16x16x32_bf16 v[114:117], v[206:209], v[214:217], v[114:117]
	v_mfma_f32_16x16x32_bf16 v[102:105], v[198:201], v[222:225], v[102:105]
	v_mfma_f32_16x16x32_bf16 v[98:101], v[206:209], v[222:225], v[98:101]
	v_mfma_f32_16x16x32_bf16 v[86:89], v[198:201], v[230:233], v[86:89]
	v_mfma_f32_16x16x32_bf16 v[82:85], v[206:209], v[230:233], v[82:85]
	v_mfma_f32_16x16x32_bf16 v[70:73], v[198:201], v[238:241], v[70:73]
	v_mfma_f32_16x16x32_bf16 v[66:69], v[206:209], v[238:241], v[66:69]
	s_barrier
	s_add_i32 s0, s3, s11
	v_lshl_add_u64 v[162:163], v[162:163], 0, s[70:71]
	s_mov_b32 m0, s0
	ds_read_b128 v[210:213], v147 offset:49152
	ds_read_b128 v[214:217], v147 offset:50176
	ds_read_b128 v[218:221], v147 offset:51200
	ds_read_b128 v[222:225], v147 offset:52224
	ds_read_b128 v[226:229], v147 offset:53248
	ds_read_b128 v[230:233], v147 offset:54272
	ds_read_b128 v[234:237], v147 offset:55296
	ds_read_b128 v[238:241], v147 offset:56320
	global_load_lds_dwordx4 v[162:163], off
	s_add_i32 m0, s0, 0x2000
	s_add_u32 s0, s22, 0x208080
	v_lshl_add_u64 v[162:163], v[166:167], 0, s[70:71]
	s_addc_u32 s1, s23, 0
	s_add_i32 s3, s4, s11
	global_load_lds_dwordx4 v[162:163], off
	s_mov_b32 m0, s3
	s_nop 0
	global_load_lds_dwordx4 v4, s[0:1]
	s_add_i32 m0, s3, 0x2000
	s_nop 0
	global_load_lds_dwordx4 v130, s[0:1]
	v_lshl_add_u64 v[162:163], v[176:177], 0, s[70:71]
	s_mov_b32 m0, s51
	s_nop 0
	global_load_lds_dwordx4 v[162:163], off
	v_lshl_add_u64 v[162:163], v[180:181], 0, s[70:71]
	s_mov_b32 m0, s52
	s_nop 0
	global_load_lds_dwordx4 v[162:163], off
	s_waitcnt vmcnt(8) lgkmcnt(0)
	s_barrier
	v_mfma_f32_16x16x32_bf16 v[62:65], v[140:143], v[210:213], v[62:65]
	v_mfma_f32_16x16x32_bf16 v[58:61], v[172:175], v[210:213], v[58:61]
	v_mfma_f32_16x16x32_bf16 v[46:49], v[140:143], v[218:221], v[46:49]
	v_mfma_f32_16x16x32_bf16 v[42:45], v[172:175], v[218:221], v[42:45]
	v_mfma_f32_16x16x32_bf16 v[30:33], v[140:143], v[226:229], v[30:33]
	v_mfma_f32_16x16x32_bf16 v[26:29], v[172:175], v[226:229], v[26:29]
	v_mfma_f32_16x16x32_bf16 v[14:17], v[140:143], v[234:237], v[14:17]
	v_mfma_f32_16x16x32_bf16 v[10:13], v[172:175], v[234:237], v[10:13]
	v_mfma_f32_16x16x32_bf16 v[62:65], v[148:151], v[214:217], v[62:65]
	v_mfma_f32_16x16x32_bf16 v[58:61], v[190:193], v[214:217], v[58:61]
	v_mfma_f32_16x16x32_bf16 v[46:49], v[148:151], v[222:225], v[46:49]
	v_mfma_f32_16x16x32_bf16 v[42:45], v[190:193], v[222:225], v[42:45]
	v_mfma_f32_16x16x32_bf16 v[30:33], v[148:151], v[230:233], v[30:33]
	v_mfma_f32_16x16x32_bf16 v[26:29], v[190:193], v[230:233], v[26:29]
	v_mfma_f32_16x16x32_bf16 v[14:17], v[148:151], v[238:241], v[14:17]
	v_mfma_f32_16x16x32_bf16 v[10:13], v[190:193], v[238:241], v[10:13]
	v_mfma_f32_16x16x32_bf16 v[54:57], v[194:197], v[210:213], v[54:57]
	v_mfma_f32_16x16x32_bf16 v[50:53], v[202:205], v[210:213], v[50:53]
	v_mfma_f32_16x16x32_bf16 v[38:41], v[194:197], v[218:221], v[38:41]
	v_mfma_f32_16x16x32_bf16 v[34:37], v[202:205], v[218:221], v[34:37]
	v_mfma_f32_16x16x32_bf16 v[22:25], v[194:197], v[226:229], v[22:25]
	v_mfma_f32_16x16x32_bf16 v[18:21], v[202:205], v[226:229], v[18:21]
	v_mfma_f32_16x16x32_bf16 v[6:9], v[194:197], v[234:237], v[6:9]
	v_mfma_f32_16x16x32_bf16 v[0:3], v[202:205], v[234:237], v[0:3]
	v_mfma_f32_16x16x32_bf16 v[54:57], v[198:201], v[214:217], v[54:57]
	v_mfma_f32_16x16x32_bf16 v[50:53], v[206:209], v[214:217], v[50:53]
	v_mfma_f32_16x16x32_bf16 v[38:41], v[198:201], v[222:225], v[38:41]
	v_mfma_f32_16x16x32_bf16 v[34:37], v[206:209], v[222:225], v[34:37]
	v_mfma_f32_16x16x32_bf16 v[22:25], v[198:201], v[230:233], v[22:25]
	v_mfma_f32_16x16x32_bf16 v[18:21], v[206:209], v[230:233], v[18:21]
	v_mfma_f32_16x16x32_bf16 v[6:9], v[198:201], v[238:241], v[6:9]
	v_mfma_f32_16x16x32_bf16 v[0:3], v[206:209], v[238:241], v[0:3]
	s_barrier
	s_add_i32 s9, s9, 2
	s_add_u32 s2, s2, 0x100
	s_addc_u32 s8, s8, 0
	s_cmpk_gt_u32 s9, 0x7d
	s_mov_b64 s[0:1], s[14:15]
	s_cbranch_scc0 .LBB0_81
	s_and_b64 vcc, exec, s[48:49]
	s_cbranch_vccz .LBB0_84
	s_barrier

.LBB0_123:
	s_ashr_i32 s3, s51, 24
	s_lshl_b32 s2, s51, 8
	s_andn2_b32 s3, s3, 63
	s_add_i32 s2, s3, s2
	s_ashr_i32 s3, s2, 31
	s_lshl_b64 s[2:3], s[2:3], 12
	s_add_u32 s48, s11, s2
	s_addc_u32 s49, s26, s3
	s_and_b64 s[2:3], s[38:39], exec
	s_cselect_b32 s2, s49, s1
	s_cselect_b32 s8, s48, s0
	s_ashr_i32 s47, s46, 31
	s_lshl_b64 s[4:5], s[46:47], 20
	v_readlane_b32 s6, v254, 1
	v_readlane_b32 s7, v254, 2
	s_add_u32 s78, s6, s4
	s_addc_u32 s79, s7, s5
	s_and_b64 s[4:5], s[38:39], exec
	s_cselect_b32 s10, s79, s15
	s_cselect_b32 s24, s78, s14
	s_add_u32 s22, s0, 0x80080
	s_addc_u32 s23, s1, 0
	s_add_u32 s9, s14, 0x100
	v_mov_b32_e32 v0, 0
	s_addc_u32 s25, s15, 0
	s_mov_b32 s28, -2
	v_mov_b32_e32 v1, v0
	v_mov_b32_e32 v2, v0
	v_mov_b32_e32 v3, v0
	v_mov_b32_e32 v6, v0
	v_mov_b32_e32 v7, v0
	v_mov_b32_e32 v8, v0
	v_mov_b32_e32 v9, v0
	v_mov_b32_e32 v10, v0
	v_mov_b32_e32 v11, v0
	v_mov_b32_e32 v12, v0
	v_mov_b32_e32 v13, v0
	v_mov_b32_e32 v14, v0
	v_mov_b32_e32 v15, v0
	v_mov_b32_e32 v16, v0
	v_mov_b32_e32 v17, v0
	v_mov_b32_e32 v18, v0
	v_mov_b32_e32 v19, v0
	v_mov_b32_e32 v20, v0
	v_mov_b32_e32 v21, v0
	v_mov_b32_e32 v22, v0
	v_mov_b32_e32 v23, v0
	v_mov_b32_e32 v24, v0
	v_mov_b32_e32 v25, v0
	v_mov_b32_e32 v26, v0
	v_mov_b32_e32 v27, v0
	v_mov_b32_e32 v28, v0
	v_mov_b32_e32 v29, v0
	v_mov_b32_e32 v30, v0
	v_mov_b32_e32 v31, v0
	v_mov_b32_e32 v32, v0
	v_mov_b32_e32 v33, v0
	v_mov_b32_e32 v58, v0
	v_mov_b32_e32 v59, v0
	v_mov_b32_e32 v60, v0
	v_mov_b32_e32 v61, v0
	v_mov_b32_e32 v62, v0
	v_mov_b32_e32 v63, v0
	v_mov_b32_e32 v64, v0
	v_mov_b32_e32 v65, v0
	v_mov_b32_e32 v74, v0
	v_mov_b32_e32 v75, v0
	v_mov_b32_e32 v76, v0
	v_mov_b32_e32 v77, v0
	v_mov_b32_e32 v78, v0
	v_mov_b32_e32 v79, v0
	v_mov_b32_e32 v80, v0
	v_mov_b32_e32 v81, v0
	v_mov_b32_e32 v82, v0
	v_mov_b32_e32 v83, v0
	v_mov_b32_e32 v84, v0
	v_mov_b32_e32 v85, v0
	v_mov_b32_e32 v86, v0
	v_mov_b32_e32 v87, v0
	v_mov_b32_e32 v88, v0
	v_mov_b32_e32 v89, v0
	v_mov_b32_e32 v90, v0
	v_mov_b32_e32 v91, v0
	v_mov_b32_e32 v92, v0
	v_mov_b32_e32 v93, v0
	v_mov_b32_e32 v94, v0
	v_mov_b32_e32 v95, v0
	v_mov_b32_e32 v96, v0
	v_mov_b32_e32 v97, v0
	v_mov_b32_e32 v34, v0
	v_mov_b32_e32 v35, v0
	v_mov_b32_e32 v36, v0
	v_mov_b32_e32 v37, v0
	v_mov_b32_e32 v38, v0
	v_mov_b32_e32 v39, v0
	v_mov_b32_e32 v40, v0
	v_mov_b32_e32 v41, v0
	v_mov_b32_e32 v42, v0
	v_mov_b32_e32 v43, v0
	v_mov_b32_e32 v44, v0
	v_mov_b32_e32 v45, v0
	v_mov_b32_e32 v46, v0
	v_mov_b32_e32 v47, v0
	v_mov_b32_e32 v48, v0
	v_mov_b32_e32 v49, v0
	v_mov_b32_e32 v50, v0
	v_mov_b32_e32 v51, v0
	v_mov_b32_e32 v52, v0
	v_mov_b32_e32 v53, v0
	v_mov_b32_e32 v54, v0
	v_mov_b32_e32 v55, v0
	v_mov_b32_e32 v56, v0
	v_mov_b32_e32 v57, v0
	v_mov_b32_e32 v66, v0
	v_mov_b32_e32 v67, v0
	v_mov_b32_e32 v68, v0
	v_mov_b32_e32 v69, v0
	v_mov_b32_e32 v70, v0
	v_mov_b32_e32 v71, v0
	v_mov_b32_e32 v72, v0
	v_mov_b32_e32 v73, v0
	v_mov_b32_e32 v98, v0
	v_mov_b32_e32 v99, v0
	v_mov_b32_e32 v100, v0
	v_mov_b32_e32 v101, v0
	v_mov_b32_e32 v102, v0
	v_mov_b32_e32 v103, v0
	v_mov_b32_e32 v104, v0
	v_mov_b32_e32 v105, v0
	v_mov_b32_e32 v106, v0
	v_mov_b32_e32 v107, v0
	v_mov_b32_e32 v108, v0
	v_mov_b32_e32 v109, v0
	v_mov_b32_e32 v110, v0
	v_mov_b32_e32 v111, v0
	v_mov_b32_e32 v112, v0
	v_mov_b32_e32 v113, v0
	v_mov_b32_e32 v114, v0
	v_mov_b32_e32 v115, v0
	v_mov_b32_e32 v116, v0
	v_mov_b32_e32 v117, v0
	v_mov_b32_e32 v118, v0
	v_mov_b32_e32 v119, v0
	v_mov_b32_e32 v120, v0
	v_mov_b32_e32 v121, v0
	v_mov_b32_e32 v122, v0
	v_mov_b32_e32 v123, v0
	v_mov_b32_e32 v124, v0
	v_mov_b32_e32 v125, v0
	v_mov_b32_e32 v126, v0
	v_mov_b32_e32 v127, v0
	v_mov_b32_e32 v128, v0
	v_mov_b32_e32 v129, v0
	s_cmp_eq_u32 s50, 1
	s_cbranch_scc1 .LBB0_124
	s_add_u32 s0, s22, 0xfff80080
	s_addc_u32 s1, s23, -1
	s_add_i32 s3, 0, 0x10000
	s_cmp_eq_u32 s28, 28
	s_cselect_b32 s15, s2, s1
	s_cselect_b32 s14, s8, s0
	v_add_u32_e32 v162, s3, v141
	s_cselect_b32 s1, s10, s25
	s_cselect_b32 s0, s24, s9
	s_add_i32 s6, 0, 0x14000
	ds_read_b128 v[144:147], v162
	ds_read_b128 v[148:151], v162 offset:1024
	ds_read_b128 v[172:175], v162 offset:2048
	ds_read_b128 v[190:193], v162 offset:3072
	v_add_u32_e32 v162, s6, v141
	ds_read_b128 v[194:197], v162
	ds_read_b128 v[198:201], v162 offset:1024
	ds_read_b128 v[202:205], v162 offset:2048
	ds_read_b128 v[206:209], v162 offset:3072
	s_add_i32 m0, s30, 0xc000
	ds_read_b128 v[210:213], v143
	ds_read_b128 v[214:217], v143 offset:1024
	ds_read_b128 v[218:221], v143 offset:2048
	ds_read_b128 v[222:225], v143 offset:3072
	ds_read_b128 v[226:229], v143 offset:4096
	ds_read_b128 v[230:233], v143 offset:5120
	ds_read_b128 v[234:237], v143 offset:6144
	ds_read_b128 v[238:241], v143 offset:7168
	global_load_lds_dwordx4 v136, s[22:23]
	s_add_i32 m0, s30, 0xe000
	s_nop 0
	global_load_lds_dwordx4 v138, s[22:23]
	s_waitcnt vmcnt(24) lgkmcnt(0)
	s_barrier
	v_mfma_f32_16x16x32_bf16 v[126:129], v[144:147], v[210:213], v[126:129]
	v_mfma_f32_16x16x32_bf16 v[122:125], v[172:175], v[210:213], v[122:125]
	v_mfma_f32_16x16x32_bf16 v[118:121], v[144:147], v[218:221], v[118:121]
	v_mfma_f32_16x16x32_bf16 v[114:117], v[172:175], v[218:221], v[114:117]
	v_mfma_f32_16x16x32_bf16 v[110:113], v[144:147], v[226:229], v[110:113]
	v_mfma_f32_16x16x32_bf16 v[106:109], v[172:175], v[226:229], v[106:109]
	v_mfma_f32_16x16x32_bf16 v[102:105], v[144:147], v[234:237], v[102:105]
	v_mfma_f32_16x16x32_bf16 v[98:101], v[172:175], v[234:237], v[98:101]
	v_mfma_f32_16x16x32_bf16 v[126:129], v[148:151], v[214:217], v[126:129]
	v_mfma_f32_16x16x32_bf16 v[122:125], v[190:193], v[214:217], v[122:125]
	v_mfma_f32_16x16x32_bf16 v[118:121], v[148:151], v[222:225], v[118:121]
	v_mfma_f32_16x16x32_bf16 v[114:117], v[190:193], v[222:225], v[114:117]
	v_mfma_f32_16x16x32_bf16 v[110:113], v[148:151], v[230:233], v[110:113]
	v_mfma_f32_16x16x32_bf16 v[106:109], v[190:193], v[230:233], v[106:109]
	v_mfma_f32_16x16x32_bf16 v[102:105], v[148:151], v[238:241], v[102:105]
	v_mfma_f32_16x16x32_bf16 v[98:101], v[190:193], v[238:241], v[98:101]
	v_mfma_f32_16x16x32_bf16 v[70:73], v[194:197], v[210:213], v[70:73]
	v_mfma_f32_16x16x32_bf16 v[66:69], v[202:205], v[210:213], v[66:69]
	v_mfma_f32_16x16x32_bf16 v[54:57], v[194:197], v[218:221], v[54:57]
	v_mfma_f32_16x16x32_bf16 v[50:53], v[202:205], v[218:221], v[50:53]
	v_mfma_f32_16x16x32_bf16 v[46:49], v[194:197], v[226:229], v[46:49]
	v_mfma_f32_16x16x32_bf16 v[42:45], v[202:205], v[226:229], v[42:45]
	v_mfma_f32_16x16x32_bf16 v[38:41], v[194:197], v[234:237], v[38:41]
	v_mfma_f32_16x16x32_bf16 v[34:37], v[202:205], v[234:237], v[34:37]
	v_mfma_f32_16x16x32_bf16 v[70:73], v[198:201], v[214:217], v[70:73]
	v_mfma_f32_16x16x32_bf16 v[66:69], v[206:209], v[214:217], v[66:69]
	v_mfma_f32_16x16x32_bf16 v[54:57], v[198:201], v[222:225], v[54:57]
	v_mfma_f32_16x16x32_bf16 v[50:53], v[206:209], v[222:225], v[50:53]
	v_mfma_f32_16x16x32_bf16 v[46:49], v[198:201], v[230:233], v[46:49]
	v_mfma_f32_16x16x32_bf16 v[42:45], v[206:209], v[230:233], v[42:45]
	v_mfma_f32_16x16x32_bf16 v[38:41], v[198:201], v[238:241], v[38:41]
	v_mfma_f32_16x16x32_bf16 v[34:37], v[206:209], v[238:241], v[34:37]
	s_barrier
	s_add_i32 s3, s3, s27
	v_lshl_add_u64 v[162:163], s[0:1], 0, v[4:5]
	s_mov_b32 m0, s3
	ds_read_b128 v[210:213], v143 offset:16384
	ds_read_b128 v[214:217], v143 offset:17408
	ds_read_b128 v[218:221], v143 offset:18432
	ds_read_b128 v[222:225], v143 offset:19456
	ds_read_b128 v[226:229], v143 offset:20480
	ds_read_b128 v[230:233], v143 offset:21504
	ds_read_b128 v[234:237], v143 offset:22528
	ds_read_b128 v[238:241], v143 offset:23552
	global_load_lds_dwordx4 v4, s[0:1]
	s_add_i32 m0, s3, 0x2000
	s_add_u32 s4, s0, 0x80000
	v_lshl_add_u64 v[166:167], s[0:1], 0, v[130:131]
	s_addc_u32 s5, s1, 0
	s_add_i32 s3, s6, s27
	global_load_lds_dwordx4 v130, s[0:1]
	s_mov_b32 m0, s3
	v_lshl_add_u64 v[180:181], s[14:15], 0, v[132:133]
	global_load_lds_dwordx4 v4, s[4:5]
	s_add_i32 m0, s3, 0x2000
	s_nop 0
	global_load_lds_dwordx4 v130, s[4:5]
	v_lshl_add_u64 v[176:177], s[14:15], 0, v[134:135]
	s_mov_b32 m0, s30
	s_nop 0
	global_load_lds_dwordx4 v134, s[14:15]
	s_mov_b32 m0, s31
	s_nop 0
	global_load_lds_dwordx4 v132, s[14:15]
	s_waitcnt vmcnt(24) lgkmcnt(0)
	s_barrier
	v_mfma_f32_16x16x32_bf16 v[94:97], v[144:147], v[210:213], v[94:97]
	v_mfma_f32_16x16x32_bf16 v[90:93], v[172:175], v[210:213], v[90:93]
	v_mfma_f32_16x16x32_bf16 v[86:89], v[144:147], v[218:221], v[86:89]
	v_mfma_f32_16x16x32_bf16 v[82:85], v[172:175], v[218:221], v[82:85]
	v_mfma_f32_16x16x32_bf16 v[78:81], v[144:147], v[226:229], v[78:81]
	v_mfma_f32_16x16x32_bf16 v[74:77], v[172:175], v[226:229], v[74:77]
	v_mfma_f32_16x16x32_bf16 v[62:65], v[144:147], v[234:237], v[62:65]
	v_mfma_f32_16x16x32_bf16 v[58:61], v[172:175], v[234:237], v[58:61]
	v_mfma_f32_16x16x32_bf16 v[94:97], v[148:151], v[214:217], v[94:97]
	v_mfma_f32_16x16x32_bf16 v[90:93], v[190:193], v[214:217], v[90:93]
	v_mfma_f32_16x16x32_bf16 v[86:89], v[148:151], v[222:225], v[86:89]
	v_mfma_f32_16x16x32_bf16 v[82:85], v[190:193], v[222:225], v[82:85]
	v_mfma_f32_16x16x32_bf16 v[78:81], v[148:151], v[230:233], v[78:81]
	v_mfma_f32_16x16x32_bf16 v[74:77], v[190:193], v[230:233], v[74:77]
	v_mfma_f32_16x16x32_bf16 v[62:65], v[148:151], v[238:241], v[62:65]
	v_mfma_f32_16x16x32_bf16 v[58:61], v[190:193], v[238:241], v[58:61]
	v_mfma_f32_16x16x32_bf16 v[30:33], v[194:197], v[210:213], v[30:33]
	v_mfma_f32_16x16x32_bf16 v[26:29], v[202:205], v[210:213], v[26:29]
	v_mfma_f32_16x16x32_bf16 v[22:25], v[194:197], v[218:221], v[22:25]
	v_mfma_f32_16x16x32_bf16 v[18:21], v[202:205], v[218:221], v[18:21]
	v_mfma_f32_16x16x32_bf16 v[14:17], v[194:197], v[226:229], v[14:17]
	v_mfma_f32_16x16x32_bf16 v[10:13], v[202:205], v[226:229], v[10:13]
	v_mfma_f32_16x16x32_bf16 v[6:9], v[194:197], v[234:237], v[6:9]
	v_mfma_f32_16x16x32_bf16 v[0:3], v[202:205], v[234:237], v[0:3]
	v_mfma_f32_16x16x32_bf16 v[30:33], v[198:201], v[214:217], v[30:33]
	v_mfma_f32_16x16x32_bf16 v[26:29], v[206:209], v[214:217], v[26:29]
	v_mfma_f32_16x16x32_bf16 v[22:25], v[198:201], v[222:225], v[22:25]
	v_mfma_f32_16x16x32_bf16 v[18:21], v[206:209], v[222:225], v[18:21]
	v_mfma_f32_16x16x32_bf16 v[14:17], v[198:201], v[230:233], v[14:17]
	v_mfma_f32_16x16x32_bf16 v[10:13], v[206:209], v[230:233], v[10:13]
	v_mfma_f32_16x16x32_bf16 v[6:9], v[198:201], v[238:241], v[6:9]
	v_mfma_f32_16x16x32_bf16 v[0:3], v[206:209], v[238:241], v[0:3]
	s_barrier
	s_branch .Lpeelmid_124
.LBB0_124:
	s_add_u32 s0, s22, 0xfff80080
	s_addc_u32 s1, s23, -1
	s_add_i32 s3, 0, 0x10000
	s_cmp_eq_u32 s28, 28
	s_cselect_b32 s15, s2, s1
	s_cselect_b32 s14, s8, s0
	v_add_u32_e32 v162, s3, v141
	s_cselect_b32 s1, s10, s25
	s_cselect_b32 s0, s24, s9
	s_add_i32 s6, 0, 0x14000
	ds_read_b128 v[144:147], v162
	ds_read_b128 v[148:151], v162 offset:1024
	ds_read_b128 v[172:175], v162 offset:2048
	ds_read_b128 v[190:193], v162 offset:3072
	v_add_u32_e32 v162, s6, v141
	ds_read_b128 v[194:197], v162
	ds_read_b128 v[198:201], v162 offset:1024
	ds_read_b128 v[202:205], v162 offset:2048
	ds_read_b128 v[206:209], v162 offset:3072
	s_add_i32 m0, s30, 0xc000
	ds_read_b128 v[210:213], v143
	ds_read_b128 v[214:217], v143 offset:1024
	ds_read_b128 v[218:221], v143 offset:2048
	ds_read_b128 v[222:225], v143 offset:3072
	ds_read_b128 v[226:229], v143 offset:4096
	ds_read_b128 v[230:233], v143 offset:5120
	ds_read_b128 v[234:237], v143 offset:6144
	ds_read_b128 v[238:241], v143 offset:7168
	global_load_lds_dwordx4 v136, s[22:23]
	s_add_i32 m0, s30, 0xe000
	s_nop 0
	global_load_lds_dwordx4 v138, s[22:23]
	s_waitcnt vmcnt(8) lgkmcnt(0)
	s_barrier
	v_mfma_f32_16x16x32_bf16 v[126:129], v[144:147], v[210:213], v[126:129]
	v_mfma_f32_16x16x32_bf16 v[122:125], v[172:175], v[210:213], v[122:125]
	v_mfma_f32_16x16x32_bf16 v[118:121], v[144:147], v[218:221], v[118:121]
	v_mfma_f32_16x16x32_bf16 v[114:117], v[172:175], v[218:221], v[114:117]
	v_mfma_f32_16x16x32_bf16 v[110:113], v[144:147], v[226:229], v[110:113]
	v_mfma_f32_16x16x32_bf16 v[106:109], v[172:175], v[226:229], v[106:109]
	v_mfma_f32_16x16x32_bf16 v[102:105], v[144:147], v[234:237], v[102:105]
	v_mfma_f32_16x16x32_bf16 v[98:101], v[172:175], v[234:237], v[98:101]
	v_mfma_f32_16x16x32_bf16 v[126:129], v[148:151], v[214:217], v[126:129]
	v_mfma_f32_16x16x32_bf16 v[122:125], v[190:193], v[214:217], v[122:125]
	v_mfma_f32_16x16x32_bf16 v[118:121], v[148:151], v[222:225], v[118:121]
	v_mfma_f32_16x16x32_bf16 v[114:117], v[190:193], v[222:225], v[114:117]
	v_mfma_f32_16x16x32_bf16 v[110:113], v[148:151], v[230:233], v[110:113]
	v_mfma_f32_16x16x32_bf16 v[106:109], v[190:193], v[230:233], v[106:109]
	v_mfma_f32_16x16x32_bf16 v[102:105], v[148:151], v[238:241], v[102:105]
	v_mfma_f32_16x16x32_bf16 v[98:101], v[190:193], v[238:241], v[98:101]
	v_mfma_f32_16x16x32_bf16 v[70:73], v[194:197], v[210:213], v[70:73]
	v_mfma_f32_16x16x32_bf16 v[66:69], v[202:205], v[210:213], v[66:69]
	v_mfma_f32_16x16x32_bf16 v[54:57], v[194:197], v[218:221], v[54:57]
	v_mfma_f32_16x16x32_bf16 v[50:53], v[202:205], v[218:221], v[50:53]
	v_mfma_f32_16x16x32_bf16 v[46:49], v[194:197], v[226:229], v[46:49]
	v_mfma_f32_16x16x32_bf16 v[42:45], v[202:205], v[226:229], v[42:45]
	v_mfma_f32_16x16x32_bf16 v[38:41], v[194:197], v[234:237], v[38:41]
	v_mfma_f32_16x16x32_bf16 v[34:37], v[202:205], v[234:237], v[34:37]
	v_mfma_f32_16x16x32_bf16 v[70:73], v[198:201], v[214:217], v[70:73]
	v_mfma_f32_16x16x32_bf16 v[66:69], v[206:209], v[214:217], v[66:69]
	v_mfma_f32_16x16x32_bf16 v[54:57], v[198:201], v[222:225], v[54:57]
	v_mfma_f32_16x16x32_bf16 v[50:53], v[206:209], v[222:225], v[50:53]
	v_mfma_f32_16x16x32_bf16 v[46:49], v[198:201], v[230:233], v[46:49]
	v_mfma_f32_16x16x32_bf16 v[42:45], v[206:209], v[230:233], v[42:45]
	v_mfma_f32_16x16x32_bf16 v[38:41], v[198:201], v[238:241], v[38:41]
	v_mfma_f32_16x16x32_bf16 v[34:37], v[206:209], v[238:241], v[34:37]
	s_barrier
	s_add_i32 s3, s3, s27
	v_lshl_add_u64 v[162:163], s[0:1], 0, v[4:5]
	s_mov_b32 m0, s3
	ds_read_b128 v[210:213], v143 offset:16384
	ds_read_b128 v[214:217], v143 offset:17408
	ds_read_b128 v[218:221], v143 offset:18432
	ds_read_b128 v[222:225], v143 offset:19456
	ds_read_b128 v[226:229], v143 offset:20480
	ds_read_b128 v[230:233], v143 offset:21504
	ds_read_b128 v[234:237], v143 offset:22528
	ds_read_b128 v[238:241], v143 offset:23552
	global_load_lds_dwordx4 v4, s[0:1]
	s_add_i32 m0, s3, 0x2000
	s_add_u32 s4, s0, 0x80000
	v_lshl_add_u64 v[166:167], s[0:1], 0, v[130:131]
	s_addc_u32 s5, s1, 0
	s_add_i32 s3, s6, s27
	global_load_lds_dwordx4 v130, s[0:1]
	s_mov_b32 m0, s3
	v_lshl_add_u64 v[180:181], s[14:15], 0, v[132:133]
	global_load_lds_dwordx4 v4, s[4:5]
	s_add_i32 m0, s3, 0x2000
	s_nop 0
	global_load_lds_dwordx4 v130, s[4:5]
	v_lshl_add_u64 v[176:177], s[14:15], 0, v[134:135]
	s_mov_b32 m0, s30
	s_nop 0
	global_load_lds_dwordx4 v134, s[14:15]
	s_mov_b32 m0, s31
	s_nop 0
	global_load_lds_dwordx4 v132, s[14:15]
	s_waitcnt vmcnt(8) lgkmcnt(0)
	s_barrier
	v_mfma_f32_16x16x32_bf16 v[94:97], v[144:147], v[210:213], v[94:97]
	v_mfma_f32_16x16x32_bf16 v[90:93], v[172:175], v[210:213], v[90:93]
	v_mfma_f32_16x16x32_bf16 v[86:89], v[144:147], v[218:221], v[86:89]
	v_mfma_f32_16x16x32_bf16 v[82:85], v[172:175], v[218:221], v[82:85]
	v_mfma_f32_16x16x32_bf16 v[78:81], v[144:147], v[226:229], v[78:81]
	v_mfma_f32_16x16x32_bf16 v[74:77], v[172:175], v[226:229], v[74:77]
	v_mfma_f32_16x16x32_bf16 v[62:65], v[144:147], v[234:237], v[62:65]
	v_mfma_f32_16x16x32_bf16 v[58:61], v[172:175], v[234:237], v[58:61]
	v_mfma_f32_16x16x32_bf16 v[94:97], v[148:151], v[214:217], v[94:97]
	v_mfma_f32_16x16x32_bf16 v[90:93], v[190:193], v[214:217], v[90:93]
	v_mfma_f32_16x16x32_bf16 v[86:89], v[148:151], v[222:225], v[86:89]
	v_mfma_f32_16x16x32_bf16 v[82:85], v[190:193], v[222:225], v[82:85]
	v_mfma_f32_16x16x32_bf16 v[78:81], v[148:151], v[230:233], v[78:81]
	v_mfma_f32_16x16x32_bf16 v[74:77], v[190:193], v[230:233], v[74:77]
	v_mfma_f32_16x16x32_bf16 v[62:65], v[148:151], v[238:241], v[62:65]
	v_mfma_f32_16x16x32_bf16 v[58:61], v[190:193], v[238:241], v[58:61]
	v_mfma_f32_16x16x32_bf16 v[30:33], v[194:197], v[210:213], v[30:33]
	v_mfma_f32_16x16x32_bf16 v[26:29], v[202:205], v[210:213], v[26:29]
	v_mfma_f32_16x16x32_bf16 v[22:25], v[194:197], v[218:221], v[22:25]
	v_mfma_f32_16x16x32_bf16 v[18:21], v[202:205], v[218:221], v[18:21]
	v_mfma_f32_16x16x32_bf16 v[14:17], v[194:197], v[226:229], v[14:17]
	v_mfma_f32_16x16x32_bf16 v[10:13], v[202:205], v[226:229], v[10:13]
	v_mfma_f32_16x16x32_bf16 v[6:9], v[194:197], v[234:237], v[6:9]
	v_mfma_f32_16x16x32_bf16 v[0:3], v[202:205], v[234:237], v[0:3]
	v_mfma_f32_16x16x32_bf16 v[30:33], v[198:201], v[214:217], v[30:33]
	v_mfma_f32_16x16x32_bf16 v[26:29], v[206:209], v[214:217], v[26:29]
	v_mfma_f32_16x16x32_bf16 v[22:25], v[198:201], v[222:225], v[22:25]
	v_mfma_f32_16x16x32_bf16 v[18:21], v[206:209], v[222:225], v[18:21]
	v_mfma_f32_16x16x32_bf16 v[14:17], v[198:201], v[230:233], v[14:17]
	v_mfma_f32_16x16x32_bf16 v[10:13], v[206:209], v[230:233], v[10:13]
	v_mfma_f32_16x16x32_bf16 v[6:9], v[198:201], v[238:241], v[6:9]
	v_mfma_f32_16x16x32_bf16 v[0:3], v[206:209], v[238:241], v[0:3]
	s_barrier
.Lpeelmid_124:
	s_add_i32 s3, 0, 0x18000
	v_add_u32_e32 v164, s3, v141
	s_add_i32 s6, 0, 0x1c000
	ds_read_b128 v[144:147], v164
	ds_read_b128 v[148:151], v164 offset:1024
	ds_read_b128 v[172:175], v164 offset:2048
	ds_read_b128 v[190:193], v164 offset:3072
	v_add_u32_e32 v164, s6, v141
	ds_read_b128 v[194:197], v164
	ds_read_b128 v[198:201], v164 offset:1024
	ds_read_b128 v[202:205], v164 offset:2048
	ds_read_b128 v[206:209], v164 offset:3072
	s_add_u32 s4, s14, 0x80000
	s_addc_u32 s5, s15, 0
	s_mov_b32 m0, s34
	ds_read_b128 v[210:213], v143 offset:32768
	ds_read_b128 v[214:217], v143 offset:33792
	ds_read_b128 v[218:221], v143 offset:34816
	ds_read_b128 v[222:225], v143 offset:35840
	ds_read_b128 v[226:229], v143 offset:36864
	ds_read_b128 v[230:233], v143 offset:37888
	ds_read_b128 v[234:237], v143 offset:38912
	ds_read_b128 v[238:241], v143 offset:39936
	global_load_lds_dwordx4 v134, s[4:5]
	v_lshl_add_u64 v[242:243], s[4:5], 0, v[132:133]
	s_mov_b32 m0, s35
	s_nop 0
	global_load_lds_dwordx4 v132, s[4:5]
	s_waitcnt vmcnt(8) lgkmcnt(0)
	s_barrier
	v_mfma_f32_16x16x32_bf16 v[126:129], v[144:147], v[210:213], v[126:129]
	v_mfma_f32_16x16x32_bf16 v[122:125], v[172:175], v[210:213], v[122:125]
	v_mfma_f32_16x16x32_bf16 v[118:121], v[144:147], v[218:221], v[118:121]
	v_mfma_f32_16x16x32_bf16 v[114:117], v[172:175], v[218:221], v[114:117]
	v_mfma_f32_16x16x32_bf16 v[110:113], v[144:147], v[226:229], v[110:113]
	v_mfma_f32_16x16x32_bf16 v[106:109], v[172:175], v[226:229], v[106:109]
	v_mfma_f32_16x16x32_bf16 v[102:105], v[144:147], v[234:237], v[102:105]
	v_mfma_f32_16x16x32_bf16 v[98:101], v[172:175], v[234:237], v[98:101]
	v_mfma_f32_16x16x32_bf16 v[126:129], v[148:151], v[214:217], v[126:129]
	v_mfma_f32_16x16x32_bf16 v[122:125], v[190:193], v[214:217], v[122:125]
	v_mfma_f32_16x16x32_bf16 v[118:121], v[148:151], v[222:225], v[118:121]
	v_mfma_f32_16x16x32_bf16 v[114:117], v[190:193], v[222:225], v[114:117]
	v_mfma_f32_16x16x32_bf16 v[110:113], v[148:151], v[230:233], v[110:113]
	v_mfma_f32_16x16x32_bf16 v[106:109], v[190:193], v[230:233], v[106:109]
	v_mfma_f32_16x16x32_bf16 v[102:105], v[148:151], v[238:241], v[102:105]
	v_mfma_f32_16x16x32_bf16 v[98:101], v[190:193], v[238:241], v[98:101]
	v_mfma_f32_16x16x32_bf16 v[70:73], v[194:197], v[210:213], v[70:73]
	v_mfma_f32_16x16x32_bf16 v[66:69], v[202:205], v[210:213], v[66:69]
	v_mfma_f32_16x16x32_bf16 v[54:57], v[194:197], v[218:221], v[54:57]
	v_mfma_f32_16x16x32_bf16 v[50:53], v[202:205], v[218:221], v[50:53]
	v_mfma_f32_16x16x32_bf16 v[46:49], v[194:197], v[226:229], v[46:49]
	v_mfma_f32_16x16x32_bf16 v[42:45], v[202:205], v[226:229], v[42:45]
	v_mfma_f32_16x16x32_bf16 v[38:41], v[194:197], v[234:237], v[38:41]
	v_mfma_f32_16x16x32_bf16 v[34:37], v[202:205], v[234:237], v[34:37]
	v_mfma_f32_16x16x32_bf16 v[70:73], v[198:201], v[214:217], v[70:73]
	v_mfma_f32_16x16x32_bf16 v[66:69], v[206:209], v[214:217], v[66:69]
	v_mfma_f32_16x16x32_bf16 v[54:57], v[198:201], v[222:225], v[54:57]
	v_mfma_f32_16x16x32_bf16 v[50:53], v[206:209], v[222:225], v[50:53]
	v_mfma_f32_16x16x32_bf16 v[46:49], v[198:201], v[230:233], v[46:49]
	v_mfma_f32_16x16x32_bf16 v[42:45], v[206:209], v[230:233], v[42:45]
	v_mfma_f32_16x16x32_bf16 v[38:41], v[198:201], v[238:241], v[38:41]
	v_mfma_f32_16x16x32_bf16 v[34:37], v[206:209], v[238:241], v[34:37]
	s_barrier
	s_add_i32 s3, s3, s27
	v_lshl_add_u64 v[162:163], v[162:163], 0, s[70:71]
	s_mov_b32 m0, s3
	ds_read_b128 v[210:213], v143 offset:49152
	ds_read_b128 v[214:217], v143 offset:50176
	ds_read_b128 v[218:221], v143 offset:51200
	ds_read_b128 v[222:225], v143 offset:52224
	ds_read_b128 v[226:229], v143 offset:53248
	ds_read_b128 v[230:233], v143 offset:54272
	ds_read_b128 v[234:237], v143 offset:55296
	ds_read_b128 v[238:241], v143 offset:56320
	global_load_lds_dwordx4 v[162:163], off
	s_add_i32 m0, s3, 0x2000
	s_add_u32 s0, s0, 0x80080
	v_lshl_add_u64 v[162:163], v[166:167], 0, s[70:71]
	s_addc_u32 s1, s1, 0
	s_add_i32 s3, s6, s27
	global_load_lds_dwordx4 v[162:163], off
	s_mov_b32 m0, s3
	s_nop 0
	global_load_lds_dwordx4 v4, s[0:1]
	s_add_i32 m0, s3, 0x2000
	s_nop 0
	global_load_lds_dwordx4 v130, s[0:1]
	v_lshl_add_u64 v[162:163], v[176:177], 0, s[70:71]
	s_mov_b32 m0, s36
	s_nop 0
	global_load_lds_dwordx4 v[162:163], off
	v_lshl_add_u64 v[162:163], v[180:181], 0, s[70:71]
	s_mov_b32 m0, s37
	s_nop 0
	global_load_lds_dwordx4 v[162:163], off
	s_waitcnt vmcnt(8) lgkmcnt(0)
	s_barrier
	v_mfma_f32_16x16x32_bf16 v[94:97], v[144:147], v[210:213], v[94:97]
	v_mfma_f32_16x16x32_bf16 v[90:93], v[172:175], v[210:213], v[90:93]
	v_mfma_f32_16x16x32_bf16 v[86:89], v[144:147], v[218:221], v[86:89]
	v_mfma_f32_16x16x32_bf16 v[82:85], v[172:175], v[218:221], v[82:85]
	v_mfma_f32_16x16x32_bf16 v[78:81], v[144:147], v[226:229], v[78:81]
	v_mfma_f32_16x16x32_bf16 v[74:77], v[172:175], v[226:229], v[74:77]
	v_mfma_f32_16x16x32_bf16 v[62:65], v[144:147], v[234:237], v[62:65]
	v_mfma_f32_16x16x32_bf16 v[58:61], v[172:175], v[234:237], v[58:61]
	v_mfma_f32_16x16x32_bf16 v[94:97], v[148:151], v[214:217], v[94:97]
	v_mfma_f32_16x16x32_bf16 v[90:93], v[190:193], v[214:217], v[90:93]
	v_mfma_f32_16x16x32_bf16 v[86:89], v[148:151], v[222:225], v[86:89]
	v_mfma_f32_16x16x32_bf16 v[82:85], v[190:193], v[222:225], v[82:85]
	v_mfma_f32_16x16x32_bf16 v[78:81], v[148:151], v[230:233], v[78:81]
	v_mfma_f32_16x16x32_bf16 v[74:77], v[190:193], v[230:233], v[74:77]
	v_mfma_f32_16x16x32_bf16 v[62:65], v[148:151], v[238:241], v[62:65]
	v_mfma_f32_16x16x32_bf16 v[58:61], v[190:193], v[238:241], v[58:61]
	v_mfma_f32_16x16x32_bf16 v[30:33], v[194:197], v[210:213], v[30:33]
	v_mfma_f32_16x16x32_bf16 v[26:29], v[202:205], v[210:213], v[26:29]
	v_mfma_f32_16x16x32_bf16 v[22:25], v[194:197], v[218:221], v[22:25]
	v_mfma_f32_16x16x32_bf16 v[18:21], v[202:205], v[218:221], v[18:21]
	v_mfma_f32_16x16x32_bf16 v[14:17], v[194:197], v[226:229], v[14:17]
	v_mfma_f32_16x16x32_bf16 v[10:13], v[202:205], v[226:229], v[10:13]
	v_mfma_f32_16x16x32_bf16 v[6:9], v[194:197], v[234:237], v[6:9]
	v_mfma_f32_16x16x32_bf16 v[0:3], v[202:205], v[234:237], v[0:3]
	v_mfma_f32_16x16x32_bf16 v[30:33], v[198:201], v[214:217], v[30:33]
	v_mfma_f32_16x16x32_bf16 v[26:29], v[206:209], v[214:217], v[26:29]
	v_mfma_f32_16x16x32_bf16 v[22:25], v[198:201], v[222:225], v[22:25]
	v_mfma_f32_16x16x32_bf16 v[18:21], v[206:209], v[222:225], v[18:21]
	v_mfma_f32_16x16x32_bf16 v[14:17], v[198:201], v[230:233], v[14:17]
	v_mfma_f32_16x16x32_bf16 v[10:13], v[206:209], v[230:233], v[10:13]
	v_mfma_f32_16x16x32_bf16 v[6:9], v[198:201], v[238:241], v[6:9]
	v_mfma_f32_16x16x32_bf16 v[0:3], v[206:209], v[238:241], v[0:3]
	s_barrier
	s_add_i32 s28, s28, 2
	s_add_u32 s22, s22, 0x100
	s_addc_u32 s23, s23, 0
	s_add_u32 s9, s9, 0x100
	s_addc_u32 s25, s25, 0
	s_cmp_gt_u32 s28, 29
	s_cbranch_scc0 .LBB0_124
	s_and_b64 vcc, exec, s[42:43]
	s_cbranch_vccz .LBB0_127
	s_barrier

.LBB0_162:
	s_ashr_i32 s49, s48, 31
	s_lshl_b64 s[2:3], s[48:49], 20
	v_readlane_b32 s4, v253, 61
	v_readlane_b32 s5, v253, 62
	s_add_u32 s82, s4, s2
	s_addc_u32 s83, s5, s3
	s_and_b64 s[2:3], s[42:43], exec
	s_cselect_b32 s2, s83, s1
	s_cselect_b32 s8, s82, s0
	s_add_u32 s22, s14, 0x80080
	s_addc_u32 s23, s15, 0
	s_add_u32 s9, s0, 0x100
	v_mov_b32_e32 v0, 0
	s_addc_u32 s10, s1, 0
	s_mov_b32 s24, -2
	v_mov_b32_e32 v1, v0
	v_mov_b32_e32 v2, v0
	v_mov_b32_e32 v3, v0
	v_mov_b32_e32 v6, v0
	s_waitcnt lgkmcnt(0)
	v_mov_b32_e32 v7, v0
	v_mov_b32_e32 v8, v0
	v_mov_b32_e32 v9, v0
	v_mov_b32_e32 v18, v0
	v_mov_b32_e32 v19, v0
	v_mov_b32_e32 v20, v0
	v_mov_b32_e32 v21, v0
	v_mov_b32_e32 v22, v0
	v_mov_b32_e32 v23, v0
	v_mov_b32_e32 v24, v0
	v_mov_b32_e32 v25, v0
	v_mov_b32_e32 v34, v0
	v_mov_b32_e32 v35, v0
	v_mov_b32_e32 v36, v0
	v_mov_b32_e32 v37, v0
	v_mov_b32_e32 v38, v0
	v_mov_b32_e32 v39, v0
	v_mov_b32_e32 v40, v0
	v_mov_b32_e32 v41, v0
	v_mov_b32_e32 v50, v0
	v_mov_b32_e32 v51, v0
	v_mov_b32_e32 v52, v0
	v_mov_b32_e32 v53, v0
	v_mov_b32_e32 v54, v0
	v_mov_b32_e32 v55, v0
	v_mov_b32_e32 v56, v0
	v_mov_b32_e32 v57, v0
	v_mov_b32_e32 v10, v0
	v_mov_b32_e32 v11, v0
	v_mov_b32_e32 v12, v0
	v_mov_b32_e32 v13, v0
	v_mov_b32_e32 v14, v0
	v_mov_b32_e32 v15, v0
	v_mov_b32_e32 v16, v0
	v_mov_b32_e32 v17, v0
	v_mov_b32_e32 v26, v0
	v_mov_b32_e32 v27, v0
	v_mov_b32_e32 v28, v0
	v_mov_b32_e32 v29, v0
	v_mov_b32_e32 v30, v0
	v_mov_b32_e32 v31, v0
	v_mov_b32_e32 v32, v0
	v_mov_b32_e32 v33, v0
	v_mov_b32_e32 v42, v0
	v_mov_b32_e32 v43, v0
	v_mov_b32_e32 v44, v0
	v_mov_b32_e32 v45, v0
	v_mov_b32_e32 v46, v0
	v_mov_b32_e32 v47, v0
	v_mov_b32_e32 v48, v0
	v_mov_b32_e32 v49, v0
	v_mov_b32_e32 v58, v0
	v_mov_b32_e32 v59, v0
	v_mov_b32_e32 v60, v0
	v_mov_b32_e32 v61, v0
	v_mov_b32_e32 v62, v0
	v_mov_b32_e32 v63, v0
	v_mov_b32_e32 v64, v0
	v_mov_b32_e32 v65, v0
	v_mov_b32_e32 v66, v0
	v_mov_b32_e32 v67, v0
	v_mov_b32_e32 v68, v0
	v_mov_b32_e32 v69, v0
	v_mov_b32_e32 v70, v0
	v_mov_b32_e32 v71, v0
	v_mov_b32_e32 v72, v0
	v_mov_b32_e32 v73, v0
	v_mov_b32_e32 v82, v0
	v_mov_b32_e32 v83, v0
	v_mov_b32_e32 v84, v0
	v_mov_b32_e32 v85, v0
	v_mov_b32_e32 v86, v0
	v_mov_b32_e32 v87, v0
	v_mov_b32_e32 v88, v0
	v_mov_b32_e32 v89, v0
	v_mov_b32_e32 v98, v0
	v_mov_b32_e32 v99, v0
	v_mov_b32_e32 v100, v0
	v_mov_b32_e32 v101, v0
	v_mov_b32_e32 v102, v0
	v_mov_b32_e32 v103, v0
	v_mov_b32_e32 v104, v0
	v_mov_b32_e32 v105, v0
	v_mov_b32_e32 v114, v0
	v_mov_b32_e32 v115, v0
	v_mov_b32_e32 v116, v0
	v_mov_b32_e32 v117, v0
	v_mov_b32_e32 v118, v0
	v_mov_b32_e32 v119, v0
	v_mov_b32_e32 v120, v0
	v_mov_b32_e32 v121, v0
	v_mov_b32_e32 v74, v0
	v_mov_b32_e32 v75, v0
	v_mov_b32_e32 v76, v0
	v_mov_b32_e32 v77, v0
	v_mov_b32_e32 v78, v0
	v_mov_b32_e32 v79, v0
	v_mov_b32_e32 v80, v0
	v_mov_b32_e32 v81, v0
	v_mov_b32_e32 v90, v0
	v_mov_b32_e32 v91, v0
	v_mov_b32_e32 v92, v0
	v_mov_b32_e32 v93, v0
	v_mov_b32_e32 v94, v0
	v_mov_b32_e32 v95, v0
	v_mov_b32_e32 v96, v0
	v_mov_b32_e32 v97, v0
	v_mov_b32_e32 v106, v0
	v_mov_b32_e32 v107, v0
	v_mov_b32_e32 v108, v0
	v_mov_b32_e32 v109, v0
	v_mov_b32_e32 v110, v0
	v_mov_b32_e32 v111, v0
	v_mov_b32_e32 v112, v0
	v_mov_b32_e32 v113, v0
	v_mov_b32_e32 v122, v0
	v_mov_b32_e32 v123, v0
	v_mov_b32_e32 v124, v0
	v_mov_b32_e32 v125, v0
	v_mov_b32_e32 v126, v0
	v_mov_b32_e32 v127, v0
	v_mov_b32_e32 v128, v0
	v_mov_b32_e32 v129, v0
	s_cmp_eq_u32 s37, 1
	s_cbranch_scc1 .LBB0_163
	s_add_u32 s0, s22, 0xfff80080
	s_addc_u32 s1, s23, -1
	s_add_i32 s3, 0, 0x10000
	s_cmp_eq_u32 s24, 28
	s_cselect_b32 s15, s79, s1
	s_cselect_b32 s14, s78, s0
	v_add_u32_e32 v162, s3, v145
	s_cselect_b32 s1, s2, s10
	s_cselect_b32 s0, s8, s9
	s_add_i32 s6, 0, 0x14000
	ds_read_b128 v[140:143], v162
	ds_read_b128 v[148:151], v162 offset:1024
	ds_read_b128 v[172:175], v162 offset:2048
	ds_read_b128 v[190:193], v162 offset:3072
	v_add_u32_e32 v162, s6, v145
	ds_read_b128 v[194:197], v162
	ds_read_b128 v[198:201], v162 offset:1024
	ds_read_b128 v[202:205], v162 offset:2048
	ds_read_b128 v[206:209], v162 offset:3072
	s_add_i32 m0, s26, 0xc000
	ds_read_b128 v[210:213], v147
	ds_read_b128 v[214:217], v147 offset:1024
	ds_read_b128 v[218:221], v147 offset:2048
	ds_read_b128 v[222:225], v147 offset:3072
	ds_read_b128 v[226:229], v147 offset:4096
	ds_read_b128 v[230:233], v147 offset:5120
	ds_read_b128 v[234:237], v147 offset:6144
	ds_read_b128 v[238:241], v147 offset:7168
	global_load_lds_dwordx4 v136, s[22:23]
	s_add_i32 m0, s26, 0xe000
	s_nop 0
	global_load_lds_dwordx4 v138, s[22:23]
	s_waitcnt vmcnt(24) lgkmcnt(0)
	s_barrier
	v_mfma_f32_16x16x32_bf16 v[126:129], v[140:143], v[210:213], v[126:129]
	v_mfma_f32_16x16x32_bf16 v[122:125], v[172:175], v[210:213], v[122:125]
	v_mfma_f32_16x16x32_bf16 v[110:113], v[140:143], v[218:221], v[110:113]
	v_mfma_f32_16x16x32_bf16 v[106:109], v[172:175], v[218:221], v[106:109]
	v_mfma_f32_16x16x32_bf16 v[94:97], v[140:143], v[226:229], v[94:97]
	v_mfma_f32_16x16x32_bf16 v[90:93], v[172:175], v[226:229], v[90:93]
	v_mfma_f32_16x16x32_bf16 v[78:81], v[140:143], v[234:237], v[78:81]
	v_mfma_f32_16x16x32_bf16 v[74:77], v[172:175], v[234:237], v[74:77]
	v_mfma_f32_16x16x32_bf16 v[126:129], v[148:151], v[214:217], v[126:129]
	v_mfma_f32_16x16x32_bf16 v[122:125], v[190:193], v[214:217], v[122:125]
	v_mfma_f32_16x16x32_bf16 v[110:113], v[148:151], v[222:225], v[110:113]
	v_mfma_f32_16x16x32_bf16 v[106:109], v[190:193], v[222:225], v[106:109]
	v_mfma_f32_16x16x32_bf16 v[94:97], v[148:151], v[230:233], v[94:97]
	v_mfma_f32_16x16x32_bf16 v[90:93], v[190:193], v[230:233], v[90:93]
	v_mfma_f32_16x16x32_bf16 v[78:81], v[148:151], v[238:241], v[78:81]
	v_mfma_f32_16x16x32_bf16 v[74:77], v[190:193], v[238:241], v[74:77]
	v_mfma_f32_16x16x32_bf16 v[118:121], v[194:197], v[210:213], v[118:121]
	v_mfma_f32_16x16x32_bf16 v[114:117], v[202:205], v[210:213], v[114:117]
	v_mfma_f32_16x16x32_bf16 v[102:105], v[194:197], v[218:221], v[102:105]
	v_mfma_f32_16x16x32_bf16 v[98:101], v[202:205], v[218:221], v[98:101]
	v_mfma_f32_16x16x32_bf16 v[86:89], v[194:197], v[226:229], v[86:89]
	v_mfma_f32_16x16x32_bf16 v[82:85], v[202:205], v[226:229], v[82:85]
	v_mfma_f32_16x16x32_bf16 v[70:73], v[194:197], v[234:237], v[70:73]
	v_mfma_f32_16x16x32_bf16 v[66:69], v[202:205], v[234:237], v[66:69]
	v_mfma_f32_16x16x32_bf16 v[118:121], v[198:201], v[214:217], v[118:121]
	v_mfma_f32_16x16x32_bf16 v[114:117], v[206:209], v[214:217], v[114:117]
	v_mfma_f32_16x16x32_bf16 v[102:105], v[198:201], v[222:225], v[102:105]
	v_mfma_f32_16x16x32_bf16 v[98:101], v[206:209], v[222:225], v[98:101]
	v_mfma_f32_16x16x32_bf16 v[86:89], v[198:201], v[230:233], v[86:89]
	v_mfma_f32_16x16x32_bf16 v[82:85], v[206:209], v[230:233], v[82:85]
	v_mfma_f32_16x16x32_bf16 v[70:73], v[198:201], v[238:241], v[70:73]
	v_mfma_f32_16x16x32_bf16 v[66:69], v[206:209], v[238:241], v[66:69]
	s_barrier
	s_add_i32 s3, s3, s11
	v_lshl_add_u64 v[162:163], s[0:1], 0, v[4:5]
	s_mov_b32 m0, s3
	ds_read_b128 v[210:213], v147 offset:16384
	ds_read_b128 v[214:217], v147 offset:17408
	ds_read_b128 v[218:221], v147 offset:18432
	ds_read_b128 v[222:225], v147 offset:19456
	ds_read_b128 v[226:229], v147 offset:20480
	ds_read_b128 v[230:233], v147 offset:21504
	ds_read_b128 v[234:237], v147 offset:22528
	ds_read_b128 v[238:241], v147 offset:23552
	global_load_lds_dwordx4 v4, s[0:1]
	s_add_i32 m0, s3, 0x2000
	s_add_u32 s4, s0, 0x80000
	v_lshl_add_u64 v[166:167], s[0:1], 0, v[130:131]
	s_addc_u32 s5, s1, 0
	s_add_i32 s3, s6, s11
	global_load_lds_dwordx4 v130, s[0:1]
	s_mov_b32 m0, s3
	v_lshl_add_u64 v[180:181], s[14:15], 0, v[132:133]
	global_load_lds_dwordx4 v4, s[4:5]
	s_add_i32 m0, s3, 0x2000
	s_nop 0
	global_load_lds_dwordx4 v130, s[4:5]
	v_lshl_add_u64 v[176:177], s[14:15], 0, v[134:135]
	s_mov_b32 m0, s26
	s_nop 0
	global_load_lds_dwordx4 v134, s[14:15]
	s_mov_b32 m0, s27
	s_nop 0
	global_load_lds_dwordx4 v132, s[14:15]
	s_waitcnt vmcnt(24) lgkmcnt(0)
	s_barrier
	v_mfma_f32_16x16x32_bf16 v[62:65], v[140:143], v[210:213], v[62:65]
	v_mfma_f32_16x16x32_bf16 v[58:61], v[172:175], v[210:213], v[58:61]
	v_mfma_f32_16x16x32_bf16 v[46:49], v[140:143], v[218:221], v[46:49]
	v_mfma_f32_16x16x32_bf16 v[42:45], v[172:175], v[218:221], v[42:45]
	v_mfma_f32_16x16x32_bf16 v[30:33], v[140:143], v[226:229], v[30:33]
	v_mfma_f32_16x16x32_bf16 v[26:29], v[172:175], v[226:229], v[26:29]
	v_mfma_f32_16x16x32_bf16 v[14:17], v[140:143], v[234:237], v[14:17]
	v_mfma_f32_16x16x32_bf16 v[10:13], v[172:175], v[234:237], v[10:13]
	v_mfma_f32_16x16x32_bf16 v[62:65], v[148:151], v[214:217], v[62:65]
	v_mfma_f32_16x16x32_bf16 v[58:61], v[190:193], v[214:217], v[58:61]
	v_mfma_f32_16x16x32_bf16 v[46:49], v[148:151], v[222:225], v[46:49]
	v_mfma_f32_16x16x32_bf16 v[42:45], v[190:193], v[222:225], v[42:45]
	v_mfma_f32_16x16x32_bf16 v[30:33], v[148:151], v[230:233], v[30:33]
	v_mfma_f32_16x16x32_bf16 v[26:29], v[190:193], v[230:233], v[26:29]
	v_mfma_f32_16x16x32_bf16 v[14:17], v[148:151], v[238:241], v[14:17]
	v_mfma_f32_16x16x32_bf16 v[10:13], v[190:193], v[238:241], v[10:13]
	v_mfma_f32_16x16x32_bf16 v[54:57], v[194:197], v[210:213], v[54:57]
	v_mfma_f32_16x16x32_bf16 v[50:53], v[202:205], v[210:213], v[50:53]
	v_mfma_f32_16x16x32_bf16 v[38:41], v[194:197], v[218:221], v[38:41]
	v_mfma_f32_16x16x32_bf16 v[34:37], v[202:205], v[218:221], v[34:37]
	v_mfma_f32_16x16x32_bf16 v[22:25], v[194:197], v[226:229], v[22:25]
	v_mfma_f32_16x16x32_bf16 v[18:21], v[202:205], v[226:229], v[18:21]
	v_mfma_f32_16x16x32_bf16 v[6:9], v[194:197], v[234:237], v[6:9]
	v_mfma_f32_16x16x32_bf16 v[0:3], v[202:205], v[234:237], v[0:3]
	v_mfma_f32_16x16x32_bf16 v[54:57], v[198:201], v[214:217], v[54:57]
	v_mfma_f32_16x16x32_bf16 v[50:53], v[206:209], v[214:217], v[50:53]
	v_mfma_f32_16x16x32_bf16 v[38:41], v[198:201], v[222:225], v[38:41]
	v_mfma_f32_16x16x32_bf16 v[34:37], v[206:209], v[222:225], v[34:37]
	v_mfma_f32_16x16x32_bf16 v[22:25], v[198:201], v[230:233], v[22:25]
	v_mfma_f32_16x16x32_bf16 v[18:21], v[206:209], v[230:233], v[18:21]
	v_mfma_f32_16x16x32_bf16 v[6:9], v[198:201], v[238:241], v[6:9]
	v_mfma_f32_16x16x32_bf16 v[0:3], v[206:209], v[238:241], v[0:3]
	s_barrier
	s_branch .Lpeelmid_163
.LBB0_163:
	s_add_u32 s0, s22, 0xfff80080
	s_addc_u32 s1, s23, -1
	s_add_i32 s3, 0, 0x10000
	s_cmp_eq_u32 s24, 28
	s_cselect_b32 s15, s79, s1
	s_cselect_b32 s14, s78, s0
	v_add_u32_e32 v162, s3, v145
	s_cselect_b32 s1, s2, s10
	s_cselect_b32 s0, s8, s9
	s_add_i32 s6, 0, 0x14000
	ds_read_b128 v[140:143], v162
	ds_read_b128 v[148:151], v162 offset:1024
	ds_read_b128 v[172:175], v162 offset:2048
	ds_read_b128 v[190:193], v162 offset:3072
	v_add_u32_e32 v162, s6, v145
	ds_read_b128 v[194:197], v162
	ds_read_b128 v[198:201], v162 offset:1024
	ds_read_b128 v[202:205], v162 offset:2048
	ds_read_b128 v[206:209], v162 offset:3072
	s_add_i32 m0, s26, 0xc000
	ds_read_b128 v[210:213], v147
	ds_read_b128 v[214:217], v147 offset:1024
	ds_read_b128 v[218:221], v147 offset:2048
	ds_read_b128 v[222:225], v147 offset:3072
	ds_read_b128 v[226:229], v147 offset:4096
	ds_read_b128 v[230:233], v147 offset:5120
	ds_read_b128 v[234:237], v147 offset:6144
	ds_read_b128 v[238:241], v147 offset:7168
	global_load_lds_dwordx4 v136, s[22:23]
	s_add_i32 m0, s26, 0xe000
	s_nop 0
	global_load_lds_dwordx4 v138, s[22:23]
	s_waitcnt vmcnt(8) lgkmcnt(0)
	s_barrier
	v_mfma_f32_16x16x32_bf16 v[126:129], v[140:143], v[210:213], v[126:129]
	v_mfma_f32_16x16x32_bf16 v[122:125], v[172:175], v[210:213], v[122:125]
	v_mfma_f32_16x16x32_bf16 v[110:113], v[140:143], v[218:221], v[110:113]
	v_mfma_f32_16x16x32_bf16 v[106:109], v[172:175], v[218:221], v[106:109]
	v_mfma_f32_16x16x32_bf16 v[94:97], v[140:143], v[226:229], v[94:97]
	v_mfma_f32_16x16x32_bf16 v[90:93], v[172:175], v[226:229], v[90:93]
	v_mfma_f32_16x16x32_bf16 v[78:81], v[140:143], v[234:237], v[78:81]
	v_mfma_f32_16x16x32_bf16 v[74:77], v[172:175], v[234:237], v[74:77]
	v_mfma_f32_16x16x32_bf16 v[126:129], v[148:151], v[214:217], v[126:129]
	v_mfma_f32_16x16x32_bf16 v[122:125], v[190:193], v[214:217], v[122:125]
	v_mfma_f32_16x16x32_bf16 v[110:113], v[148:151], v[222:225], v[110:113]
	v_mfma_f32_16x16x32_bf16 v[106:109], v[190:193], v[222:225], v[106:109]
	v_mfma_f32_16x16x32_bf16 v[94:97], v[148:151], v[230:233], v[94:97]
	v_mfma_f32_16x16x32_bf16 v[90:93], v[190:193], v[230:233], v[90:93]
	v_mfma_f32_16x16x32_bf16 v[78:81], v[148:151], v[238:241], v[78:81]
	v_mfma_f32_16x16x32_bf16 v[74:77], v[190:193], v[238:241], v[74:77]
	v_mfma_f32_16x16x32_bf16 v[118:121], v[194:197], v[210:213], v[118:121]
	v_mfma_f32_16x16x32_bf16 v[114:117], v[202:205], v[210:213], v[114:117]
	v_mfma_f32_16x16x32_bf16 v[102:105], v[194:197], v[218:221], v[102:105]
	v_mfma_f32_16x16x32_bf16 v[98:101], v[202:205], v[218:221], v[98:101]
	v_mfma_f32_16x16x32_bf16 v[86:89], v[194:197], v[226:229], v[86:89]
	v_mfma_f32_16x16x32_bf16 v[82:85], v[202:205], v[226:229], v[82:85]
	v_mfma_f32_16x16x32_bf16 v[70:73], v[194:197], v[234:237], v[70:73]
	v_mfma_f32_16x16x32_bf16 v[66:69], v[202:205], v[234:237], v[66:69]
	v_mfma_f32_16x16x32_bf16 v[118:121], v[198:201], v[214:217], v[118:121]
	v_mfma_f32_16x16x32_bf16 v[114:117], v[206:209], v[214:217], v[114:117]
	v_mfma_f32_16x16x32_bf16 v[102:105], v[198:201], v[222:225], v[102:105]
	v_mfma_f32_16x16x32_bf16 v[98:101], v[206:209], v[222:225], v[98:101]
	v_mfma_f32_16x16x32_bf16 v[86:89], v[198:201], v[230:233], v[86:89]
	v_mfma_f32_16x16x32_bf16 v[82:85], v[206:209], v[230:233], v[82:85]
	v_mfma_f32_16x16x32_bf16 v[70:73], v[198:201], v[238:241], v[70:73]
	v_mfma_f32_16x16x32_bf16 v[66:69], v[206:209], v[238:241], v[66:69]
	s_barrier
	s_add_i32 s3, s3, s11
	v_lshl_add_u64 v[162:163], s[0:1], 0, v[4:5]
	s_mov_b32 m0, s3
	ds_read_b128 v[210:213], v147 offset:16384
	ds_read_b128 v[214:217], v147 offset:17408
	ds_read_b128 v[218:221], v147 offset:18432
	ds_read_b128 v[222:225], v147 offset:19456
	ds_read_b128 v[226:229], v147 offset:20480
	ds_read_b128 v[230:233], v147 offset:21504
	ds_read_b128 v[234:237], v147 offset:22528
	ds_read_b128 v[238:241], v147 offset:23552
	global_load_lds_dwordx4 v4, s[0:1]
	s_add_i32 m0, s3, 0x2000
	s_add_u32 s4, s0, 0x80000
	v_lshl_add_u64 v[166:167], s[0:1], 0, v[130:131]
	s_addc_u32 s5, s1, 0
	s_add_i32 s3, s6, s11
	global_load_lds_dwordx4 v130, s[0:1]
	s_mov_b32 m0, s3
	v_lshl_add_u64 v[180:181], s[14:15], 0, v[132:133]
	global_load_lds_dwordx4 v4, s[4:5]
	s_add_i32 m0, s3, 0x2000
	s_nop 0
	global_load_lds_dwordx4 v130, s[4:5]
	v_lshl_add_u64 v[176:177], s[14:15], 0, v[134:135]
	s_mov_b32 m0, s26
	s_nop 0
	global_load_lds_dwordx4 v134, s[14:15]
	s_mov_b32 m0, s27
	s_nop 0
	global_load_lds_dwordx4 v132, s[14:15]
	s_waitcnt vmcnt(8) lgkmcnt(0)
	s_barrier
	v_mfma_f32_16x16x32_bf16 v[62:65], v[140:143], v[210:213], v[62:65]
	v_mfma_f32_16x16x32_bf16 v[58:61], v[172:175], v[210:213], v[58:61]
	v_mfma_f32_16x16x32_bf16 v[46:49], v[140:143], v[218:221], v[46:49]
	v_mfma_f32_16x16x32_bf16 v[42:45], v[172:175], v[218:221], v[42:45]
	v_mfma_f32_16x16x32_bf16 v[30:33], v[140:143], v[226:229], v[30:33]
	v_mfma_f32_16x16x32_bf16 v[26:29], v[172:175], v[226:229], v[26:29]
	v_mfma_f32_16x16x32_bf16 v[14:17], v[140:143], v[234:237], v[14:17]
	v_mfma_f32_16x16x32_bf16 v[10:13], v[172:175], v[234:237], v[10:13]
	v_mfma_f32_16x16x32_bf16 v[62:65], v[148:151], v[214:217], v[62:65]
	v_mfma_f32_16x16x32_bf16 v[58:61], v[190:193], v[214:217], v[58:61]
	v_mfma_f32_16x16x32_bf16 v[46:49], v[148:151], v[222:225], v[46:49]
	v_mfma_f32_16x16x32_bf16 v[42:45], v[190:193], v[222:225], v[42:45]
	v_mfma_f32_16x16x32_bf16 v[30:33], v[148:151], v[230:233], v[30:33]
	v_mfma_f32_16x16x32_bf16 v[26:29], v[190:193], v[230:233], v[26:29]
	v_mfma_f32_16x16x32_bf16 v[14:17], v[148:151], v[238:241], v[14:17]
	v_mfma_f32_16x16x32_bf16 v[10:13], v[190:193], v[238:241], v[10:13]
	v_mfma_f32_16x16x32_bf16 v[54:57], v[194:197], v[210:213], v[54:57]
	v_mfma_f32_16x16x32_bf16 v[50:53], v[202:205], v[210:213], v[50:53]
	v_mfma_f32_16x16x32_bf16 v[38:41], v[194:197], v[218:221], v[38:41]
	v_mfma_f32_16x16x32_bf16 v[34:37], v[202:205], v[218:221], v[34:37]
	v_mfma_f32_16x16x32_bf16 v[22:25], v[194:197], v[226:229], v[22:25]
	v_mfma_f32_16x16x32_bf16 v[18:21], v[202:205], v[226:229], v[18:21]
	v_mfma_f32_16x16x32_bf16 v[6:9], v[194:197], v[234:237], v[6:9]
	v_mfma_f32_16x16x32_bf16 v[0:3], v[202:205], v[234:237], v[0:3]
	v_mfma_f32_16x16x32_bf16 v[54:57], v[198:201], v[214:217], v[54:57]
	v_mfma_f32_16x16x32_bf16 v[50:53], v[206:209], v[214:217], v[50:53]
	v_mfma_f32_16x16x32_bf16 v[38:41], v[198:201], v[222:225], v[38:41]
	v_mfma_f32_16x16x32_bf16 v[34:37], v[206:209], v[222:225], v[34:37]
	v_mfma_f32_16x16x32_bf16 v[22:25], v[198:201], v[230:233], v[22:25]
	v_mfma_f32_16x16x32_bf16 v[18:21], v[206:209], v[230:233], v[18:21]
	v_mfma_f32_16x16x32_bf16 v[6:9], v[198:201], v[238:241], v[6:9]
	v_mfma_f32_16x16x32_bf16 v[0:3], v[206:209], v[238:241], v[0:3]
	s_barrier
.Lpeelmid_163:
	s_add_i32 s3, 0, 0x18000
	v_add_u32_e32 v164, s3, v145
	s_add_i32 s6, 0, 0x1c000
	ds_read_b128 v[140:143], v164
	ds_read_b128 v[148:151], v164 offset:1024
	ds_read_b128 v[172:175], v164 offset:2048
	ds_read_b128 v[190:193], v164 offset:3072
	v_add_u32_e32 v164, s6, v145
	ds_read_b128 v[194:197], v164
	ds_read_b128 v[198:201], v164 offset:1024
	ds_read_b128 v[202:205], v164 offset:2048
	ds_read_b128 v[206:209], v164 offset:3072
	s_add_u32 s4, s14, 0x80000
	s_addc_u32 s5, s15, 0
	s_mov_b32 m0, s30
	ds_read_b128 v[210:213], v147 offset:32768
	ds_read_b128 v[214:217], v147 offset:33792
	ds_read_b128 v[218:221], v147 offset:34816
	ds_read_b128 v[222:225], v147 offset:35840
	ds_read_b128 v[226:229], v147 offset:36864
	ds_read_b128 v[230:233], v147 offset:37888
	ds_read_b128 v[234:237], v147 offset:38912
	ds_read_b128 v[238:241], v147 offset:39936
	global_load_lds_dwordx4 v134, s[4:5]
	v_lshl_add_u64 v[242:243], s[4:5], 0, v[132:133]
	s_mov_b32 m0, s31
	s_nop 0
	global_load_lds_dwordx4 v132, s[4:5]
	s_waitcnt vmcnt(8) lgkmcnt(0)
	s_barrier
	v_mfma_f32_16x16x32_bf16 v[126:129], v[140:143], v[210:213], v[126:129]
	v_mfma_f32_16x16x32_bf16 v[122:125], v[172:175], v[210:213], v[122:125]
	v_mfma_f32_16x16x32_bf16 v[110:113], v[140:143], v[218:221], v[110:113]
	v_mfma_f32_16x16x32_bf16 v[106:109], v[172:175], v[218:221], v[106:109]
	v_mfma_f32_16x16x32_bf16 v[94:97], v[140:143], v[226:229], v[94:97]
	v_mfma_f32_16x16x32_bf16 v[90:93], v[172:175], v[226:229], v[90:93]
	v_mfma_f32_16x16x32_bf16 v[78:81], v[140:143], v[234:237], v[78:81]
	v_mfma_f32_16x16x32_bf16 v[74:77], v[172:175], v[234:237], v[74:77]
	v_mfma_f32_16x16x32_bf16 v[126:129], v[148:151], v[214:217], v[126:129]
	v_mfma_f32_16x16x32_bf16 v[122:125], v[190:193], v[214:217], v[122:125]
	v_mfma_f32_16x16x32_bf16 v[110:113], v[148:151], v[222:225], v[110:113]
	v_mfma_f32_16x16x32_bf16 v[106:109], v[190:193], v[222:225], v[106:109]
	v_mfma_f32_16x16x32_bf16 v[94:97], v[148:151], v[230:233], v[94:97]
	v_mfma_f32_16x16x32_bf16 v[90:93], v[190:193], v[230:233], v[90:93]
	v_mfma_f32_16x16x32_bf16 v[78:81], v[148:151], v[238:241], v[78:81]
	v_mfma_f32_16x16x32_bf16 v[74:77], v[190:193], v[238:241], v[74:77]
	v_mfma_f32_16x16x32_bf16 v[118:121], v[194:197], v[210:213], v[118:121]
	v_mfma_f32_16x16x32_bf16 v[114:117], v[202:205], v[210:213], v[114:117]
	v_mfma_f32_16x16x32_bf16 v[102:105], v[194:197], v[218:221], v[102:105]
	v_mfma_f32_16x16x32_bf16 v[98:101], v[202:205], v[218:221], v[98:101]
	v_mfma_f32_16x16x32_bf16 v[86:89], v[194:197], v[226:229], v[86:89]
	v_mfma_f32_16x16x32_bf16 v[82:85], v[202:205], v[226:229], v[82:85]
	v_mfma_f32_16x16x32_bf16 v[70:73], v[194:197], v[234:237], v[70:73]
	v_mfma_f32_16x16x32_bf16 v[66:69], v[202:205], v[234:237], v[66:69]
	v_mfma_f32_16x16x32_bf16 v[118:121], v[198:201], v[214:217], v[118:121]
	v_mfma_f32_16x16x32_bf16 v[114:117], v[206:209], v[214:217], v[114:117]
	v_mfma_f32_16x16x32_bf16 v[102:105], v[198:201], v[222:225], v[102:105]
	v_mfma_f32_16x16x32_bf16 v[98:101], v[206:209], v[222:225], v[98:101]
	v_mfma_f32_16x16x32_bf16 v[86:89], v[198:201], v[230:233], v[86:89]
	v_mfma_f32_16x16x32_bf16 v[82:85], v[206:209], v[230:233], v[82:85]
	v_mfma_f32_16x16x32_bf16 v[70:73], v[198:201], v[238:241], v[70:73]
	v_mfma_f32_16x16x32_bf16 v[66:69], v[206:209], v[238:241], v[66:69]
	s_barrier
	s_add_i32 s3, s3, s11
	v_lshl_add_u64 v[162:163], v[162:163], 0, s[70:71]
	s_mov_b32 m0, s3
	ds_read_b128 v[210:213], v147 offset:49152
	ds_read_b128 v[214:217], v147 offset:50176
	ds_read_b128 v[218:221], v147 offset:51200
	ds_read_b128 v[222:225], v147 offset:52224
	ds_read_b128 v[226:229], v147 offset:53248
	ds_read_b128 v[230:233], v147 offset:54272
	ds_read_b128 v[234:237], v147 offset:55296
	ds_read_b128 v[238:241], v147 offset:56320
	global_load_lds_dwordx4 v[162:163], off
	s_add_i32 m0, s3, 0x2000
	s_add_u32 s0, s0, 0x80080
	v_lshl_add_u64 v[162:163], v[166:167], 0, s[70:71]
	s_addc_u32 s1, s1, 0
	s_add_i32 s3, s6, s11
	global_load_lds_dwordx4 v[162:163], off
	s_mov_b32 m0, s3
	s_nop 0
	global_load_lds_dwordx4 v4, s[0:1]
	s_add_i32 m0, s3, 0x2000
	s_nop 0
	global_load_lds_dwordx4 v130, s[0:1]
	v_lshl_add_u64 v[162:163], v[176:177], 0, s[70:71]
	s_mov_b32 m0, s35
	s_nop 0
	global_load_lds_dwordx4 v[162:163], off
	v_lshl_add_u64 v[162:163], v[180:181], 0, s[70:71]
	s_mov_b32 m0, s36
	s_nop 0
	global_load_lds_dwordx4 v[162:163], off
	s_waitcnt vmcnt(8) lgkmcnt(0)
	s_barrier
	v_mfma_f32_16x16x32_bf16 v[62:65], v[140:143], v[210:213], v[62:65]
	v_mfma_f32_16x16x32_bf16 v[58:61], v[172:175], v[210:213], v[58:61]
	v_mfma_f32_16x16x32_bf16 v[46:49], v[140:143], v[218:221], v[46:49]
	v_mfma_f32_16x16x32_bf16 v[42:45], v[172:175], v[218:221], v[42:45]
	v_mfma_f32_16x16x32_bf16 v[30:33], v[140:143], v[226:229], v[30:33]
	v_mfma_f32_16x16x32_bf16 v[26:29], v[172:175], v[226:229], v[26:29]
	v_mfma_f32_16x16x32_bf16 v[14:17], v[140:143], v[234:237], v[14:17]
	v_mfma_f32_16x16x32_bf16 v[10:13], v[172:175], v[234:237], v[10:13]
	v_mfma_f32_16x16x32_bf16 v[62:65], v[148:151], v[214:217], v[62:65]
	v_mfma_f32_16x16x32_bf16 v[58:61], v[190:193], v[214:217], v[58:61]
	v_mfma_f32_16x16x32_bf16 v[46:49], v[148:151], v[222:225], v[46:49]
	v_mfma_f32_16x16x32_bf16 v[42:45], v[190:193], v[222:225], v[42:45]
	v_mfma_f32_16x16x32_bf16 v[30:33], v[148:151], v[230:233], v[30:33]
	v_mfma_f32_16x16x32_bf16 v[26:29], v[190:193], v[230:233], v[26:29]
	v_mfma_f32_16x16x32_bf16 v[14:17], v[148:151], v[238:241], v[14:17]
	v_mfma_f32_16x16x32_bf16 v[10:13], v[190:193], v[238:241], v[10:13]
	v_mfma_f32_16x16x32_bf16 v[54:57], v[194:197], v[210:213], v[54:57]
	v_mfma_f32_16x16x32_bf16 v[50:53], v[202:205], v[210:213], v[50:53]
	v_mfma_f32_16x16x32_bf16 v[38:41], v[194:197], v[218:221], v[38:41]
	v_mfma_f32_16x16x32_bf16 v[34:37], v[202:205], v[218:221], v[34:37]
	v_mfma_f32_16x16x32_bf16 v[22:25], v[194:197], v[226:229], v[22:25]
	v_mfma_f32_16x16x32_bf16 v[18:21], v[202:205], v[226:229], v[18:21]
	v_mfma_f32_16x16x32_bf16 v[6:9], v[194:197], v[234:237], v[6:9]
	v_mfma_f32_16x16x32_bf16 v[0:3], v[202:205], v[234:237], v[0:3]
	v_mfma_f32_16x16x32_bf16 v[54:57], v[198:201], v[214:217], v[54:57]
	v_mfma_f32_16x16x32_bf16 v[50:53], v[206:209], v[214:217], v[50:53]
	v_mfma_f32_16x16x32_bf16 v[38:41], v[198:201], v[222:225], v[38:41]
	v_mfma_f32_16x16x32_bf16 v[34:37], v[206:209], v[222:225], v[34:37]
	v_mfma_f32_16x16x32_bf16 v[22:25], v[198:201], v[230:233], v[22:25]
	v_mfma_f32_16x16x32_bf16 v[18:21], v[206:209], v[230:233], v[18:21]
	v_mfma_f32_16x16x32_bf16 v[6:9], v[198:201], v[238:241], v[6:9]
	v_mfma_f32_16x16x32_bf16 v[0:3], v[206:209], v[238:241], v[0:3]
	s_barrier
	s_add_i32 s24, s24, 2
	s_add_u32 s22, s22, 0x100
	s_addc_u32 s23, s23, 0
	s_add_u32 s9, s9, 0x100
	s_addc_u32 s10, s10, 0
	s_cmp_gt_u32 s24, 29
	s_cbranch_scc0 .LBB0_163
	s_and_b64 vcc, exec, s[46:47]
	s_cbranch_vccz .LBB0_166
	s_barrier

.LBB0_204:
	s_ashr_i32 s49, s48, 31
	s_lshl_b64 s[2:3], s[48:49], 19
	v_readlane_b32 s4, v253, 17
	v_readlane_b32 s5, v253, 18
	s_add_u32 s84, s4, s2
	s_addc_u32 s85, s5, s3
	s_and_b64 s[2:3], s[42:43], exec
	s_cselect_b32 s2, s85, s15
	s_cselect_b32 s8, s84, s14
	s_add_u32 s22, s0, 0x40080
	s_addc_u32 s23, s1, 0
	s_add_u32 s9, s14, 0x100
	v_mov_b32_e32 v0, 0
	s_addc_u32 s10, s15, 0
	s_mov_b32 s24, -2
	v_mov_b32_e32 v1, v0
	v_mov_b32_e32 v2, v0
	v_mov_b32_e32 v3, v0
	v_mov_b32_e32 v6, v0
	v_mov_b32_e32 v7, v0
	v_mov_b32_e32 v8, v0
	v_mov_b32_e32 v9, v0
	v_mov_b32_e32 v10, v0
	v_mov_b32_e32 v11, v0
	v_mov_b32_e32 v12, v0
	v_mov_b32_e32 v13, v0
	v_mov_b32_e32 v14, v0
	v_mov_b32_e32 v15, v0
	v_mov_b32_e32 v16, v0
	v_mov_b32_e32 v17, v0
	v_mov_b32_e32 v18, v0
	v_mov_b32_e32 v19, v0
	v_mov_b32_e32 v20, v0
	v_mov_b32_e32 v21, v0
	v_mov_b32_e32 v22, v0
	v_mov_b32_e32 v23, v0
	v_mov_b32_e32 v24, v0
	v_mov_b32_e32 v25, v0
	v_mov_b32_e32 v26, v0
	v_mov_b32_e32 v27, v0
	v_mov_b32_e32 v28, v0
	v_mov_b32_e32 v29, v0
	v_mov_b32_e32 v30, v0
	v_mov_b32_e32 v31, v0
	v_mov_b32_e32 v32, v0
	v_mov_b32_e32 v33, v0
	v_mov_b32_e32 v66, v0
	v_mov_b32_e32 v67, v0
	v_mov_b32_e32 v68, v0
	v_mov_b32_e32 v69, v0
	v_mov_b32_e32 v70, v0
	v_mov_b32_e32 v71, v0
	v_mov_b32_e32 v72, v0
	v_mov_b32_e32 v73, v0
	v_mov_b32_e32 v74, v0
	v_mov_b32_e32 v75, v0
	v_mov_b32_e32 v76, v0
	v_mov_b32_e32 v77, v0
	v_mov_b32_e32 v78, v0
	v_mov_b32_e32 v79, v0
	v_mov_b32_e32 v80, v0
	v_mov_b32_e32 v81, v0
	v_mov_b32_e32 v82, v0
	v_mov_b32_e32 v83, v0
	v_mov_b32_e32 v84, v0
	v_mov_b32_e32 v85, v0
	v_mov_b32_e32 v86, v0
	v_mov_b32_e32 v87, v0
	v_mov_b32_e32 v88, v0
	v_mov_b32_e32 v89, v0
	v_mov_b32_e32 v90, v0
	v_mov_b32_e32 v91, v0
	v_mov_b32_e32 v92, v0
	v_mov_b32_e32 v93, v0
	v_mov_b32_e32 v94, v0
	v_mov_b32_e32 v95, v0
	v_mov_b32_e32 v96, v0
	v_mov_b32_e32 v97, v0
	v_mov_b32_e32 v34, v0
	v_mov_b32_e32 v35, v0
	v_mov_b32_e32 v36, v0
	v_mov_b32_e32 v37, v0
	v_mov_b32_e32 v38, v0
	v_mov_b32_e32 v39, v0
	v_mov_b32_e32 v40, v0
	v_mov_b32_e32 v41, v0
	v_mov_b32_e32 v42, v0
	v_mov_b32_e32 v43, v0
	v_mov_b32_e32 v44, v0
	v_mov_b32_e32 v45, v0
	v_mov_b32_e32 v46, v0
	v_mov_b32_e32 v47, v0
	v_mov_b32_e32 v48, v0
	v_mov_b32_e32 v49, v0
	v_mov_b32_e32 v50, v0
	v_mov_b32_e32 v51, v0
	v_mov_b32_e32 v52, v0
	v_mov_b32_e32 v53, v0
	v_mov_b32_e32 v54, v0
	v_mov_b32_e32 v55, v0
	v_mov_b32_e32 v56, v0
	v_mov_b32_e32 v57, v0
	v_mov_b32_e32 v58, v0
	v_mov_b32_e32 v59, v0
	v_mov_b32_e32 v60, v0
	v_mov_b32_e32 v61, v0
	v_mov_b32_e32 v62, v0
	v_mov_b32_e32 v63, v0
	v_mov_b32_e32 v64, v0
	v_mov_b32_e32 v65, v0
	v_mov_b32_e32 v98, v0
	v_mov_b32_e32 v99, v0
	v_mov_b32_e32 v100, v0
	v_mov_b32_e32 v101, v0
	v_mov_b32_e32 v102, v0
	v_mov_b32_e32 v103, v0
	v_mov_b32_e32 v104, v0
	v_mov_b32_e32 v105, v0
	v_mov_b32_e32 v106, v0
	v_mov_b32_e32 v107, v0
	v_mov_b32_e32 v108, v0
	v_mov_b32_e32 v109, v0
	v_mov_b32_e32 v110, v0
	v_mov_b32_e32 v111, v0
	v_mov_b32_e32 v112, v0
	v_mov_b32_e32 v113, v0
	v_mov_b32_e32 v114, v0
	v_mov_b32_e32 v115, v0
	v_mov_b32_e32 v116, v0
	v_mov_b32_e32 v117, v0
	v_mov_b32_e32 v118, v0
	v_mov_b32_e32 v119, v0
	v_mov_b32_e32 v120, v0
	v_mov_b32_e32 v121, v0
	v_mov_b32_e32 v122, v0
	v_mov_b32_e32 v123, v0
	v_mov_b32_e32 v124, v0
	v_mov_b32_e32 v125, v0
	v_mov_b32_e32 v126, v0
	v_mov_b32_e32 v127, v0
	v_mov_b32_e32 v128, v0
	v_mov_b32_e32 v129, v0
	s_cmp_eq_u32 s37, 1
	s_cbranch_scc1 .LBB0_205
	s_add_u32 s0, s22, 0xfffc0080
	s_addc_u32 s1, s23, -1
	s_add_i32 s3, 0, 0x10000
	s_cmp_eq_u32 s24, 12
	s_cselect_b32 s15, s83, s1
	s_cselect_b32 s14, s82, s0
	v_add_u32_e32 v144, s3, v168
	s_cselect_b32 s1, s2, s10
	s_cselect_b32 s0, s8, s9
	s_add_i32 s6, 0, 0x14000
	ds_read_b128 v[140:143], v144
	ds_read_b128 v[174:177], v144 offset:1024
	ds_read_b128 v[190:193], v144 offset:2048
	ds_read_b128 v[194:197], v144 offset:3072
	v_add_u32_e32 v144, s6, v168
	ds_read_b128 v[198:201], v144
	ds_read_b128 v[202:205], v144 offset:1024
	ds_read_b128 v[206:209], v144 offset:2048
	ds_read_b128 v[210:213], v144 offset:3072
	s_add_i32 m0, s27, 0xc000
	ds_read_b128 v[214:217], v172
	ds_read_b128 v[218:221], v172 offset:1024
	ds_read_b128 v[222:225], v172 offset:2048
	ds_read_b128 v[226:229], v172 offset:3072
	ds_read_b128 v[230:233], v172 offset:4096
	ds_read_b128 v[234:237], v172 offset:5120
	ds_read_b128 v[238:241], v172 offset:6144
	ds_read_b128 v[242:245], v172 offset:7168
	global_load_lds_dwordx4 v136, s[22:23]
	s_add_i32 m0, s27, 0xe000
	s_nop 0
	global_load_lds_dwordx4 v138, s[22:23]
	s_waitcnt vmcnt(24) lgkmcnt(0)
	s_barrier
	v_mfma_f32_16x16x32_bf16 v[126:129], v[140:143], v[214:217], v[126:129]
	v_mfma_f32_16x16x32_bf16 v[122:125], v[190:193], v[214:217], v[122:125]
	v_mfma_f32_16x16x32_bf16 v[118:121], v[140:143], v[222:225], v[118:121]
	v_mfma_f32_16x16x32_bf16 v[114:117], v[190:193], v[222:225], v[114:117]
	v_mfma_f32_16x16x32_bf16 v[110:113], v[140:143], v[230:233], v[110:113]
	v_mfma_f32_16x16x32_bf16 v[106:109], v[190:193], v[230:233], v[106:109]
	v_mfma_f32_16x16x32_bf16 v[102:105], v[140:143], v[238:241], v[102:105]
	v_mfma_f32_16x16x32_bf16 v[98:101], v[190:193], v[238:241], v[98:101]
	v_mfma_f32_16x16x32_bf16 v[126:129], v[174:177], v[218:221], v[126:129]
	v_mfma_f32_16x16x32_bf16 v[122:125], v[194:197], v[218:221], v[122:125]
	v_mfma_f32_16x16x32_bf16 v[118:121], v[174:177], v[226:229], v[118:121]
	v_mfma_f32_16x16x32_bf16 v[114:117], v[194:197], v[226:229], v[114:117]
	v_mfma_f32_16x16x32_bf16 v[110:113], v[174:177], v[234:237], v[110:113]
	v_mfma_f32_16x16x32_bf16 v[106:109], v[194:197], v[234:237], v[106:109]
	v_mfma_f32_16x16x32_bf16 v[102:105], v[174:177], v[242:245], v[102:105]
	v_mfma_f32_16x16x32_bf16 v[98:101], v[194:197], v[242:245], v[98:101]
	v_mfma_f32_16x16x32_bf16 v[62:65], v[198:201], v[214:217], v[62:65]
	v_mfma_f32_16x16x32_bf16 v[58:61], v[206:209], v[214:217], v[58:61]
	v_mfma_f32_16x16x32_bf16 v[54:57], v[198:201], v[222:225], v[54:57]
	v_mfma_f32_16x16x32_bf16 v[50:53], v[206:209], v[222:225], v[50:53]
	v_mfma_f32_16x16x32_bf16 v[46:49], v[198:201], v[230:233], v[46:49]
	v_mfma_f32_16x16x32_bf16 v[42:45], v[206:209], v[230:233], v[42:45]
	v_mfma_f32_16x16x32_bf16 v[38:41], v[198:201], v[238:241], v[38:41]
	v_mfma_f32_16x16x32_bf16 v[34:37], v[206:209], v[238:241], v[34:37]
	v_mfma_f32_16x16x32_bf16 v[62:65], v[202:205], v[218:221], v[62:65]
	v_mfma_f32_16x16x32_bf16 v[58:61], v[210:213], v[218:221], v[58:61]
	v_mfma_f32_16x16x32_bf16 v[54:57], v[202:205], v[226:229], v[54:57]
	v_mfma_f32_16x16x32_bf16 v[50:53], v[210:213], v[226:229], v[50:53]
	v_mfma_f32_16x16x32_bf16 v[46:49], v[202:205], v[234:237], v[46:49]
	v_mfma_f32_16x16x32_bf16 v[42:45], v[210:213], v[234:237], v[42:45]
	v_mfma_f32_16x16x32_bf16 v[38:41], v[202:205], v[242:245], v[38:41]
	v_mfma_f32_16x16x32_bf16 v[34:37], v[210:213], v[242:245], v[34:37]
	s_barrier
	s_add_i32 s3, s3, s26
	v_lshl_add_u64 v[144:145], s[0:1], 0, v[4:5]
	s_mov_b32 m0, s3
	ds_read_b128 v[214:217], v172 offset:16384
	ds_read_b128 v[218:221], v172 offset:17408
	ds_read_b128 v[222:225], v172 offset:18432
	ds_read_b128 v[226:229], v172 offset:19456
	ds_read_b128 v[230:233], v172 offset:20480
	ds_read_b128 v[234:237], v172 offset:21504
	ds_read_b128 v[238:241], v172 offset:22528
	ds_read_b128 v[242:245], v172 offset:23552
	global_load_lds_dwordx4 v4, s[0:1]
	s_add_i32 m0, s3, 0x2000
	s_add_u32 s4, s0, 0x40000
	v_lshl_add_u64 v[246:247], s[0:1], 0, v[134:135]
	s_addc_u32 s5, s1, 0
	s_add_i32 s3, s6, s26
	global_load_lds_dwordx4 v134, s[0:1]
	s_mov_b32 m0, s3
	v_lshl_add_u64 v[250:251], s[14:15], 0, v[132:133]
	global_load_lds_dwordx4 v4, s[4:5]
	s_add_i32 m0, s3, 0x2000
	s_nop 0
	global_load_lds_dwordx4 v134, s[4:5]
	v_lshl_add_u64 v[248:249], s[14:15], 0, v[130:131]
	s_mov_b32 m0, s27
	s_nop 0
	global_load_lds_dwordx4 v130, s[14:15]
	s_mov_b32 m0, s30
	s_nop 0
	global_load_lds_dwordx4 v132, s[14:15]
	s_waitcnt vmcnt(24) lgkmcnt(0)
	s_barrier
	v_mfma_f32_16x16x32_bf16 v[94:97], v[140:143], v[214:217], v[94:97]
	v_mfma_f32_16x16x32_bf16 v[90:93], v[190:193], v[214:217], v[90:93]
	v_mfma_f32_16x16x32_bf16 v[86:89], v[140:143], v[222:225], v[86:89]
	v_mfma_f32_16x16x32_bf16 v[82:85], v[190:193], v[222:225], v[82:85]
	v_mfma_f32_16x16x32_bf16 v[78:81], v[140:143], v[230:233], v[78:81]
	v_mfma_f32_16x16x32_bf16 v[74:77], v[190:193], v[230:233], v[74:77]
	v_mfma_f32_16x16x32_bf16 v[70:73], v[140:143], v[238:241], v[70:73]
	v_mfma_f32_16x16x32_bf16 v[66:69], v[190:193], v[238:241], v[66:69]
	v_mfma_f32_16x16x32_bf16 v[94:97], v[174:177], v[218:221], v[94:97]
	v_mfma_f32_16x16x32_bf16 v[90:93], v[194:197], v[218:221], v[90:93]
	v_mfma_f32_16x16x32_bf16 v[86:89], v[174:177], v[226:229], v[86:89]
	v_mfma_f32_16x16x32_bf16 v[82:85], v[194:197], v[226:229], v[82:85]
	v_mfma_f32_16x16x32_bf16 v[78:81], v[174:177], v[234:237], v[78:81]
	v_mfma_f32_16x16x32_bf16 v[74:77], v[194:197], v[234:237], v[74:77]
	v_mfma_f32_16x16x32_bf16 v[70:73], v[174:177], v[242:245], v[70:73]
	v_mfma_f32_16x16x32_bf16 v[66:69], v[194:197], v[242:245], v[66:69]
	v_mfma_f32_16x16x32_bf16 v[30:33], v[198:201], v[214:217], v[30:33]
	v_mfma_f32_16x16x32_bf16 v[26:29], v[206:209], v[214:217], v[26:29]
	v_mfma_f32_16x16x32_bf16 v[22:25], v[198:201], v[222:225], v[22:25]
	v_mfma_f32_16x16x32_bf16 v[18:21], v[206:209], v[222:225], v[18:21]
	v_mfma_f32_16x16x32_bf16 v[14:17], v[198:201], v[230:233], v[14:17]
	v_mfma_f32_16x16x32_bf16 v[10:13], v[206:209], v[230:233], v[10:13]
	v_mfma_f32_16x16x32_bf16 v[6:9], v[198:201], v[238:241], v[6:9]
	v_mfma_f32_16x16x32_bf16 v[0:3], v[206:209], v[238:241], v[0:3]
	v_mfma_f32_16x16x32_bf16 v[30:33], v[202:205], v[218:221], v[30:33]
	v_mfma_f32_16x16x32_bf16 v[26:29], v[210:213], v[218:221], v[26:29]
	v_mfma_f32_16x16x32_bf16 v[22:25], v[202:205], v[226:229], v[22:25]
	v_mfma_f32_16x16x32_bf16 v[18:21], v[210:213], v[226:229], v[18:21]
	v_mfma_f32_16x16x32_bf16 v[14:17], v[202:205], v[234:237], v[14:17]
	v_mfma_f32_16x16x32_bf16 v[10:13], v[210:213], v[234:237], v[10:13]
	v_mfma_f32_16x16x32_bf16 v[6:9], v[202:205], v[242:245], v[6:9]
	v_mfma_f32_16x16x32_bf16 v[0:3], v[210:213], v[242:245], v[0:3]
	s_barrier
	s_branch .Lpeelmid_205
.LBB0_205:
	s_add_u32 s0, s22, 0xfffc0080
	s_addc_u32 s1, s23, -1
	s_add_i32 s3, 0, 0x10000
	s_cmp_eq_u32 s24, 12
	s_cselect_b32 s15, s83, s1
	s_cselect_b32 s14, s82, s0
	v_add_u32_e32 v144, s3, v168
	s_cselect_b32 s1, s2, s10
	s_cselect_b32 s0, s8, s9
	s_add_i32 s6, 0, 0x14000
	ds_read_b128 v[140:143], v144
	ds_read_b128 v[174:177], v144 offset:1024
	ds_read_b128 v[190:193], v144 offset:2048
	ds_read_b128 v[194:197], v144 offset:3072
	v_add_u32_e32 v144, s6, v168
	ds_read_b128 v[198:201], v144
	ds_read_b128 v[202:205], v144 offset:1024
	ds_read_b128 v[206:209], v144 offset:2048
	ds_read_b128 v[210:213], v144 offset:3072
	s_add_i32 m0, s27, 0xc000
	ds_read_b128 v[214:217], v172
	ds_read_b128 v[218:221], v172 offset:1024
	ds_read_b128 v[222:225], v172 offset:2048
	ds_read_b128 v[226:229], v172 offset:3072
	ds_read_b128 v[230:233], v172 offset:4096
	ds_read_b128 v[234:237], v172 offset:5120
	ds_read_b128 v[238:241], v172 offset:6144
	ds_read_b128 v[242:245], v172 offset:7168
	global_load_lds_dwordx4 v136, s[22:23]
	s_add_i32 m0, s27, 0xe000
	s_nop 0
	global_load_lds_dwordx4 v138, s[22:23]
	s_waitcnt vmcnt(8) lgkmcnt(0)
	s_barrier
	v_mfma_f32_16x16x32_bf16 v[126:129], v[140:143], v[214:217], v[126:129]
	v_mfma_f32_16x16x32_bf16 v[122:125], v[190:193], v[214:217], v[122:125]
	v_mfma_f32_16x16x32_bf16 v[118:121], v[140:143], v[222:225], v[118:121]
	v_mfma_f32_16x16x32_bf16 v[114:117], v[190:193], v[222:225], v[114:117]
	v_mfma_f32_16x16x32_bf16 v[110:113], v[140:143], v[230:233], v[110:113]
	v_mfma_f32_16x16x32_bf16 v[106:109], v[190:193], v[230:233], v[106:109]
	v_mfma_f32_16x16x32_bf16 v[102:105], v[140:143], v[238:241], v[102:105]
	v_mfma_f32_16x16x32_bf16 v[98:101], v[190:193], v[238:241], v[98:101]
	v_mfma_f32_16x16x32_bf16 v[126:129], v[174:177], v[218:221], v[126:129]
	v_mfma_f32_16x16x32_bf16 v[122:125], v[194:197], v[218:221], v[122:125]
	v_mfma_f32_16x16x32_bf16 v[118:121], v[174:177], v[226:229], v[118:121]
	v_mfma_f32_16x16x32_bf16 v[114:117], v[194:197], v[226:229], v[114:117]
	v_mfma_f32_16x16x32_bf16 v[110:113], v[174:177], v[234:237], v[110:113]
	v_mfma_f32_16x16x32_bf16 v[106:109], v[194:197], v[234:237], v[106:109]
	v_mfma_f32_16x16x32_bf16 v[102:105], v[174:177], v[242:245], v[102:105]
	v_mfma_f32_16x16x32_bf16 v[98:101], v[194:197], v[242:245], v[98:101]
	v_mfma_f32_16x16x32_bf16 v[62:65], v[198:201], v[214:217], v[62:65]
	v_mfma_f32_16x16x32_bf16 v[58:61], v[206:209], v[214:217], v[58:61]
	v_mfma_f32_16x16x32_bf16 v[54:57], v[198:201], v[222:225], v[54:57]
	v_mfma_f32_16x16x32_bf16 v[50:53], v[206:209], v[222:225], v[50:53]
	v_mfma_f32_16x16x32_bf16 v[46:49], v[198:201], v[230:233], v[46:49]
	v_mfma_f32_16x16x32_bf16 v[42:45], v[206:209], v[230:233], v[42:45]
	v_mfma_f32_16x16x32_bf16 v[38:41], v[198:201], v[238:241], v[38:41]
	v_mfma_f32_16x16x32_bf16 v[34:37], v[206:209], v[238:241], v[34:37]
	v_mfma_f32_16x16x32_bf16 v[62:65], v[202:205], v[218:221], v[62:65]
	v_mfma_f32_16x16x32_bf16 v[58:61], v[210:213], v[218:221], v[58:61]
	v_mfma_f32_16x16x32_bf16 v[54:57], v[202:205], v[226:229], v[54:57]
	v_mfma_f32_16x16x32_bf16 v[50:53], v[210:213], v[226:229], v[50:53]
	v_mfma_f32_16x16x32_bf16 v[46:49], v[202:205], v[234:237], v[46:49]
	v_mfma_f32_16x16x32_bf16 v[42:45], v[210:213], v[234:237], v[42:45]
	v_mfma_f32_16x16x32_bf16 v[38:41], v[202:205], v[242:245], v[38:41]
	v_mfma_f32_16x16x32_bf16 v[34:37], v[210:213], v[242:245], v[34:37]
	s_barrier
	s_add_i32 s3, s3, s26
	v_lshl_add_u64 v[144:145], s[0:1], 0, v[4:5]
	s_mov_b32 m0, s3
	ds_read_b128 v[214:217], v172 offset:16384
	ds_read_b128 v[218:221], v172 offset:17408
	ds_read_b128 v[222:225], v172 offset:18432
	ds_read_b128 v[226:229], v172 offset:19456
	ds_read_b128 v[230:233], v172 offset:20480
	ds_read_b128 v[234:237], v172 offset:21504
	ds_read_b128 v[238:241], v172 offset:22528
	ds_read_b128 v[242:245], v172 offset:23552
	global_load_lds_dwordx4 v4, s[0:1]
	s_add_i32 m0, s3, 0x2000
	s_add_u32 s4, s0, 0x40000
	v_lshl_add_u64 v[246:247], s[0:1], 0, v[134:135]
	s_addc_u32 s5, s1, 0
	s_add_i32 s3, s6, s26
	global_load_lds_dwordx4 v134, s[0:1]
	s_mov_b32 m0, s3
	v_lshl_add_u64 v[250:251], s[14:15], 0, v[132:133]
	global_load_lds_dwordx4 v4, s[4:5]
	s_add_i32 m0, s3, 0x2000
	s_nop 0
	global_load_lds_dwordx4 v134, s[4:5]
	v_lshl_add_u64 v[248:249], s[14:15], 0, v[130:131]
	s_mov_b32 m0, s27
	s_nop 0
	global_load_lds_dwordx4 v130, s[14:15]
	s_mov_b32 m0, s30
	s_nop 0
	global_load_lds_dwordx4 v132, s[14:15]
	s_waitcnt vmcnt(8) lgkmcnt(0)
	s_barrier
	v_mfma_f32_16x16x32_bf16 v[94:97], v[140:143], v[214:217], v[94:97]
	v_mfma_f32_16x16x32_bf16 v[90:93], v[190:193], v[214:217], v[90:93]
	v_mfma_f32_16x16x32_bf16 v[86:89], v[140:143], v[222:225], v[86:89]
	v_mfma_f32_16x16x32_bf16 v[82:85], v[190:193], v[222:225], v[82:85]
	v_mfma_f32_16x16x32_bf16 v[78:81], v[140:143], v[230:233], v[78:81]
	v_mfma_f32_16x16x32_bf16 v[74:77], v[190:193], v[230:233], v[74:77]
	v_mfma_f32_16x16x32_bf16 v[70:73], v[140:143], v[238:241], v[70:73]
	v_mfma_f32_16x16x32_bf16 v[66:69], v[190:193], v[238:241], v[66:69]
	v_mfma_f32_16x16x32_bf16 v[94:97], v[174:177], v[218:221], v[94:97]
	v_mfma_f32_16x16x32_bf16 v[90:93], v[194:197], v[218:221], v[90:93]
	v_mfma_f32_16x16x32_bf16 v[86:89], v[174:177], v[226:229], v[86:89]
	v_mfma_f32_16x16x32_bf16 v[82:85], v[194:197], v[226:229], v[82:85]
	v_mfma_f32_16x16x32_bf16 v[78:81], v[174:177], v[234:237], v[78:81]
	v_mfma_f32_16x16x32_bf16 v[74:77], v[194:197], v[234:237], v[74:77]
	v_mfma_f32_16x16x32_bf16 v[70:73], v[174:177], v[242:245], v[70:73]
	v_mfma_f32_16x16x32_bf16 v[66:69], v[194:197], v[242:245], v[66:69]
	v_mfma_f32_16x16x32_bf16 v[30:33], v[198:201], v[214:217], v[30:33]
	v_mfma_f32_16x16x32_bf16 v[26:29], v[206:209], v[214:217], v[26:29]
	v_mfma_f32_16x16x32_bf16 v[22:25], v[198:201], v[222:225], v[22:25]
	v_mfma_f32_16x16x32_bf16 v[18:21], v[206:209], v[222:225], v[18:21]
	v_mfma_f32_16x16x32_bf16 v[14:17], v[198:201], v[230:233], v[14:17]
	v_mfma_f32_16x16x32_bf16 v[10:13], v[206:209], v[230:233], v[10:13]
	v_mfma_f32_16x16x32_bf16 v[6:9], v[198:201], v[238:241], v[6:9]
	v_mfma_f32_16x16x32_bf16 v[0:3], v[206:209], v[238:241], v[0:3]
	v_mfma_f32_16x16x32_bf16 v[30:33], v[202:205], v[218:221], v[30:33]
	v_mfma_f32_16x16x32_bf16 v[26:29], v[210:213], v[218:221], v[26:29]
	v_mfma_f32_16x16x32_bf16 v[22:25], v[202:205], v[226:229], v[22:25]
	v_mfma_f32_16x16x32_bf16 v[18:21], v[210:213], v[226:229], v[18:21]
	v_mfma_f32_16x16x32_bf16 v[14:17], v[202:205], v[234:237], v[14:17]
	v_mfma_f32_16x16x32_bf16 v[10:13], v[210:213], v[234:237], v[10:13]
	v_mfma_f32_16x16x32_bf16 v[6:9], v[202:205], v[242:245], v[6:9]
	v_mfma_f32_16x16x32_bf16 v[0:3], v[210:213], v[242:245], v[0:3]
	s_barrier
.Lpeelmid_205:
	s_add_i32 s3, 0, 0x18000
	v_add_u32_e32 v173, s3, v168
	s_add_i32 s6, 0, 0x1c000
	ds_read_b128 v[140:143], v173
	ds_read_b128 v[174:177], v173 offset:1024
	ds_read_b128 v[190:193], v173 offset:2048
	ds_read_b128 v[194:197], v173 offset:3072
	v_add_u32_e32 v173, s6, v168
	ds_read_b128 v[198:201], v173
	ds_read_b128 v[202:205], v173 offset:1024
	ds_read_b128 v[206:209], v173 offset:2048
	ds_read_b128 v[210:213], v173 offset:3072
	s_add_u32 s4, s14, 0x40000
	s_addc_u32 s5, s15, 0
	s_mov_b32 m0, s31
	ds_read_b128 v[214:217], v172 offset:32768
	ds_read_b128 v[218:221], v172 offset:33792
	ds_read_b128 v[222:225], v172 offset:34816
	ds_read_b128 v[226:229], v172 offset:35840
	ds_read_b128 v[230:233], v172 offset:36864
	ds_read_b128 v[234:237], v172 offset:37888
	ds_read_b128 v[238:241], v172 offset:38912
	ds_read_b128 v[242:245], v172 offset:39936
	global_load_lds_dwordx4 v130, s[4:5]
	v_lshl_add_u64 v[180:181], s[4:5], 0, v[132:133]
	s_mov_b32 m0, s34
	s_nop 0
	global_load_lds_dwordx4 v132, s[4:5]
	s_waitcnt vmcnt(8) lgkmcnt(0)
	s_barrier
	v_mfma_f32_16x16x32_bf16 v[126:129], v[140:143], v[214:217], v[126:129]
	v_mfma_f32_16x16x32_bf16 v[122:125], v[190:193], v[214:217], v[122:125]
	v_mfma_f32_16x16x32_bf16 v[118:121], v[140:143], v[222:225], v[118:121]
	v_mfma_f32_16x16x32_bf16 v[114:117], v[190:193], v[222:225], v[114:117]
	v_mfma_f32_16x16x32_bf16 v[110:113], v[140:143], v[230:233], v[110:113]
	v_mfma_f32_16x16x32_bf16 v[106:109], v[190:193], v[230:233], v[106:109]
	v_mfma_f32_16x16x32_bf16 v[102:105], v[140:143], v[238:241], v[102:105]
	v_mfma_f32_16x16x32_bf16 v[98:101], v[190:193], v[238:241], v[98:101]
	v_mfma_f32_16x16x32_bf16 v[126:129], v[174:177], v[218:221], v[126:129]
	v_mfma_f32_16x16x32_bf16 v[122:125], v[194:197], v[218:221], v[122:125]
	v_mfma_f32_16x16x32_bf16 v[118:121], v[174:177], v[226:229], v[118:121]
	v_mfma_f32_16x16x32_bf16 v[114:117], v[194:197], v[226:229], v[114:117]
	v_mfma_f32_16x16x32_bf16 v[110:113], v[174:177], v[234:237], v[110:113]
	v_mfma_f32_16x16x32_bf16 v[106:109], v[194:197], v[234:237], v[106:109]
	v_mfma_f32_16x16x32_bf16 v[102:105], v[174:177], v[242:245], v[102:105]
	v_mfma_f32_16x16x32_bf16 v[98:101], v[194:197], v[242:245], v[98:101]
	v_mfma_f32_16x16x32_bf16 v[62:65], v[198:201], v[214:217], v[62:65]
	v_mfma_f32_16x16x32_bf16 v[58:61], v[206:209], v[214:217], v[58:61]
	v_mfma_f32_16x16x32_bf16 v[54:57], v[198:201], v[222:225], v[54:57]
	v_mfma_f32_16x16x32_bf16 v[50:53], v[206:209], v[222:225], v[50:53]
	v_mfma_f32_16x16x32_bf16 v[46:49], v[198:201], v[230:233], v[46:49]
	v_mfma_f32_16x16x32_bf16 v[42:45], v[206:209], v[230:233], v[42:45]
	v_mfma_f32_16x16x32_bf16 v[38:41], v[198:201], v[238:241], v[38:41]
	v_mfma_f32_16x16x32_bf16 v[34:37], v[206:209], v[238:241], v[34:37]
	v_mfma_f32_16x16x32_bf16 v[62:65], v[202:205], v[218:221], v[62:65]
	v_mfma_f32_16x16x32_bf16 v[58:61], v[210:213], v[218:221], v[58:61]
	v_mfma_f32_16x16x32_bf16 v[54:57], v[202:205], v[226:229], v[54:57]
	v_mfma_f32_16x16x32_bf16 v[50:53], v[210:213], v[226:229], v[50:53]
	v_mfma_f32_16x16x32_bf16 v[46:49], v[202:205], v[234:237], v[46:49]
	v_mfma_f32_16x16x32_bf16 v[42:45], v[210:213], v[234:237], v[42:45]
	v_mfma_f32_16x16x32_bf16 v[38:41], v[202:205], v[242:245], v[38:41]
	v_mfma_f32_16x16x32_bf16 v[34:37], v[210:213], v[242:245], v[34:37]
	s_barrier
	s_add_i32 s3, s3, s26
	v_lshl_add_u64 v[144:145], v[144:145], 0, s[70:71]
	s_mov_b32 m0, s3
	ds_read_b128 v[214:217], v172 offset:49152
	ds_read_b128 v[218:221], v172 offset:50176
	ds_read_b128 v[222:225], v172 offset:51200
	ds_read_b128 v[226:229], v172 offset:52224
	ds_read_b128 v[230:233], v172 offset:53248
	ds_read_b128 v[234:237], v172 offset:54272
	ds_read_b128 v[238:241], v172 offset:55296
	ds_read_b128 v[242:245], v172 offset:56320
	global_load_lds_dwordx4 v[144:145], off
	s_add_i32 m0, s3, 0x2000
	s_add_u32 s0, s0, 0x40080
	v_lshl_add_u64 v[144:145], v[246:247], 0, s[70:71]
	s_addc_u32 s1, s1, 0
	s_add_i32 s3, s6, s26
	global_load_lds_dwordx4 v[144:145], off
	s_mov_b32 m0, s3
	s_nop 0
	global_load_lds_dwordx4 v4, s[0:1]
	s_add_i32 m0, s3, 0x2000
	s_nop 0
	global_load_lds_dwordx4 v134, s[0:1]
	v_lshl_add_u64 v[144:145], v[248:249], 0, s[70:71]
	s_mov_b32 m0, s35
	s_nop 0
	global_load_lds_dwordx4 v[144:145], off
	v_lshl_add_u64 v[144:145], v[250:251], 0, s[70:71]
	s_mov_b32 m0, s36
	s_nop 0
	global_load_lds_dwordx4 v[144:145], off
	s_waitcnt vmcnt(8) lgkmcnt(0)
	s_barrier
	v_mfma_f32_16x16x32_bf16 v[94:97], v[140:143], v[214:217], v[94:97]
	v_mfma_f32_16x16x32_bf16 v[90:93], v[190:193], v[214:217], v[90:93]
	v_mfma_f32_16x16x32_bf16 v[86:89], v[140:143], v[222:225], v[86:89]
	v_mfma_f32_16x16x32_bf16 v[82:85], v[190:193], v[222:225], v[82:85]
	v_mfma_f32_16x16x32_bf16 v[78:81], v[140:143], v[230:233], v[78:81]
	v_mfma_f32_16x16x32_bf16 v[74:77], v[190:193], v[230:233], v[74:77]
	v_mfma_f32_16x16x32_bf16 v[70:73], v[140:143], v[238:241], v[70:73]
	v_mfma_f32_16x16x32_bf16 v[66:69], v[190:193], v[238:241], v[66:69]
	v_mfma_f32_16x16x32_bf16 v[94:97], v[174:177], v[218:221], v[94:97]
	v_mfma_f32_16x16x32_bf16 v[90:93], v[194:197], v[218:221], v[90:93]
	v_mfma_f32_16x16x32_bf16 v[86:89], v[174:177], v[226:229], v[86:89]
	v_mfma_f32_16x16x32_bf16 v[82:85], v[194:197], v[226:229], v[82:85]
	v_mfma_f32_16x16x32_bf16 v[78:81], v[174:177], v[234:237], v[78:81]
	v_mfma_f32_16x16x32_bf16 v[74:77], v[194:197], v[234:237], v[74:77]
	v_mfma_f32_16x16x32_bf16 v[70:73], v[174:177], v[242:245], v[70:73]
	v_mfma_f32_16x16x32_bf16 v[66:69], v[194:197], v[242:245], v[66:69]
	v_mfma_f32_16x16x32_bf16 v[30:33], v[198:201], v[214:217], v[30:33]
	v_mfma_f32_16x16x32_bf16 v[26:29], v[206:209], v[214:217], v[26:29]
	v_mfma_f32_16x16x32_bf16 v[22:25], v[198:201], v[222:225], v[22:25]
	v_mfma_f32_16x16x32_bf16 v[18:21], v[206:209], v[222:225], v[18:21]
	v_mfma_f32_16x16x32_bf16 v[14:17], v[198:201], v[230:233], v[14:17]
	v_mfma_f32_16x16x32_bf16 v[10:13], v[206:209], v[230:233], v[10:13]
	v_mfma_f32_16x16x32_bf16 v[6:9], v[198:201], v[238:241], v[6:9]
	v_mfma_f32_16x16x32_bf16 v[0:3], v[206:209], v[238:241], v[0:3]
	v_mfma_f32_16x16x32_bf16 v[30:33], v[202:205], v[218:221], v[30:33]
	v_mfma_f32_16x16x32_bf16 v[26:29], v[210:213], v[218:221], v[26:29]
	v_mfma_f32_16x16x32_bf16 v[22:25], v[202:205], v[226:229], v[22:25]
	v_mfma_f32_16x16x32_bf16 v[18:21], v[210:213], v[226:229], v[18:21]
	v_mfma_f32_16x16x32_bf16 v[14:17], v[202:205], v[234:237], v[14:17]
	v_mfma_f32_16x16x32_bf16 v[10:13], v[210:213], v[234:237], v[10:13]
	v_mfma_f32_16x16x32_bf16 v[6:9], v[202:205], v[242:245], v[6:9]
	v_mfma_f32_16x16x32_bf16 v[0:3], v[210:213], v[242:245], v[0:3]
	s_barrier
	s_add_i32 s24, s24, 2
	s_add_u32 s22, s22, 0x100
	s_addc_u32 s23, s23, 0
	s_add_u32 s9, s9, 0x100
	s_addc_u32 s10, s10, 0
	s_cmp_gt_u32 s24, 13
	s_cbranch_scc0 .LBB0_205
	s_and_b64 vcc, exec, s[46:47]
	s_cbranch_vccz .LBB0_208
	s_barrier

.LBB0_227:
	s_ashr_i32 s47, s46, 31
	s_lshl_b64 s[2:3], s[46:47], 19
	v_readlane_b32 s4, v253, 25
	v_readlane_b32 s5, v253, 26
	s_add_u32 s82, s4, s2
	s_addc_u32 s83, s5, s3
	s_and_b64 s[2:3], s[40:41], exec
	s_cselect_b32 s2, s83, s15
	s_cselect_b32 s8, s82, s14
	s_add_u32 s22, s0, 0x40080
	s_addc_u32 s23, s1, 0
	s_add_u32 s9, s14, 0x100
	v_mov_b32_e32 v0, 0
	s_addc_u32 s10, s15, 0
	s_mov_b32 s24, -2
	v_mov_b32_e32 v1, v0
	v_mov_b32_e32 v2, v0
	v_mov_b32_e32 v3, v0
	v_mov_b32_e32 v6, v0
	v_mov_b32_e32 v7, v0
	v_mov_b32_e32 v8, v0
	v_mov_b32_e32 v9, v0
	v_mov_b32_e32 v10, v0
	v_mov_b32_e32 v11, v0
	v_mov_b32_e32 v12, v0
	v_mov_b32_e32 v13, v0
	v_mov_b32_e32 v14, v0
	v_mov_b32_e32 v15, v0
	v_mov_b32_e32 v16, v0
	v_mov_b32_e32 v17, v0
	v_mov_b32_e32 v18, v0
	v_mov_b32_e32 v19, v0
	v_mov_b32_e32 v20, v0
	v_mov_b32_e32 v21, v0
	v_mov_b32_e32 v22, v0
	v_mov_b32_e32 v23, v0
	v_mov_b32_e32 v24, v0
	v_mov_b32_e32 v25, v0
	v_mov_b32_e32 v26, v0
	v_mov_b32_e32 v27, v0
	v_mov_b32_e32 v28, v0
	v_mov_b32_e32 v29, v0
	v_mov_b32_e32 v30, v0
	v_mov_b32_e32 v31, v0
	v_mov_b32_e32 v32, v0
	v_mov_b32_e32 v33, v0
	v_mov_b32_e32 v62, v0
	v_mov_b32_e32 v63, v0
	v_mov_b32_e32 v64, v0
	v_mov_b32_e32 v65, v0
	v_mov_b32_e32 v70, v0
	v_mov_b32_e32 v71, v0
	v_mov_b32_e32 v72, v0
	v_mov_b32_e32 v73, v0
	v_mov_b32_e32 v74, v0
	v_mov_b32_e32 v75, v0
	v_mov_b32_e32 v76, v0
	v_mov_b32_e32 v77, v0
	v_mov_b32_e32 v78, v0
	v_mov_b32_e32 v79, v0
	v_mov_b32_e32 v80, v0
	v_mov_b32_e32 v81, v0
	v_mov_b32_e32 v82, v0
	v_mov_b32_e32 v83, v0
	v_mov_b32_e32 v84, v0
	v_mov_b32_e32 v85, v0
	v_mov_b32_e32 v86, v0
	v_mov_b32_e32 v87, v0
	v_mov_b32_e32 v88, v0
	v_mov_b32_e32 v89, v0
	v_mov_b32_e32 v90, v0
	v_mov_b32_e32 v91, v0
	v_mov_b32_e32 v92, v0
	v_mov_b32_e32 v93, v0
	v_mov_b32_e32 v94, v0
	v_mov_b32_e32 v95, v0
	v_mov_b32_e32 v96, v0
	v_mov_b32_e32 v97, v0
	v_mov_b32_e32 v34, v0
	v_mov_b32_e32 v35, v0
	v_mov_b32_e32 v36, v0
	v_mov_b32_e32 v37, v0
	v_mov_b32_e32 v38, v0
	v_mov_b32_e32 v39, v0
	v_mov_b32_e32 v40, v0
	v_mov_b32_e32 v41, v0
	v_mov_b32_e32 v42, v0
	v_mov_b32_e32 v43, v0
	v_mov_b32_e32 v44, v0
	v_mov_b32_e32 v45, v0
	v_mov_b32_e32 v46, v0
	v_mov_b32_e32 v47, v0
	v_mov_b32_e32 v48, v0
	v_mov_b32_e32 v49, v0
	v_mov_b32_e32 v50, v0
	v_mov_b32_e32 v51, v0
	v_mov_b32_e32 v52, v0
	v_mov_b32_e32 v53, v0
	v_mov_b32_e32 v54, v0
	v_mov_b32_e32 v55, v0
	v_mov_b32_e32 v56, v0
	v_mov_b32_e32 v57, v0
	v_mov_b32_e32 v58, v0
	v_mov_b32_e32 v59, v0
	v_mov_b32_e32 v60, v0
	v_mov_b32_e32 v61, v0
	v_mov_b32_e32 v66, v0
	v_mov_b32_e32 v67, v0
	v_mov_b32_e32 v68, v0
	v_mov_b32_e32 v69, v0
	v_mov_b32_e32 v98, v0
	v_mov_b32_e32 v99, v0
	v_mov_b32_e32 v100, v0
	v_mov_b32_e32 v101, v0
	v_mov_b32_e32 v102, v0
	v_mov_b32_e32 v103, v0
	v_mov_b32_e32 v104, v0
	v_mov_b32_e32 v105, v0
	v_mov_b32_e32 v106, v0
	v_mov_b32_e32 v107, v0
	v_mov_b32_e32 v108, v0
	v_mov_b32_e32 v109, v0
	v_mov_b32_e32 v110, v0
	v_mov_b32_e32 v111, v0
	v_mov_b32_e32 v112, v0
	v_mov_b32_e32 v113, v0
	v_mov_b32_e32 v114, v0
	v_mov_b32_e32 v115, v0
	v_mov_b32_e32 v116, v0
	v_mov_b32_e32 v117, v0
	v_mov_b32_e32 v118, v0
	v_mov_b32_e32 v119, v0
	v_mov_b32_e32 v120, v0
	v_mov_b32_e32 v121, v0
	v_mov_b32_e32 v122, v0
	v_mov_b32_e32 v123, v0
	v_mov_b32_e32 v124, v0
	v_mov_b32_e32 v125, v0
	v_mov_b32_e32 v126, v0
	v_mov_b32_e32 v127, v0
	v_mov_b32_e32 v128, v0
	v_mov_b32_e32 v129, v0
	s_cmp_eq_u32 s37, 1
	s_cbranch_scc1 .LBB0_228
	s_add_u32 s0, s22, 0xfffc0080
	s_addc_u32 s1, s23, -1
	s_add_i32 s3, 0, 0x10000
	s_cmp_eq_u32 s24, 12
	s_cselect_b32 s15, s49, s1
	s_cselect_b32 s14, s48, s0
	v_add_u32_e32 v162, s3, v149
	s_cselect_b32 s1, s2, s10
	s_cselect_b32 s0, s8, s9
	s_add_i32 s6, 0, 0x14000
	ds_read_b128 v[140:143], v162
	ds_read_b128 v[144:147], v162 offset:1024
	ds_read_b128 v[172:175], v162 offset:2048
	ds_read_b128 v[190:193], v162 offset:3072
	v_add_u32_e32 v162, s6, v149
	ds_read_b128 v[194:197], v162
	ds_read_b128 v[198:201], v162 offset:1024
	ds_read_b128 v[202:205], v162 offset:2048
	ds_read_b128 v[206:209], v162 offset:3072
	s_add_i32 m0, s27, 0xc000
	ds_read_b128 v[210:213], v151
	ds_read_b128 v[214:217], v151 offset:1024
	ds_read_b128 v[218:221], v151 offset:2048
	ds_read_b128 v[222:225], v151 offset:3072
	ds_read_b128 v[226:229], v151 offset:4096
	ds_read_b128 v[230:233], v151 offset:5120
	ds_read_b128 v[234:237], v151 offset:6144
	ds_read_b128 v[238:241], v151 offset:7168
	global_load_lds_dwordx4 v136, s[22:23]
	s_add_i32 m0, s27, 0xe000
	s_nop 0
	global_load_lds_dwordx4 v138, s[22:23]
	s_waitcnt vmcnt(24) lgkmcnt(0)
	s_barrier
	v_mfma_f32_16x16x32_bf16 v[126:129], v[140:143], v[210:213], v[126:129]
	v_mfma_f32_16x16x32_bf16 v[122:125], v[172:175], v[210:213], v[122:125]
	v_mfma_f32_16x16x32_bf16 v[118:121], v[140:143], v[218:221], v[118:121]
	v_mfma_f32_16x16x32_bf16 v[114:117], v[172:175], v[218:221], v[114:117]
	v_mfma_f32_16x16x32_bf16 v[110:113], v[140:143], v[226:229], v[110:113]
	v_mfma_f32_16x16x32_bf16 v[106:109], v[172:175], v[226:229], v[106:109]
	v_mfma_f32_16x16x32_bf16 v[102:105], v[140:143], v[234:237], v[102:105]
	v_mfma_f32_16x16x32_bf16 v[98:101], v[172:175], v[234:237], v[98:101]
	v_mfma_f32_16x16x32_bf16 v[126:129], v[144:147], v[214:217], v[126:129]
	v_mfma_f32_16x16x32_bf16 v[122:125], v[190:193], v[214:217], v[122:125]
	v_mfma_f32_16x16x32_bf16 v[118:121], v[144:147], v[222:225], v[118:121]
	v_mfma_f32_16x16x32_bf16 v[114:117], v[190:193], v[222:225], v[114:117]
	v_mfma_f32_16x16x32_bf16 v[110:113], v[144:147], v[230:233], v[110:113]
	v_mfma_f32_16x16x32_bf16 v[106:109], v[190:193], v[230:233], v[106:109]
	v_mfma_f32_16x16x32_bf16 v[102:105], v[144:147], v[238:241], v[102:105]
	v_mfma_f32_16x16x32_bf16 v[98:101], v[190:193], v[238:241], v[98:101]
	v_mfma_f32_16x16x32_bf16 v[66:69], v[194:197], v[210:213], v[66:69]
	v_mfma_f32_16x16x32_bf16 v[58:61], v[202:205], v[210:213], v[58:61]
	v_mfma_f32_16x16x32_bf16 v[54:57], v[194:197], v[218:221], v[54:57]
	v_mfma_f32_16x16x32_bf16 v[50:53], v[202:205], v[218:221], v[50:53]
	v_mfma_f32_16x16x32_bf16 v[46:49], v[194:197], v[226:229], v[46:49]
	v_mfma_f32_16x16x32_bf16 v[42:45], v[202:205], v[226:229], v[42:45]
	v_mfma_f32_16x16x32_bf16 v[38:41], v[194:197], v[234:237], v[38:41]
	v_mfma_f32_16x16x32_bf16 v[34:37], v[202:205], v[234:237], v[34:37]
	v_mfma_f32_16x16x32_bf16 v[66:69], v[198:201], v[214:217], v[66:69]
	v_mfma_f32_16x16x32_bf16 v[58:61], v[206:209], v[214:217], v[58:61]
	v_mfma_f32_16x16x32_bf16 v[54:57], v[198:201], v[222:225], v[54:57]
	v_mfma_f32_16x16x32_bf16 v[50:53], v[206:209], v[222:225], v[50:53]
	v_mfma_f32_16x16x32_bf16 v[46:49], v[198:201], v[230:233], v[46:49]
	v_mfma_f32_16x16x32_bf16 v[42:45], v[206:209], v[230:233], v[42:45]
	v_mfma_f32_16x16x32_bf16 v[38:41], v[198:201], v[238:241], v[38:41]
	v_mfma_f32_16x16x32_bf16 v[34:37], v[206:209], v[238:241], v[34:37]
	s_barrier
	s_add_i32 s3, s3, s26
	v_lshl_add_u64 v[162:163], s[0:1], 0, v[4:5]
	s_mov_b32 m0, s3
	ds_read_b128 v[210:213], v151 offset:16384
	ds_read_b128 v[214:217], v151 offset:17408
	ds_read_b128 v[218:221], v151 offset:18432
	ds_read_b128 v[222:225], v151 offset:19456
	ds_read_b128 v[226:229], v151 offset:20480
	ds_read_b128 v[230:233], v151 offset:21504
	ds_read_b128 v[234:237], v151 offset:22528
	ds_read_b128 v[238:241], v151 offset:23552
	global_load_lds_dwordx4 v4, s[0:1]
	s_add_i32 m0, s3, 0x2000
	s_add_u32 s4, s0, 0x40000
	v_lshl_add_u64 v[166:167], s[0:1], 0, v[134:135]
	s_addc_u32 s5, s1, 0
	s_add_i32 s3, s6, s26
	global_load_lds_dwordx4 v134, s[0:1]
	s_mov_b32 m0, s3
	v_lshl_add_u64 v[180:181], s[14:15], 0, v[132:133]
	global_load_lds_dwordx4 v4, s[4:5]
	s_add_i32 m0, s3, 0x2000
	s_nop 0
	global_load_lds_dwordx4 v134, s[4:5]
	v_lshl_add_u64 v[176:177], s[14:15], 0, v[130:131]
	s_mov_b32 m0, s27
	s_nop 0
	global_load_lds_dwordx4 v130, s[14:15]
	s_mov_b32 m0, s30
	s_nop 0
	global_load_lds_dwordx4 v132, s[14:15]
	s_waitcnt vmcnt(24) lgkmcnt(0)
	s_barrier
	v_mfma_f32_16x16x32_bf16 v[94:97], v[140:143], v[210:213], v[94:97]
	v_mfma_f32_16x16x32_bf16 v[90:93], v[172:175], v[210:213], v[90:93]
	v_mfma_f32_16x16x32_bf16 v[86:89], v[140:143], v[218:221], v[86:89]
	v_mfma_f32_16x16x32_bf16 v[82:85], v[172:175], v[218:221], v[82:85]
	v_mfma_f32_16x16x32_bf16 v[78:81], v[140:143], v[226:229], v[78:81]
	v_mfma_f32_16x16x32_bf16 v[74:77], v[172:175], v[226:229], v[74:77]
	v_mfma_f32_16x16x32_bf16 v[70:73], v[140:143], v[234:237], v[70:73]
	v_mfma_f32_16x16x32_bf16 v[62:65], v[172:175], v[234:237], v[62:65]
	v_mfma_f32_16x16x32_bf16 v[94:97], v[144:147], v[214:217], v[94:97]
	v_mfma_f32_16x16x32_bf16 v[90:93], v[190:193], v[214:217], v[90:93]
	v_mfma_f32_16x16x32_bf16 v[86:89], v[144:147], v[222:225], v[86:89]
	v_mfma_f32_16x16x32_bf16 v[82:85], v[190:193], v[222:225], v[82:85]
	v_mfma_f32_16x16x32_bf16 v[78:81], v[144:147], v[230:233], v[78:81]
	v_mfma_f32_16x16x32_bf16 v[74:77], v[190:193], v[230:233], v[74:77]
	v_mfma_f32_16x16x32_bf16 v[70:73], v[144:147], v[238:241], v[70:73]
	v_mfma_f32_16x16x32_bf16 v[62:65], v[190:193], v[238:241], v[62:65]
	v_mfma_f32_16x16x32_bf16 v[30:33], v[194:197], v[210:213], v[30:33]
	v_mfma_f32_16x16x32_bf16 v[26:29], v[202:205], v[210:213], v[26:29]
	v_mfma_f32_16x16x32_bf16 v[22:25], v[194:197], v[218:221], v[22:25]
	v_mfma_f32_16x16x32_bf16 v[18:21], v[202:205], v[218:221], v[18:21]
	v_mfma_f32_16x16x32_bf16 v[14:17], v[194:197], v[226:229], v[14:17]
	v_mfma_f32_16x16x32_bf16 v[10:13], v[202:205], v[226:229], v[10:13]
	v_mfma_f32_16x16x32_bf16 v[6:9], v[194:197], v[234:237], v[6:9]
	v_mfma_f32_16x16x32_bf16 v[0:3], v[202:205], v[234:237], v[0:3]
	v_mfma_f32_16x16x32_bf16 v[30:33], v[198:201], v[214:217], v[30:33]
	v_mfma_f32_16x16x32_bf16 v[26:29], v[206:209], v[214:217], v[26:29]
	v_mfma_f32_16x16x32_bf16 v[22:25], v[198:201], v[222:225], v[22:25]
	v_mfma_f32_16x16x32_bf16 v[18:21], v[206:209], v[222:225], v[18:21]
	v_mfma_f32_16x16x32_bf16 v[14:17], v[198:201], v[230:233], v[14:17]
	v_mfma_f32_16x16x32_bf16 v[10:13], v[206:209], v[230:233], v[10:13]
	v_mfma_f32_16x16x32_bf16 v[6:9], v[198:201], v[238:241], v[6:9]
	v_mfma_f32_16x16x32_bf16 v[0:3], v[206:209], v[238:241], v[0:3]
	s_barrier
	s_branch .Lpeelmid_228
.LBB0_228:
	s_add_u32 s0, s22, 0xfffc0080
	s_addc_u32 s1, s23, -1
	s_add_i32 s3, 0, 0x10000
	s_cmp_eq_u32 s24, 12
	s_cselect_b32 s15, s49, s1
	s_cselect_b32 s14, s48, s0
	v_add_u32_e32 v162, s3, v149
	s_cselect_b32 s1, s2, s10
	s_cselect_b32 s0, s8, s9
	s_add_i32 s6, 0, 0x14000
	ds_read_b128 v[140:143], v162
	ds_read_b128 v[144:147], v162 offset:1024
	ds_read_b128 v[172:175], v162 offset:2048
	ds_read_b128 v[190:193], v162 offset:3072
	v_add_u32_e32 v162, s6, v149
	ds_read_b128 v[194:197], v162
	ds_read_b128 v[198:201], v162 offset:1024
	ds_read_b128 v[202:205], v162 offset:2048
	ds_read_b128 v[206:209], v162 offset:3072
	s_add_i32 m0, s27, 0xc000
	ds_read_b128 v[210:213], v151
	ds_read_b128 v[214:217], v151 offset:1024
	ds_read_b128 v[218:221], v151 offset:2048
	ds_read_b128 v[222:225], v151 offset:3072
	ds_read_b128 v[226:229], v151 offset:4096
	ds_read_b128 v[230:233], v151 offset:5120
	ds_read_b128 v[234:237], v151 offset:6144
	ds_read_b128 v[238:241], v151 offset:7168
	global_load_lds_dwordx4 v136, s[22:23]
	s_add_i32 m0, s27, 0xe000
	s_nop 0
	global_load_lds_dwordx4 v138, s[22:23]
	s_waitcnt vmcnt(8) lgkmcnt(0)
	s_barrier
	v_mfma_f32_16x16x32_bf16 v[126:129], v[140:143], v[210:213], v[126:129]
	v_mfma_f32_16x16x32_bf16 v[122:125], v[172:175], v[210:213], v[122:125]
	v_mfma_f32_16x16x32_bf16 v[118:121], v[140:143], v[218:221], v[118:121]
	v_mfma_f32_16x16x32_bf16 v[114:117], v[172:175], v[218:221], v[114:117]
	v_mfma_f32_16x16x32_bf16 v[110:113], v[140:143], v[226:229], v[110:113]
	v_mfma_f32_16x16x32_bf16 v[106:109], v[172:175], v[226:229], v[106:109]
	v_mfma_f32_16x16x32_bf16 v[102:105], v[140:143], v[234:237], v[102:105]
	v_mfma_f32_16x16x32_bf16 v[98:101], v[172:175], v[234:237], v[98:101]
	v_mfma_f32_16x16x32_bf16 v[126:129], v[144:147], v[214:217], v[126:129]
	v_mfma_f32_16x16x32_bf16 v[122:125], v[190:193], v[214:217], v[122:125]
	v_mfma_f32_16x16x32_bf16 v[118:121], v[144:147], v[222:225], v[118:121]
	v_mfma_f32_16x16x32_bf16 v[114:117], v[190:193], v[222:225], v[114:117]
	v_mfma_f32_16x16x32_bf16 v[110:113], v[144:147], v[230:233], v[110:113]
	v_mfma_f32_16x16x32_bf16 v[106:109], v[190:193], v[230:233], v[106:109]
	v_mfma_f32_16x16x32_bf16 v[102:105], v[144:147], v[238:241], v[102:105]
	v_mfma_f32_16x16x32_bf16 v[98:101], v[190:193], v[238:241], v[98:101]
	v_mfma_f32_16x16x32_bf16 v[66:69], v[194:197], v[210:213], v[66:69]
	v_mfma_f32_16x16x32_bf16 v[58:61], v[202:205], v[210:213], v[58:61]
	v_mfma_f32_16x16x32_bf16 v[54:57], v[194:197], v[218:221], v[54:57]
	v_mfma_f32_16x16x32_bf16 v[50:53], v[202:205], v[218:221], v[50:53]
	v_mfma_f32_16x16x32_bf16 v[46:49], v[194:197], v[226:229], v[46:49]
	v_mfma_f32_16x16x32_bf16 v[42:45], v[202:205], v[226:229], v[42:45]
	v_mfma_f32_16x16x32_bf16 v[38:41], v[194:197], v[234:237], v[38:41]
	v_mfma_f32_16x16x32_bf16 v[34:37], v[202:205], v[234:237], v[34:37]
	v_mfma_f32_16x16x32_bf16 v[66:69], v[198:201], v[214:217], v[66:69]
	v_mfma_f32_16x16x32_bf16 v[58:61], v[206:209], v[214:217], v[58:61]
	v_mfma_f32_16x16x32_bf16 v[54:57], v[198:201], v[222:225], v[54:57]
	v_mfma_f32_16x16x32_bf16 v[50:53], v[206:209], v[222:225], v[50:53]
	v_mfma_f32_16x16x32_bf16 v[46:49], v[198:201], v[230:233], v[46:49]
	v_mfma_f32_16x16x32_bf16 v[42:45], v[206:209], v[230:233], v[42:45]
	v_mfma_f32_16x16x32_bf16 v[38:41], v[198:201], v[238:241], v[38:41]
	v_mfma_f32_16x16x32_bf16 v[34:37], v[206:209], v[238:241], v[34:37]
	s_barrier
	s_add_i32 s3, s3, s26
	v_lshl_add_u64 v[162:163], s[0:1], 0, v[4:5]
	s_mov_b32 m0, s3
	ds_read_b128 v[210:213], v151 offset:16384
	ds_read_b128 v[214:217], v151 offset:17408
	ds_read_b128 v[218:221], v151 offset:18432
	ds_read_b128 v[222:225], v151 offset:19456
	ds_read_b128 v[226:229], v151 offset:20480
	ds_read_b128 v[230:233], v151 offset:21504
	ds_read_b128 v[234:237], v151 offset:22528
	ds_read_b128 v[238:241], v151 offset:23552
	global_load_lds_dwordx4 v4, s[0:1]
	s_add_i32 m0, s3, 0x2000
	s_add_u32 s4, s0, 0x40000
	v_lshl_add_u64 v[166:167], s[0:1], 0, v[134:135]
	s_addc_u32 s5, s1, 0
	s_add_i32 s3, s6, s26
	global_load_lds_dwordx4 v134, s[0:1]
	s_mov_b32 m0, s3
	v_lshl_add_u64 v[180:181], s[14:15], 0, v[132:133]
	global_load_lds_dwordx4 v4, s[4:5]
	s_add_i32 m0, s3, 0x2000
	s_nop 0
	global_load_lds_dwordx4 v134, s[4:5]
	v_lshl_add_u64 v[176:177], s[14:15], 0, v[130:131]
	s_mov_b32 m0, s27
	s_nop 0
	global_load_lds_dwordx4 v130, s[14:15]
	s_mov_b32 m0, s30
	s_nop 0
	global_load_lds_dwordx4 v132, s[14:15]
	s_waitcnt vmcnt(8) lgkmcnt(0)
	s_barrier
	v_mfma_f32_16x16x32_bf16 v[94:97], v[140:143], v[210:213], v[94:97]
	v_mfma_f32_16x16x32_bf16 v[90:93], v[172:175], v[210:213], v[90:93]
	v_mfma_f32_16x16x32_bf16 v[86:89], v[140:143], v[218:221], v[86:89]
	v_mfma_f32_16x16x32_bf16 v[82:85], v[172:175], v[218:221], v[82:85]
	v_mfma_f32_16x16x32_bf16 v[78:81], v[140:143], v[226:229], v[78:81]
	v_mfma_f32_16x16x32_bf16 v[74:77], v[172:175], v[226:229], v[74:77]
	v_mfma_f32_16x16x32_bf16 v[70:73], v[140:143], v[234:237], v[70:73]
	v_mfma_f32_16x16x32_bf16 v[62:65], v[172:175], v[234:237], v[62:65]
	v_mfma_f32_16x16x32_bf16 v[94:97], v[144:147], v[214:217], v[94:97]
	v_mfma_f32_16x16x32_bf16 v[90:93], v[190:193], v[214:217], v[90:93]
	v_mfma_f32_16x16x32_bf16 v[86:89], v[144:147], v[222:225], v[86:89]
	v_mfma_f32_16x16x32_bf16 v[82:85], v[190:193], v[222:225], v[82:85]
	v_mfma_f32_16x16x32_bf16 v[78:81], v[144:147], v[230:233], v[78:81]
	v_mfma_f32_16x16x32_bf16 v[74:77], v[190:193], v[230:233], v[74:77]
	v_mfma_f32_16x16x32_bf16 v[70:73], v[144:147], v[238:241], v[70:73]
	v_mfma_f32_16x16x32_bf16 v[62:65], v[190:193], v[238:241], v[62:65]
	v_mfma_f32_16x16x32_bf16 v[30:33], v[194:197], v[210:213], v[30:33]
	v_mfma_f32_16x16x32_bf16 v[26:29], v[202:205], v[210:213], v[26:29]
	v_mfma_f32_16x16x32_bf16 v[22:25], v[194:197], v[218:221], v[22:25]
	v_mfma_f32_16x16x32_bf16 v[18:21], v[202:205], v[218:221], v[18:21]
	v_mfma_f32_16x16x32_bf16 v[14:17], v[194:197], v[226:229], v[14:17]
	v_mfma_f32_16x16x32_bf16 v[10:13], v[202:205], v[226:229], v[10:13]
	v_mfma_f32_16x16x32_bf16 v[6:9], v[194:197], v[234:237], v[6:9]
	v_mfma_f32_16x16x32_bf16 v[0:3], v[202:205], v[234:237], v[0:3]
	v_mfma_f32_16x16x32_bf16 v[30:33], v[198:201], v[214:217], v[30:33]
	v_mfma_f32_16x16x32_bf16 v[26:29], v[206:209], v[214:217], v[26:29]
	v_mfma_f32_16x16x32_bf16 v[22:25], v[198:201], v[222:225], v[22:25]
	v_mfma_f32_16x16x32_bf16 v[18:21], v[206:209], v[222:225], v[18:21]
	v_mfma_f32_16x16x32_bf16 v[14:17], v[198:201], v[230:233], v[14:17]
	v_mfma_f32_16x16x32_bf16 v[10:13], v[206:209], v[230:233], v[10:13]
	v_mfma_f32_16x16x32_bf16 v[6:9], v[198:201], v[238:241], v[6:9]
	v_mfma_f32_16x16x32_bf16 v[0:3], v[206:209], v[238:241], v[0:3]
	s_barrier
.Lpeelmid_228:
	s_add_i32 s3, 0, 0x18000
	v_add_u32_e32 v164, s3, v149
	s_add_i32 s6, 0, 0x1c000
	ds_read_b128 v[140:143], v164
	ds_read_b128 v[144:147], v164 offset:1024
	ds_read_b128 v[172:175], v164 offset:2048
	ds_read_b128 v[190:193], v164 offset:3072
	v_add_u32_e32 v164, s6, v149
	ds_read_b128 v[194:197], v164
	ds_read_b128 v[198:201], v164 offset:1024
	ds_read_b128 v[202:205], v164 offset:2048
	ds_read_b128 v[206:209], v164 offset:3072
	s_add_u32 s4, s14, 0x40000
	s_addc_u32 s5, s15, 0
	s_mov_b32 m0, s31
	ds_read_b128 v[210:213], v151 offset:32768
	ds_read_b128 v[214:217], v151 offset:33792
	ds_read_b128 v[218:221], v151 offset:34816
	ds_read_b128 v[222:225], v151 offset:35840
	ds_read_b128 v[226:229], v151 offset:36864
	ds_read_b128 v[230:233], v151 offset:37888
	ds_read_b128 v[234:237], v151 offset:38912
	ds_read_b128 v[238:241], v151 offset:39936
	global_load_lds_dwordx4 v130, s[4:5]
	v_lshl_add_u64 v[242:243], s[4:5], 0, v[132:133]
	s_mov_b32 m0, s34
	s_nop 0
	global_load_lds_dwordx4 v132, s[4:5]
	s_waitcnt vmcnt(8) lgkmcnt(0)
	s_barrier
	v_mfma_f32_16x16x32_bf16 v[126:129], v[140:143], v[210:213], v[126:129]
	v_mfma_f32_16x16x32_bf16 v[122:125], v[172:175], v[210:213], v[122:125]
	v_mfma_f32_16x16x32_bf16 v[118:121], v[140:143], v[218:221], v[118:121]
	v_mfma_f32_16x16x32_bf16 v[114:117], v[172:175], v[218:221], v[114:117]
	v_mfma_f32_16x16x32_bf16 v[110:113], v[140:143], v[226:229], v[110:113]
	v_mfma_f32_16x16x32_bf16 v[106:109], v[172:175], v[226:229], v[106:109]
	v_mfma_f32_16x16x32_bf16 v[102:105], v[140:143], v[234:237], v[102:105]
	v_mfma_f32_16x16x32_bf16 v[98:101], v[172:175], v[234:237], v[98:101]
	v_mfma_f32_16x16x32_bf16 v[126:129], v[144:147], v[214:217], v[126:129]
	v_mfma_f32_16x16x32_bf16 v[122:125], v[190:193], v[214:217], v[122:125]
	v_mfma_f32_16x16x32_bf16 v[118:121], v[144:147], v[222:225], v[118:121]
	v_mfma_f32_16x16x32_bf16 v[114:117], v[190:193], v[222:225], v[114:117]
	v_mfma_f32_16x16x32_bf16 v[110:113], v[144:147], v[230:233], v[110:113]
	v_mfma_f32_16x16x32_bf16 v[106:109], v[190:193], v[230:233], v[106:109]
	v_mfma_f32_16x16x32_bf16 v[102:105], v[144:147], v[238:241], v[102:105]
	v_mfma_f32_16x16x32_bf16 v[98:101], v[190:193], v[238:241], v[98:101]
	v_mfma_f32_16x16x32_bf16 v[66:69], v[194:197], v[210:213], v[66:69]
	v_mfma_f32_16x16x32_bf16 v[58:61], v[202:205], v[210:213], v[58:61]
	v_mfma_f32_16x16x32_bf16 v[54:57], v[194:197], v[218:221], v[54:57]
	v_mfma_f32_16x16x32_bf16 v[50:53], v[202:205], v[218:221], v[50:53]
	v_mfma_f32_16x16x32_bf16 v[46:49], v[194:197], v[226:229], v[46:49]
	v_mfma_f32_16x16x32_bf16 v[42:45], v[202:205], v[226:229], v[42:45]
	v_mfma_f32_16x16x32_bf16 v[38:41], v[194:197], v[234:237], v[38:41]
	v_mfma_f32_16x16x32_bf16 v[34:37], v[202:205], v[234:237], v[34:37]
	v_mfma_f32_16x16x32_bf16 v[66:69], v[198:201], v[214:217], v[66:69]
	v_mfma_f32_16x16x32_bf16 v[58:61], v[206:209], v[214:217], v[58:61]
	v_mfma_f32_16x16x32_bf16 v[54:57], v[198:201], v[222:225], v[54:57]
	v_mfma_f32_16x16x32_bf16 v[50:53], v[206:209], v[222:225], v[50:53]
	v_mfma_f32_16x16x32_bf16 v[46:49], v[198:201], v[230:233], v[46:49]
	v_mfma_f32_16x16x32_bf16 v[42:45], v[206:209], v[230:233], v[42:45]
	v_mfma_f32_16x16x32_bf16 v[38:41], v[198:201], v[238:241], v[38:41]
	v_mfma_f32_16x16x32_bf16 v[34:37], v[206:209], v[238:241], v[34:37]
	s_barrier
	s_add_i32 s3, s3, s26
	v_lshl_add_u64 v[162:163], v[162:163], 0, s[70:71]
	s_mov_b32 m0, s3
	ds_read_b128 v[210:213], v151 offset:49152
	ds_read_b128 v[214:217], v151 offset:50176
	ds_read_b128 v[218:221], v151 offset:51200
	ds_read_b128 v[222:225], v151 offset:52224
	ds_read_b128 v[226:229], v151 offset:53248
	ds_read_b128 v[230:233], v151 offset:54272
	ds_read_b128 v[234:237], v151 offset:55296
	ds_read_b128 v[238:241], v151 offset:56320
	global_load_lds_dwordx4 v[162:163], off
	s_add_i32 m0, s3, 0x2000
	s_add_u32 s0, s0, 0x40080
	v_lshl_add_u64 v[162:163], v[166:167], 0, s[70:71]
	s_addc_u32 s1, s1, 0
	s_add_i32 s3, s6, s26
	global_load_lds_dwordx4 v[162:163], off
	s_mov_b32 m0, s3
	s_nop 0
	global_load_lds_dwordx4 v4, s[0:1]
	s_add_i32 m0, s3, 0x2000
	s_nop 0
	global_load_lds_dwordx4 v134, s[0:1]
	v_lshl_add_u64 v[162:163], v[176:177], 0, s[70:71]
	s_mov_b32 m0, s35
	s_nop 0
	global_load_lds_dwordx4 v[162:163], off
	v_lshl_add_u64 v[162:163], v[180:181], 0, s[70:71]
	s_mov_b32 m0, s36
	s_nop 0
	global_load_lds_dwordx4 v[162:163], off
	s_waitcnt vmcnt(8) lgkmcnt(0)
	s_barrier
	v_mfma_f32_16x16x32_bf16 v[94:97], v[140:143], v[210:213], v[94:97]
	v_mfma_f32_16x16x32_bf16 v[90:93], v[172:175], v[210:213], v[90:93]
	v_mfma_f32_16x16x32_bf16 v[86:89], v[140:143], v[218:221], v[86:89]
	v_mfma_f32_16x16x32_bf16 v[82:85], v[172:175], v[218:221], v[82:85]
	v_mfma_f32_16x16x32_bf16 v[78:81], v[140:143], v[226:229], v[78:81]
	v_mfma_f32_16x16x32_bf16 v[74:77], v[172:175], v[226:229], v[74:77]
	v_mfma_f32_16x16x32_bf16 v[70:73], v[140:143], v[234:237], v[70:73]
	v_mfma_f32_16x16x32_bf16 v[62:65], v[172:175], v[234:237], v[62:65]
	v_mfma_f32_16x16x32_bf16 v[94:97], v[144:147], v[214:217], v[94:97]
	v_mfma_f32_16x16x32_bf16 v[90:93], v[190:193], v[214:217], v[90:93]
	v_mfma_f32_16x16x32_bf16 v[86:89], v[144:147], v[222:225], v[86:89]
	v_mfma_f32_16x16x32_bf16 v[82:85], v[190:193], v[222:225], v[82:85]
	v_mfma_f32_16x16x32_bf16 v[78:81], v[144:147], v[230:233], v[78:81]
	v_mfma_f32_16x16x32_bf16 v[74:77], v[190:193], v[230:233], v[74:77]
	v_mfma_f32_16x16x32_bf16 v[70:73], v[144:147], v[238:241], v[70:73]
	v_mfma_f32_16x16x32_bf16 v[62:65], v[190:193], v[238:241], v[62:65]
	v_mfma_f32_16x16x32_bf16 v[30:33], v[194:197], v[210:213], v[30:33]
	v_mfma_f32_16x16x32_bf16 v[26:29], v[202:205], v[210:213], v[26:29]
	v_mfma_f32_16x16x32_bf16 v[22:25], v[194:197], v[218:221], v[22:25]
	v_mfma_f32_16x16x32_bf16 v[18:21], v[202:205], v[218:221], v[18:21]
	v_mfma_f32_16x16x32_bf16 v[14:17], v[194:197], v[226:229], v[14:17]
	v_mfma_f32_16x16x32_bf16 v[10:13], v[202:205], v[226:229], v[10:13]
	v_mfma_f32_16x16x32_bf16 v[6:9], v[194:197], v[234:237], v[6:9]
	v_mfma_f32_16x16x32_bf16 v[0:3], v[202:205], v[234:237], v[0:3]
	v_mfma_f32_16x16x32_bf16 v[30:33], v[198:201], v[214:217], v[30:33]
	v_mfma_f32_16x16x32_bf16 v[26:29], v[206:209], v[214:217], v[26:29]
	v_mfma_f32_16x16x32_bf16 v[22:25], v[198:201], v[222:225], v[22:25]
	v_mfma_f32_16x16x32_bf16 v[18:21], v[206:209], v[222:225], v[18:21]
	v_mfma_f32_16x16x32_bf16 v[14:17], v[198:201], v[230:233], v[14:17]
	v_mfma_f32_16x16x32_bf16 v[10:13], v[206:209], v[230:233], v[10:13]
	v_mfma_f32_16x16x32_bf16 v[6:9], v[198:201], v[238:241], v[6:9]
	v_mfma_f32_16x16x32_bf16 v[0:3], v[206:209], v[238:241], v[0:3]
	s_barrier
	s_add_i32 s24, s24, 2
	s_add_u32 s22, s22, 0x100
	s_addc_u32 s23, s23, 0
	s_add_u32 s9, s9, 0x100
	s_addc_u32 s10, s10, 0
	s_cmp_gt_u32 s24, 13
	s_cbranch_scc0 .LBB0_228
	s_and_b64 vcc, exec, s[44:45]
	s_cbranch_vccz .LBB0_231
	s_barrier

.LBB0_251:
	s_ashr_i32 s47, s46, 31
	s_lshl_b64 s[2:3], s[46:47], 20
	v_readlane_b32 s4, v253, 36
	s_add_u32 s82, s4, s2
	v_readlane_b32 s2, v253, 37
	s_addc_u32 s83, s2, s3
	s_and_b64 s[2:3], s[40:41], exec
	s_cselect_b32 s2, s83, s15
	s_cselect_b32 s8, s82, s14
	s_add_u32 s22, s0, 0x80080
	s_addc_u32 s23, s1, 0
	s_add_u32 s9, s14, 0x100
	v_mov_b32_e32 v0, 0
	s_addc_u32 s10, s15, 0
	s_mov_b32 s24, -2
	v_mov_b32_e32 v1, v0
	v_mov_b32_e32 v2, v0
	v_mov_b32_e32 v3, v0
	v_mov_b32_e32 v6, v0
	v_mov_b32_e32 v7, v0
	v_mov_b32_e32 v8, v0
	v_mov_b32_e32 v9, v0
	v_mov_b32_e32 v10, v0
	v_mov_b32_e32 v11, v0
	v_mov_b32_e32 v12, v0
	v_mov_b32_e32 v13, v0
	v_mov_b32_e32 v14, v0
	v_mov_b32_e32 v15, v0
	v_mov_b32_e32 v16, v0
	v_mov_b32_e32 v17, v0
	v_mov_b32_e32 v18, v0
	v_mov_b32_e32 v19, v0
	v_mov_b32_e32 v20, v0
	v_mov_b32_e32 v21, v0
	v_mov_b32_e32 v22, v0
	v_mov_b32_e32 v23, v0
	v_mov_b32_e32 v24, v0
	v_mov_b32_e32 v25, v0
	v_mov_b32_e32 v26, v0
	v_mov_b32_e32 v27, v0
	v_mov_b32_e32 v28, v0
	v_mov_b32_e32 v29, v0
	v_mov_b32_e32 v30, v0
	v_mov_b32_e32 v31, v0
	v_mov_b32_e32 v32, v0
	v_mov_b32_e32 v33, v0
	v_mov_b32_e32 v62, v0
	v_mov_b32_e32 v63, v0
	v_mov_b32_e32 v64, v0
	v_mov_b32_e32 v65, v0
	v_mov_b32_e32 v70, v0
	v_mov_b32_e32 v71, v0
	v_mov_b32_e32 v72, v0
	v_mov_b32_e32 v73, v0
	v_mov_b32_e32 v74, v0
	v_mov_b32_e32 v75, v0
	v_mov_b32_e32 v76, v0
	v_mov_b32_e32 v77, v0
	v_mov_b32_e32 v78, v0
	v_mov_b32_e32 v79, v0
	v_mov_b32_e32 v80, v0
	v_mov_b32_e32 v81, v0
	v_mov_b32_e32 v82, v0
	v_mov_b32_e32 v83, v0
	v_mov_b32_e32 v84, v0
	v_mov_b32_e32 v85, v0
	v_mov_b32_e32 v86, v0
	v_mov_b32_e32 v87, v0
	v_mov_b32_e32 v88, v0
	v_mov_b32_e32 v89, v0
	v_mov_b32_e32 v90, v0
	v_mov_b32_e32 v91, v0
	v_mov_b32_e32 v92, v0
	v_mov_b32_e32 v93, v0
	v_mov_b32_e32 v94, v0
	v_mov_b32_e32 v95, v0
	v_mov_b32_e32 v96, v0
	v_mov_b32_e32 v97, v0
	v_mov_b32_e32 v34, v0
	v_mov_b32_e32 v35, v0
	v_mov_b32_e32 v36, v0
	v_mov_b32_e32 v37, v0
	v_mov_b32_e32 v38, v0
	v_mov_b32_e32 v39, v0
	v_mov_b32_e32 v40, v0
	v_mov_b32_e32 v41, v0
	v_mov_b32_e32 v42, v0
	v_mov_b32_e32 v43, v0
	v_mov_b32_e32 v44, v0
	v_mov_b32_e32 v45, v0
	v_mov_b32_e32 v46, v0
	v_mov_b32_e32 v47, v0
	v_mov_b32_e32 v48, v0
	v_mov_b32_e32 v49, v0
	v_mov_b32_e32 v50, v0
	v_mov_b32_e32 v51, v0
	v_mov_b32_e32 v52, v0
	v_mov_b32_e32 v53, v0
	v_mov_b32_e32 v54, v0
	v_mov_b32_e32 v55, v0
	v_mov_b32_e32 v56, v0
	v_mov_b32_e32 v57, v0
	v_mov_b32_e32 v58, v0
	v_mov_b32_e32 v59, v0
	v_mov_b32_e32 v60, v0
	v_mov_b32_e32 v61, v0
	v_mov_b32_e32 v66, v0
	v_mov_b32_e32 v67, v0
	v_mov_b32_e32 v68, v0
	v_mov_b32_e32 v69, v0
	v_mov_b32_e32 v98, v0
	v_mov_b32_e32 v99, v0
	v_mov_b32_e32 v100, v0
	v_mov_b32_e32 v101, v0
	v_mov_b32_e32 v102, v0
	v_mov_b32_e32 v103, v0
	v_mov_b32_e32 v104, v0
	v_mov_b32_e32 v105, v0
	v_mov_b32_e32 v106, v0
	v_mov_b32_e32 v107, v0
	v_mov_b32_e32 v108, v0
	v_mov_b32_e32 v109, v0
	v_mov_b32_e32 v110, v0
	v_mov_b32_e32 v111, v0
	v_mov_b32_e32 v112, v0
	v_mov_b32_e32 v113, v0
	v_mov_b32_e32 v114, v0
	v_mov_b32_e32 v115, v0
	v_mov_b32_e32 v116, v0
	v_mov_b32_e32 v117, v0
	v_mov_b32_e32 v118, v0
	v_mov_b32_e32 v119, v0
	v_mov_b32_e32 v120, v0
	v_mov_b32_e32 v121, v0
	v_mov_b32_e32 v122, v0
	v_mov_b32_e32 v123, v0
	v_mov_b32_e32 v124, v0
	v_mov_b32_e32 v125, v0
	v_mov_b32_e32 v126, v0
	v_mov_b32_e32 v127, v0
	v_mov_b32_e32 v128, v0
	v_mov_b32_e32 v129, v0
	s_cmp_eq_u32 s37, 1
	s_cbranch_scc1 .LBB0_252
	s_add_u32 s0, s22, 0xfff80080
	s_addc_u32 s1, s23, -1
	s_add_i32 s3, 0, 0x10000
	s_cmp_eq_u32 s24, 28
	s_cselect_b32 s15, s49, s1
	s_cselect_b32 s14, s48, s0
	v_add_u32_e32 v162, s3, v141
	s_cselect_b32 s1, s2, s10
	s_cselect_b32 s0, s8, s9
	s_add_i32 s6, 0, 0x14000
	ds_read_b128 v[144:147], v162
	ds_read_b128 v[148:151], v162 offset:1024
	ds_read_b128 v[172:175], v162 offset:2048
	ds_read_b128 v[190:193], v162 offset:3072
	v_add_u32_e32 v162, s6, v141
	ds_read_b128 v[194:197], v162
	ds_read_b128 v[198:201], v162 offset:1024
	ds_read_b128 v[202:205], v162 offset:2048
	ds_read_b128 v[206:209], v162 offset:3072
	s_add_i32 m0, s27, 0xc000
	ds_read_b128 v[210:213], v143
	ds_read_b128 v[214:217], v143 offset:1024
	ds_read_b128 v[218:221], v143 offset:2048
	ds_read_b128 v[222:225], v143 offset:3072
	ds_read_b128 v[226:229], v143 offset:4096
	ds_read_b128 v[230:233], v143 offset:5120
	ds_read_b128 v[234:237], v143 offset:6144
	ds_read_b128 v[238:241], v143 offset:7168
	global_load_lds_dwordx4 v136, s[22:23]
	s_add_i32 m0, s27, 0xe000
	s_nop 0
	global_load_lds_dwordx4 v138, s[22:23]
	s_waitcnt vmcnt(24) lgkmcnt(0)
	s_barrier
	v_mfma_f32_16x16x32_bf16 v[126:129], v[144:147], v[210:213], v[126:129]
	v_mfma_f32_16x16x32_bf16 v[122:125], v[172:175], v[210:213], v[122:125]
	v_mfma_f32_16x16x32_bf16 v[118:121], v[144:147], v[218:221], v[118:121]
	v_mfma_f32_16x16x32_bf16 v[114:117], v[172:175], v[218:221], v[114:117]
	v_mfma_f32_16x16x32_bf16 v[110:113], v[144:147], v[226:229], v[110:113]
	v_mfma_f32_16x16x32_bf16 v[106:109], v[172:175], v[226:229], v[106:109]
	v_mfma_f32_16x16x32_bf16 v[102:105], v[144:147], v[234:237], v[102:105]
	v_mfma_f32_16x16x32_bf16 v[98:101], v[172:175], v[234:237], v[98:101]
	v_mfma_f32_16x16x32_bf16 v[126:129], v[148:151], v[214:217], v[126:129]
	v_mfma_f32_16x16x32_bf16 v[122:125], v[190:193], v[214:217], v[122:125]
	v_mfma_f32_16x16x32_bf16 v[118:121], v[148:151], v[222:225], v[118:121]
	v_mfma_f32_16x16x32_bf16 v[114:117], v[190:193], v[222:225], v[114:117]
	v_mfma_f32_16x16x32_bf16 v[110:113], v[148:151], v[230:233], v[110:113]
	v_mfma_f32_16x16x32_bf16 v[106:109], v[190:193], v[230:233], v[106:109]
	v_mfma_f32_16x16x32_bf16 v[102:105], v[148:151], v[238:241], v[102:105]
	v_mfma_f32_16x16x32_bf16 v[98:101], v[190:193], v[238:241], v[98:101]
	v_mfma_f32_16x16x32_bf16 v[66:69], v[194:197], v[210:213], v[66:69]
	v_mfma_f32_16x16x32_bf16 v[58:61], v[202:205], v[210:213], v[58:61]
	v_mfma_f32_16x16x32_bf16 v[54:57], v[194:197], v[218:221], v[54:57]
	v_mfma_f32_16x16x32_bf16 v[50:53], v[202:205], v[218:221], v[50:53]
	v_mfma_f32_16x16x32_bf16 v[46:49], v[194:197], v[226:229], v[46:49]
	v_mfma_f32_16x16x32_bf16 v[42:45], v[202:205], v[226:229], v[42:45]
	v_mfma_f32_16x16x32_bf16 v[38:41], v[194:197], v[234:237], v[38:41]
	v_mfma_f32_16x16x32_bf16 v[34:37], v[202:205], v[234:237], v[34:37]
	v_mfma_f32_16x16x32_bf16 v[66:69], v[198:201], v[214:217], v[66:69]
	v_mfma_f32_16x16x32_bf16 v[58:61], v[206:209], v[214:217], v[58:61]
	v_mfma_f32_16x16x32_bf16 v[54:57], v[198:201], v[222:225], v[54:57]
	v_mfma_f32_16x16x32_bf16 v[50:53], v[206:209], v[222:225], v[50:53]
	v_mfma_f32_16x16x32_bf16 v[46:49], v[198:201], v[230:233], v[46:49]
	v_mfma_f32_16x16x32_bf16 v[42:45], v[206:209], v[230:233], v[42:45]
	v_mfma_f32_16x16x32_bf16 v[38:41], v[198:201], v[238:241], v[38:41]
	v_mfma_f32_16x16x32_bf16 v[34:37], v[206:209], v[238:241], v[34:37]
	s_barrier
	s_add_i32 s3, s3, s26
	v_lshl_add_u64 v[162:163], s[0:1], 0, v[4:5]
	s_mov_b32 m0, s3
	ds_read_b128 v[210:213], v143 offset:16384
	ds_read_b128 v[214:217], v143 offset:17408
	ds_read_b128 v[218:221], v143 offset:18432
	ds_read_b128 v[222:225], v143 offset:19456
	ds_read_b128 v[226:229], v143 offset:20480
	ds_read_b128 v[230:233], v143 offset:21504
	ds_read_b128 v[234:237], v143 offset:22528
	ds_read_b128 v[238:241], v143 offset:23552
	global_load_lds_dwordx4 v4, s[0:1]
	s_add_i32 m0, s3, 0x2000
	s_add_u32 s4, s0, 0x80000
	v_lshl_add_u64 v[166:167], s[0:1], 0, v[130:131]
	s_addc_u32 s5, s1, 0
	s_add_i32 s3, s6, s26
	global_load_lds_dwordx4 v130, s[0:1]
	s_mov_b32 m0, s3
	v_lshl_add_u64 v[242:243], s[14:15], 0, v[132:133]
	global_load_lds_dwordx4 v4, s[4:5]
	s_add_i32 m0, s3, 0x2000
	s_nop 0
	global_load_lds_dwordx4 v130, s[4:5]
	v_lshl_add_u64 v[176:177], s[14:15], 0, v[134:135]
	s_mov_b32 m0, s27
	s_nop 0
	global_load_lds_dwordx4 v134, s[14:15]
	s_mov_b32 m0, s30
	s_nop 0
	global_load_lds_dwordx4 v132, s[14:15]
	s_waitcnt vmcnt(24) lgkmcnt(0)
	s_barrier
	v_mfma_f32_16x16x32_bf16 v[94:97], v[144:147], v[210:213], v[94:97]
	v_mfma_f32_16x16x32_bf16 v[90:93], v[172:175], v[210:213], v[90:93]
	v_mfma_f32_16x16x32_bf16 v[86:89], v[144:147], v[218:221], v[86:89]
	v_mfma_f32_16x16x32_bf16 v[82:85], v[172:175], v[218:221], v[82:85]
	v_mfma_f32_16x16x32_bf16 v[78:81], v[144:147], v[226:229], v[78:81]
	v_mfma_f32_16x16x32_bf16 v[74:77], v[172:175], v[226:229], v[74:77]
	v_mfma_f32_16x16x32_bf16 v[70:73], v[144:147], v[234:237], v[70:73]
	v_mfma_f32_16x16x32_bf16 v[62:65], v[172:175], v[234:237], v[62:65]
	v_mfma_f32_16x16x32_bf16 v[94:97], v[148:151], v[214:217], v[94:97]
	v_mfma_f32_16x16x32_bf16 v[90:93], v[190:193], v[214:217], v[90:93]
	v_mfma_f32_16x16x32_bf16 v[86:89], v[148:151], v[222:225], v[86:89]
	v_mfma_f32_16x16x32_bf16 v[82:85], v[190:193], v[222:225], v[82:85]
	v_mfma_f32_16x16x32_bf16 v[78:81], v[148:151], v[230:233], v[78:81]
	v_mfma_f32_16x16x32_bf16 v[74:77], v[190:193], v[230:233], v[74:77]
	v_mfma_f32_16x16x32_bf16 v[70:73], v[148:151], v[238:241], v[70:73]
	v_mfma_f32_16x16x32_bf16 v[62:65], v[190:193], v[238:241], v[62:65]
	v_mfma_f32_16x16x32_bf16 v[30:33], v[194:197], v[210:213], v[30:33]
	v_mfma_f32_16x16x32_bf16 v[26:29], v[202:205], v[210:213], v[26:29]
	v_mfma_f32_16x16x32_bf16 v[22:25], v[194:197], v[218:221], v[22:25]
	v_mfma_f32_16x16x32_bf16 v[18:21], v[202:205], v[218:221], v[18:21]
	v_mfma_f32_16x16x32_bf16 v[14:17], v[194:197], v[226:229], v[14:17]
	v_mfma_f32_16x16x32_bf16 v[10:13], v[202:205], v[226:229], v[10:13]
	v_mfma_f32_16x16x32_bf16 v[6:9], v[194:197], v[234:237], v[6:9]
	v_mfma_f32_16x16x32_bf16 v[0:3], v[202:205], v[234:237], v[0:3]
	v_mfma_f32_16x16x32_bf16 v[30:33], v[198:201], v[214:217], v[30:33]
	v_mfma_f32_16x16x32_bf16 v[26:29], v[206:209], v[214:217], v[26:29]
	v_mfma_f32_16x16x32_bf16 v[22:25], v[198:201], v[222:225], v[22:25]
	v_mfma_f32_16x16x32_bf16 v[18:21], v[206:209], v[222:225], v[18:21]
	v_mfma_f32_16x16x32_bf16 v[14:17], v[198:201], v[230:233], v[14:17]
	v_mfma_f32_16x16x32_bf16 v[10:13], v[206:209], v[230:233], v[10:13]
	v_mfma_f32_16x16x32_bf16 v[6:9], v[198:201], v[238:241], v[6:9]
	v_mfma_f32_16x16x32_bf16 v[0:3], v[206:209], v[238:241], v[0:3]
	s_barrier
	s_branch .Lpeelmid_252
.LBB0_252:
	s_add_u32 s0, s22, 0xfff80080
	s_addc_u32 s1, s23, -1
	s_add_i32 s3, 0, 0x10000
	s_cmp_eq_u32 s24, 28
	s_cselect_b32 s15, s49, s1
	s_cselect_b32 s14, s48, s0
	v_add_u32_e32 v162, s3, v141
	s_cselect_b32 s1, s2, s10
	s_cselect_b32 s0, s8, s9
	s_add_i32 s6, 0, 0x14000
	ds_read_b128 v[144:147], v162
	ds_read_b128 v[148:151], v162 offset:1024
	ds_read_b128 v[172:175], v162 offset:2048
	ds_read_b128 v[190:193], v162 offset:3072
	v_add_u32_e32 v162, s6, v141
	ds_read_b128 v[194:197], v162
	ds_read_b128 v[198:201], v162 offset:1024
	ds_read_b128 v[202:205], v162 offset:2048
	ds_read_b128 v[206:209], v162 offset:3072
	s_add_i32 m0, s27, 0xc000
	ds_read_b128 v[210:213], v143
	ds_read_b128 v[214:217], v143 offset:1024
	ds_read_b128 v[218:221], v143 offset:2048
	ds_read_b128 v[222:225], v143 offset:3072
	ds_read_b128 v[226:229], v143 offset:4096
	ds_read_b128 v[230:233], v143 offset:5120
	ds_read_b128 v[234:237], v143 offset:6144
	ds_read_b128 v[238:241], v143 offset:7168
	global_load_lds_dwordx4 v136, s[22:23]
	s_add_i32 m0, s27, 0xe000
	s_nop 0
	global_load_lds_dwordx4 v138, s[22:23]
	s_waitcnt vmcnt(8) lgkmcnt(0)
	s_barrier
	v_mfma_f32_16x16x32_bf16 v[126:129], v[144:147], v[210:213], v[126:129]
	v_mfma_f32_16x16x32_bf16 v[122:125], v[172:175], v[210:213], v[122:125]
	v_mfma_f32_16x16x32_bf16 v[118:121], v[144:147], v[218:221], v[118:121]
	v_mfma_f32_16x16x32_bf16 v[114:117], v[172:175], v[218:221], v[114:117]
	v_mfma_f32_16x16x32_bf16 v[110:113], v[144:147], v[226:229], v[110:113]
	v_mfma_f32_16x16x32_bf16 v[106:109], v[172:175], v[226:229], v[106:109]
	v_mfma_f32_16x16x32_bf16 v[102:105], v[144:147], v[234:237], v[102:105]
	v_mfma_f32_16x16x32_bf16 v[98:101], v[172:175], v[234:237], v[98:101]
	v_mfma_f32_16x16x32_bf16 v[126:129], v[148:151], v[214:217], v[126:129]
	v_mfma_f32_16x16x32_bf16 v[122:125], v[190:193], v[214:217], v[122:125]
	v_mfma_f32_16x16x32_bf16 v[118:121], v[148:151], v[222:225], v[118:121]
	v_mfma_f32_16x16x32_bf16 v[114:117], v[190:193], v[222:225], v[114:117]
	v_mfma_f32_16x16x32_bf16 v[110:113], v[148:151], v[230:233], v[110:113]
	v_mfma_f32_16x16x32_bf16 v[106:109], v[190:193], v[230:233], v[106:109]
	v_mfma_f32_16x16x32_bf16 v[102:105], v[148:151], v[238:241], v[102:105]
	v_mfma_f32_16x16x32_bf16 v[98:101], v[190:193], v[238:241], v[98:101]
	v_mfma_f32_16x16x32_bf16 v[66:69], v[194:197], v[210:213], v[66:69]
	v_mfma_f32_16x16x32_bf16 v[58:61], v[202:205], v[210:213], v[58:61]
	v_mfma_f32_16x16x32_bf16 v[54:57], v[194:197], v[218:221], v[54:57]
	v_mfma_f32_16x16x32_bf16 v[50:53], v[202:205], v[218:221], v[50:53]
	v_mfma_f32_16x16x32_bf16 v[46:49], v[194:197], v[226:229], v[46:49]
	v_mfma_f32_16x16x32_bf16 v[42:45], v[202:205], v[226:229], v[42:45]
	v_mfma_f32_16x16x32_bf16 v[38:41], v[194:197], v[234:237], v[38:41]
	v_mfma_f32_16x16x32_bf16 v[34:37], v[202:205], v[234:237], v[34:37]
	v_mfma_f32_16x16x32_bf16 v[66:69], v[198:201], v[214:217], v[66:69]
	v_mfma_f32_16x16x32_bf16 v[58:61], v[206:209], v[214:217], v[58:61]
	v_mfma_f32_16x16x32_bf16 v[54:57], v[198:201], v[222:225], v[54:57]
	v_mfma_f32_16x16x32_bf16 v[50:53], v[206:209], v[222:225], v[50:53]
	v_mfma_f32_16x16x32_bf16 v[46:49], v[198:201], v[230:233], v[46:49]
	v_mfma_f32_16x16x32_bf16 v[42:45], v[206:209], v[230:233], v[42:45]
	v_mfma_f32_16x16x32_bf16 v[38:41], v[198:201], v[238:241], v[38:41]
	v_mfma_f32_16x16x32_bf16 v[34:37], v[206:209], v[238:241], v[34:37]
	s_barrier
	s_add_i32 s3, s3, s26
	v_lshl_add_u64 v[162:163], s[0:1], 0, v[4:5]
	s_mov_b32 m0, s3
	ds_read_b128 v[210:213], v143 offset:16384
	ds_read_b128 v[214:217], v143 offset:17408
	ds_read_b128 v[218:221], v143 offset:18432
	ds_read_b128 v[222:225], v143 offset:19456
	ds_read_b128 v[226:229], v143 offset:20480
	ds_read_b128 v[230:233], v143 offset:21504
	ds_read_b128 v[234:237], v143 offset:22528
	ds_read_b128 v[238:241], v143 offset:23552
	global_load_lds_dwordx4 v4, s[0:1]
	s_add_i32 m0, s3, 0x2000
	s_add_u32 s4, s0, 0x80000
	v_lshl_add_u64 v[166:167], s[0:1], 0, v[130:131]
	s_addc_u32 s5, s1, 0
	s_add_i32 s3, s6, s26
	global_load_lds_dwordx4 v130, s[0:1]
	s_mov_b32 m0, s3
	v_lshl_add_u64 v[242:243], s[14:15], 0, v[132:133]
	global_load_lds_dwordx4 v4, s[4:5]
	s_add_i32 m0, s3, 0x2000
	s_nop 0
	global_load_lds_dwordx4 v130, s[4:5]
	v_lshl_add_u64 v[176:177], s[14:15], 0, v[134:135]
	s_mov_b32 m0, s27
	s_nop 0
	global_load_lds_dwordx4 v134, s[14:15]
	s_mov_b32 m0, s30
	s_nop 0
	global_load_lds_dwordx4 v132, s[14:15]
	s_waitcnt vmcnt(8) lgkmcnt(0)
	s_barrier
	v_mfma_f32_16x16x32_bf16 v[94:97], v[144:147], v[210:213], v[94:97]
	v_mfma_f32_16x16x32_bf16 v[90:93], v[172:175], v[210:213], v[90:93]
	v_mfma_f32_16x16x32_bf16 v[86:89], v[144:147], v[218:221], v[86:89]
	v_mfma_f32_16x16x32_bf16 v[82:85], v[172:175], v[218:221], v[82:85]
	v_mfma_f32_16x16x32_bf16 v[78:81], v[144:147], v[226:229], v[78:81]
	v_mfma_f32_16x16x32_bf16 v[74:77], v[172:175], v[226:229], v[74:77]
	v_mfma_f32_16x16x32_bf16 v[70:73], v[144:147], v[234:237], v[70:73]
	v_mfma_f32_16x16x32_bf16 v[62:65], v[172:175], v[234:237], v[62:65]
	v_mfma_f32_16x16x32_bf16 v[94:97], v[148:151], v[214:217], v[94:97]
	v_mfma_f32_16x16x32_bf16 v[90:93], v[190:193], v[214:217], v[90:93]
	v_mfma_f32_16x16x32_bf16 v[86:89], v[148:151], v[222:225], v[86:89]
	v_mfma_f32_16x16x32_bf16 v[82:85], v[190:193], v[222:225], v[82:85]
	v_mfma_f32_16x16x32_bf16 v[78:81], v[148:151], v[230:233], v[78:81]
	v_mfma_f32_16x16x32_bf16 v[74:77], v[190:193], v[230:233], v[74:77]
	v_mfma_f32_16x16x32_bf16 v[70:73], v[148:151], v[238:241], v[70:73]
	v_mfma_f32_16x16x32_bf16 v[62:65], v[190:193], v[238:241], v[62:65]
	v_mfma_f32_16x16x32_bf16 v[30:33], v[194:197], v[210:213], v[30:33]
	v_mfma_f32_16x16x32_bf16 v[26:29], v[202:205], v[210:213], v[26:29]
	v_mfma_f32_16x16x32_bf16 v[22:25], v[194:197], v[218:221], v[22:25]
	v_mfma_f32_16x16x32_bf16 v[18:21], v[202:205], v[218:221], v[18:21]
	v_mfma_f32_16x16x32_bf16 v[14:17], v[194:197], v[226:229], v[14:17]
	v_mfma_f32_16x16x32_bf16 v[10:13], v[202:205], v[226:229], v[10:13]
	v_mfma_f32_16x16x32_bf16 v[6:9], v[194:197], v[234:237], v[6:9]
	v_mfma_f32_16x16x32_bf16 v[0:3], v[202:205], v[234:237], v[0:3]
	v_mfma_f32_16x16x32_bf16 v[30:33], v[198:201], v[214:217], v[30:33]
	v_mfma_f32_16x16x32_bf16 v[26:29], v[206:209], v[214:217], v[26:29]
	v_mfma_f32_16x16x32_bf16 v[22:25], v[198:201], v[222:225], v[22:25]
	v_mfma_f32_16x16x32_bf16 v[18:21], v[206:209], v[222:225], v[18:21]
	v_mfma_f32_16x16x32_bf16 v[14:17], v[198:201], v[230:233], v[14:17]
	v_mfma_f32_16x16x32_bf16 v[10:13], v[206:209], v[230:233], v[10:13]
	v_mfma_f32_16x16x32_bf16 v[6:9], v[198:201], v[238:241], v[6:9]
	v_mfma_f32_16x16x32_bf16 v[0:3], v[206:209], v[238:241], v[0:3]
	s_barrier
.Lpeelmid_252:
	s_add_i32 s3, 0, 0x18000
	v_add_u32_e32 v164, s3, v141
	s_add_i32 s6, 0, 0x1c000
	ds_read_b128 v[144:147], v164
	ds_read_b128 v[148:151], v164 offset:1024
	ds_read_b128 v[172:175], v164 offset:2048
	ds_read_b128 v[190:193], v164 offset:3072
	v_add_u32_e32 v164, s6, v141
	ds_read_b128 v[194:197], v164
	ds_read_b128 v[198:201], v164 offset:1024
	ds_read_b128 v[202:205], v164 offset:2048
	ds_read_b128 v[206:209], v164 offset:3072
	s_add_u32 s4, s14, 0x80000
	s_addc_u32 s5, s15, 0
	s_mov_b32 m0, s31
	ds_read_b128 v[210:213], v143 offset:32768
	ds_read_b128 v[214:217], v143 offset:33792
	ds_read_b128 v[218:221], v143 offset:34816
	ds_read_b128 v[222:225], v143 offset:35840
	ds_read_b128 v[226:229], v143 offset:36864
	ds_read_b128 v[230:233], v143 offset:37888
	ds_read_b128 v[234:237], v143 offset:38912
	ds_read_b128 v[238:241], v143 offset:39936
	global_load_lds_dwordx4 v134, s[4:5]
	v_lshl_add_u64 v[244:245], s[4:5], 0, v[132:133]
	s_mov_b32 m0, s34
	s_nop 0
	global_load_lds_dwordx4 v132, s[4:5]
	s_waitcnt vmcnt(8) lgkmcnt(0)
	s_barrier
	v_mfma_f32_16x16x32_bf16 v[126:129], v[144:147], v[210:213], v[126:129]
	v_mfma_f32_16x16x32_bf16 v[122:125], v[172:175], v[210:213], v[122:125]
	v_mfma_f32_16x16x32_bf16 v[118:121], v[144:147], v[218:221], v[118:121]
	v_mfma_f32_16x16x32_bf16 v[114:117], v[172:175], v[218:221], v[114:117]
	v_mfma_f32_16x16x32_bf16 v[110:113], v[144:147], v[226:229], v[110:113]
	v_mfma_f32_16x16x32_bf16 v[106:109], v[172:175], v[226:229], v[106:109]
	v_mfma_f32_16x16x32_bf16 v[102:105], v[144:147], v[234:237], v[102:105]
	v_mfma_f32_16x16x32_bf16 v[98:101], v[172:175], v[234:237], v[98:101]
	v_mfma_f32_16x16x32_bf16 v[126:129], v[148:151], v[214:217], v[126:129]
	v_mfma_f32_16x16x32_bf16 v[122:125], v[190:193], v[214:217], v[122:125]
	v_mfma_f32_16x16x32_bf16 v[118:121], v[148:151], v[222:225], v[118:121]
	v_mfma_f32_16x16x32_bf16 v[114:117], v[190:193], v[222:225], v[114:117]
	v_mfma_f32_16x16x32_bf16 v[110:113], v[148:151], v[230:233], v[110:113]
	v_mfma_f32_16x16x32_bf16 v[106:109], v[190:193], v[230:233], v[106:109]
	v_mfma_f32_16x16x32_bf16 v[102:105], v[148:151], v[238:241], v[102:105]
	v_mfma_f32_16x16x32_bf16 v[98:101], v[190:193], v[238:241], v[98:101]
	v_mfma_f32_16x16x32_bf16 v[66:69], v[194:197], v[210:213], v[66:69]
	v_mfma_f32_16x16x32_bf16 v[58:61], v[202:205], v[210:213], v[58:61]
	v_mfma_f32_16x16x32_bf16 v[54:57], v[194:197], v[218:221], v[54:57]
	v_mfma_f32_16x16x32_bf16 v[50:53], v[202:205], v[218:221], v[50:53]
	v_mfma_f32_16x16x32_bf16 v[46:49], v[194:197], v[226:229], v[46:49]
	v_mfma_f32_16x16x32_bf16 v[42:45], v[202:205], v[226:229], v[42:45]
	v_mfma_f32_16x16x32_bf16 v[38:41], v[194:197], v[234:237], v[38:41]
	v_mfma_f32_16x16x32_bf16 v[34:37], v[202:205], v[234:237], v[34:37]
	v_mfma_f32_16x16x32_bf16 v[66:69], v[198:201], v[214:217], v[66:69]
	v_mfma_f32_16x16x32_bf16 v[58:61], v[206:209], v[214:217], v[58:61]
	v_mfma_f32_16x16x32_bf16 v[54:57], v[198:201], v[222:225], v[54:57]
	v_mfma_f32_16x16x32_bf16 v[50:53], v[206:209], v[222:225], v[50:53]
	v_mfma_f32_16x16x32_bf16 v[46:49], v[198:201], v[230:233], v[46:49]
	v_mfma_f32_16x16x32_bf16 v[42:45], v[206:209], v[230:233], v[42:45]
	v_mfma_f32_16x16x32_bf16 v[38:41], v[198:201], v[238:241], v[38:41]
	v_mfma_f32_16x16x32_bf16 v[34:37], v[206:209], v[238:241], v[34:37]
	s_barrier
	s_add_i32 s3, s3, s26
	v_lshl_add_u64 v[162:163], v[162:163], 0, s[70:71]
	s_mov_b32 m0, s3
	ds_read_b128 v[210:213], v143 offset:49152
	ds_read_b128 v[214:217], v143 offset:50176
	ds_read_b128 v[218:221], v143 offset:51200
	ds_read_b128 v[222:225], v143 offset:52224
	ds_read_b128 v[226:229], v143 offset:53248
	ds_read_b128 v[230:233], v143 offset:54272
	ds_read_b128 v[234:237], v143 offset:55296
	ds_read_b128 v[238:241], v143 offset:56320
	global_load_lds_dwordx4 v[162:163], off
	s_add_i32 m0, s3, 0x2000
	s_add_u32 s0, s0, 0x80080
	v_lshl_add_u64 v[162:163], v[166:167], 0, s[70:71]
	s_addc_u32 s1, s1, 0
	s_add_i32 s3, s6, s26
	global_load_lds_dwordx4 v[162:163], off
	s_mov_b32 m0, s3
	s_nop 0
	global_load_lds_dwordx4 v4, s[0:1]
	s_add_i32 m0, s3, 0x2000
	s_nop 0
	global_load_lds_dwordx4 v130, s[0:1]
	v_lshl_add_u64 v[162:163], v[176:177], 0, s[70:71]
	s_mov_b32 m0, s35
	s_nop 0
	global_load_lds_dwordx4 v[162:163], off
	v_lshl_add_u64 v[162:163], v[242:243], 0, s[70:71]
	s_mov_b32 m0, s36
	s_nop 0
	global_load_lds_dwordx4 v[162:163], off
	s_waitcnt vmcnt(8) lgkmcnt(0)
	s_barrier
	v_mfma_f32_16x16x32_bf16 v[94:97], v[144:147], v[210:213], v[94:97]
	v_mfma_f32_16x16x32_bf16 v[90:93], v[172:175], v[210:213], v[90:93]
	v_mfma_f32_16x16x32_bf16 v[86:89], v[144:147], v[218:221], v[86:89]
	v_mfma_f32_16x16x32_bf16 v[82:85], v[172:175], v[218:221], v[82:85]
	v_mfma_f32_16x16x32_bf16 v[78:81], v[144:147], v[226:229], v[78:81]
	v_mfma_f32_16x16x32_bf16 v[74:77], v[172:175], v[226:229], v[74:77]
	v_mfma_f32_16x16x32_bf16 v[70:73], v[144:147], v[234:237], v[70:73]
	v_mfma_f32_16x16x32_bf16 v[62:65], v[172:175], v[234:237], v[62:65]
	v_mfma_f32_16x16x32_bf16 v[94:97], v[148:151], v[214:217], v[94:97]
	v_mfma_f32_16x16x32_bf16 v[90:93], v[190:193], v[214:217], v[90:93]
	v_mfma_f32_16x16x32_bf16 v[86:89], v[148:151], v[222:225], v[86:89]
	v_mfma_f32_16x16x32_bf16 v[82:85], v[190:193], v[222:225], v[82:85]
	v_mfma_f32_16x16x32_bf16 v[78:81], v[148:151], v[230:233], v[78:81]
	v_mfma_f32_16x16x32_bf16 v[74:77], v[190:193], v[230:233], v[74:77]
	v_mfma_f32_16x16x32_bf16 v[70:73], v[148:151], v[238:241], v[70:73]
	v_mfma_f32_16x16x32_bf16 v[62:65], v[190:193], v[238:241], v[62:65]
	v_mfma_f32_16x16x32_bf16 v[30:33], v[194:197], v[210:213], v[30:33]
	v_mfma_f32_16x16x32_bf16 v[26:29], v[202:205], v[210:213], v[26:29]
	v_mfma_f32_16x16x32_bf16 v[22:25], v[194:197], v[218:221], v[22:25]
	v_mfma_f32_16x16x32_bf16 v[18:21], v[202:205], v[218:221], v[18:21]
	v_mfma_f32_16x16x32_bf16 v[14:17], v[194:197], v[226:229], v[14:17]
	v_mfma_f32_16x16x32_bf16 v[10:13], v[202:205], v[226:229], v[10:13]
	v_mfma_f32_16x16x32_bf16 v[6:9], v[194:197], v[234:237], v[6:9]
	v_mfma_f32_16x16x32_bf16 v[0:3], v[202:205], v[234:237], v[0:3]
	v_mfma_f32_16x16x32_bf16 v[30:33], v[198:201], v[214:217], v[30:33]
	v_mfma_f32_16x16x32_bf16 v[26:29], v[206:209], v[214:217], v[26:29]
	v_mfma_f32_16x16x32_bf16 v[22:25], v[198:201], v[222:225], v[22:25]
	v_mfma_f32_16x16x32_bf16 v[18:21], v[206:209], v[222:225], v[18:21]
	v_mfma_f32_16x16x32_bf16 v[14:17], v[198:201], v[230:233], v[14:17]
	v_mfma_f32_16x16x32_bf16 v[10:13], v[206:209], v[230:233], v[10:13]
	v_mfma_f32_16x16x32_bf16 v[6:9], v[198:201], v[238:241], v[6:9]
	v_mfma_f32_16x16x32_bf16 v[0:3], v[206:209], v[238:241], v[0:3]
	s_barrier
	s_add_i32 s24, s24, 2
	s_add_u32 s22, s22, 0x100
	s_addc_u32 s23, s23, 0
	s_add_u32 s9, s9, 0x100
	s_addc_u32 s10, s10, 0
	s_cmp_gt_u32 s24, 29
	s_cbranch_scc0 .LBB0_252
	s_and_b64 vcc, exec, s[44:45]
	s_cbranch_vccz .LBB0_255
	s_barrier

.LBB0_851:
	s_ashr_i32 s3, s37, 24
	s_lshl_b32 s2, s37, 8
	s_andn2_b32 s3, s3, 63
	s_add_i32 s2, s3, s2
	s_ashr_i32 s3, s2, 31
	s_lshl_b64 s[2:3], s[2:3], 12
	v_readlane_b32 s4, v252, 6
	v_readlane_b32 s5, v252, 7
	s_add_u32 s76, s4, s2
	s_addc_u32 s77, s5, s3
	s_and_b64 s[2:3], s[38:39], exec
	s_cselect_b32 s2, s77, s15
	s_cselect_b32 s8, s76, s14
	s_ashr_i32 s59, s58, 31
	s_lshl_b64 s[4:5], s[58:59], 20
	v_readlane_b32 s6, v252, 4
	v_readlane_b32 s7, v252, 5
	s_add_u32 s78, s6, s4
	s_addc_u32 s79, s7, s5
	s_and_b64 s[4:5], s[38:39], exec
	s_cselect_b32 s10, s79, s1
	s_cselect_b32 s24, s78, s0
	s_add_u32 s22, s14, 0x80080
	s_addc_u32 s23, s15, 0
	s_add_u32 s9, s0, 0x100
	v_mov_b32_e32 v0, 0
	s_addc_u32 s25, s1, 0
	s_mov_b32 s28, -2
	v_mov_b32_e32 v1, v0
	v_mov_b32_e32 v2, v0
	v_mov_b32_e32 v3, v0
	v_mov_b32_e32 v6, v0
	v_mov_b32_e32 v7, v0
	v_mov_b32_e32 v8, v0
	v_mov_b32_e32 v9, v0
	v_mov_b32_e32 v10, v0
	v_mov_b32_e32 v11, v0
	v_mov_b32_e32 v12, v0
	v_mov_b32_e32 v13, v0
	v_mov_b32_e32 v14, v0
	v_mov_b32_e32 v15, v0
	v_mov_b32_e32 v16, v0
	v_mov_b32_e32 v17, v0
	v_mov_b32_e32 v18, v0
	v_mov_b32_e32 v19, v0
	v_mov_b32_e32 v20, v0
	v_mov_b32_e32 v21, v0
	v_mov_b32_e32 v22, v0
	v_mov_b32_e32 v23, v0
	v_mov_b32_e32 v24, v0
	v_mov_b32_e32 v25, v0
	v_mov_b32_e32 v26, v0
	v_mov_b32_e32 v27, v0
	v_mov_b32_e32 v28, v0
	v_mov_b32_e32 v29, v0
	v_mov_b32_e32 v30, v0
	v_mov_b32_e32 v31, v0
	v_mov_b32_e32 v32, v0
	v_mov_b32_e32 v33, v0
	v_mov_b32_e32 v66, v0
	v_mov_b32_e32 v67, v0
	v_mov_b32_e32 v68, v0
	v_mov_b32_e32 v69, v0
	v_mov_b32_e32 v70, v0
	v_mov_b32_e32 v71, v0
	v_mov_b32_e32 v72, v0
	v_mov_b32_e32 v73, v0
	v_mov_b32_e32 v74, v0
	v_mov_b32_e32 v75, v0
	v_mov_b32_e32 v76, v0
	v_mov_b32_e32 v77, v0
	v_mov_b32_e32 v78, v0
	v_mov_b32_e32 v79, v0
	v_mov_b32_e32 v80, v0
	v_mov_b32_e32 v81, v0
	v_mov_b32_e32 v82, v0
	v_mov_b32_e32 v83, v0
	v_mov_b32_e32 v84, v0
	v_mov_b32_e32 v85, v0
	v_mov_b32_e32 v86, v0
	v_mov_b32_e32 v87, v0
	v_mov_b32_e32 v88, v0
	v_mov_b32_e32 v89, v0
	v_mov_b32_e32 v90, v0
	v_mov_b32_e32 v91, v0
	v_mov_b32_e32 v92, v0
	v_mov_b32_e32 v93, v0
	v_mov_b32_e32 v94, v0
	v_mov_b32_e32 v95, v0
	v_mov_b32_e32 v96, v0
	v_mov_b32_e32 v97, v0
	v_mov_b32_e32 v34, v0
	v_mov_b32_e32 v35, v0
	v_mov_b32_e32 v36, v0
	v_mov_b32_e32 v37, v0
	v_mov_b32_e32 v38, v0
	v_mov_b32_e32 v39, v0
	v_mov_b32_e32 v40, v0
	v_mov_b32_e32 v41, v0
	v_mov_b32_e32 v42, v0
	v_mov_b32_e32 v43, v0
	v_mov_b32_e32 v44, v0
	v_mov_b32_e32 v45, v0
	v_mov_b32_e32 v46, v0
	v_mov_b32_e32 v47, v0
	v_mov_b32_e32 v48, v0
	v_mov_b32_e32 v49, v0
	v_mov_b32_e32 v50, v0
	v_mov_b32_e32 v51, v0
	v_mov_b32_e32 v52, v0
	v_mov_b32_e32 v53, v0
	v_mov_b32_e32 v54, v0
	v_mov_b32_e32 v55, v0
	v_mov_b32_e32 v56, v0
	v_mov_b32_e32 v57, v0
	v_mov_b32_e32 v58, v0
	v_mov_b32_e32 v59, v0
	v_mov_b32_e32 v60, v0
	v_mov_b32_e32 v61, v0
	v_mov_b32_e32 v62, v0
	v_mov_b32_e32 v63, v0
	v_mov_b32_e32 v64, v0
	v_mov_b32_e32 v65, v0
	v_mov_b32_e32 v98, v0
	v_mov_b32_e32 v99, v0
	v_mov_b32_e32 v100, v0
	v_mov_b32_e32 v101, v0
	v_mov_b32_e32 v102, v0
	v_mov_b32_e32 v103, v0
	v_mov_b32_e32 v104, v0
	v_mov_b32_e32 v105, v0
	v_mov_b32_e32 v106, v0
	v_mov_b32_e32 v107, v0
	v_mov_b32_e32 v108, v0
	v_mov_b32_e32 v109, v0
	v_mov_b32_e32 v110, v0
	v_mov_b32_e32 v111, v0
	v_mov_b32_e32 v112, v0
	v_mov_b32_e32 v113, v0
	v_mov_b32_e32 v114, v0
	v_mov_b32_e32 v115, v0
	v_mov_b32_e32 v116, v0
	v_mov_b32_e32 v117, v0
	v_mov_b32_e32 v118, v0
	v_mov_b32_e32 v119, v0
	v_mov_b32_e32 v120, v0
	v_mov_b32_e32 v121, v0
	v_mov_b32_e32 v122, v0
	v_mov_b32_e32 v123, v0
	v_mov_b32_e32 v124, v0
	v_mov_b32_e32 v125, v0
	v_mov_b32_e32 v126, v0
	v_mov_b32_e32 v127, v0
	v_mov_b32_e32 v128, v0
	v_mov_b32_e32 v129, v0
	s_cmp_eq_u32 s36, 1
	s_cbranch_scc1 .LBB0_852
	s_add_u32 s0, s22, 0xfff80080
	s_addc_u32 s1, s23, -1
	s_add_i32 s3, 0, 0x10000
	s_cmp_eq_u32 s28, 28
	s_cselect_b32 s15, s2, s1
	s_cselect_b32 s14, s8, s0
	v_add_u32_e32 v167, s3, v163
	s_cselect_b32 s1, s10, s25
	s_cselect_b32 s0, s24, s9
	s_add_i32 s6, 0, 0x14000
	ds_read_b128 v[140:143], v167
	ds_read_b128 v[144:147], v167 offset:1024
	ds_read_b128 v[148:151], v167 offset:2048
	ds_read_b128 v[172:175], v167 offset:3072
	v_add_u32_e32 v167, s6, v163
	ds_read_b128 v[190:193], v167
	ds_read_b128 v[194:197], v167 offset:1024
	ds_read_b128 v[198:201], v167 offset:2048
	ds_read_b128 v[202:205], v167 offset:3072
	s_add_i32 m0, s26, 0xc000
	ds_read_b128 v[206:209], v166
	ds_read_b128 v[210:213], v166 offset:1024
	ds_read_b128 v[214:217], v166 offset:2048
	ds_read_b128 v[218:221], v166 offset:3072
	ds_read_b128 v[222:225], v166 offset:4096
	ds_read_b128 v[226:229], v166 offset:5120
	ds_read_b128 v[230:233], v166 offset:6144
	ds_read_b128 v[234:237], v166 offset:7168
	global_load_lds_dwordx4 v136, s[22:23]
	s_add_i32 m0, s26, 0xe000
	s_nop 0
	global_load_lds_dwordx4 v138, s[22:23]
	s_waitcnt vmcnt(24) lgkmcnt(0)
	s_barrier
	v_mfma_f32_16x16x32_bf16 v[126:129], v[140:143], v[206:209], v[126:129]
	v_mfma_f32_16x16x32_bf16 v[122:125], v[148:151], v[206:209], v[122:125]
	v_mfma_f32_16x16x32_bf16 v[118:121], v[140:143], v[214:217], v[118:121]
	v_mfma_f32_16x16x32_bf16 v[114:117], v[148:151], v[214:217], v[114:117]
	v_mfma_f32_16x16x32_bf16 v[110:113], v[140:143], v[222:225], v[110:113]
	v_mfma_f32_16x16x32_bf16 v[106:109], v[148:151], v[222:225], v[106:109]
	v_mfma_f32_16x16x32_bf16 v[102:105], v[140:143], v[230:233], v[102:105]
	v_mfma_f32_16x16x32_bf16 v[98:101], v[148:151], v[230:233], v[98:101]
	v_mfma_f32_16x16x32_bf16 v[126:129], v[144:147], v[210:213], v[126:129]
	v_mfma_f32_16x16x32_bf16 v[122:125], v[172:175], v[210:213], v[122:125]
	v_mfma_f32_16x16x32_bf16 v[118:121], v[144:147], v[218:221], v[118:121]
	v_mfma_f32_16x16x32_bf16 v[114:117], v[172:175], v[218:221], v[114:117]
	v_mfma_f32_16x16x32_bf16 v[110:113], v[144:147], v[226:229], v[110:113]
	v_mfma_f32_16x16x32_bf16 v[106:109], v[172:175], v[226:229], v[106:109]
	v_mfma_f32_16x16x32_bf16 v[102:105], v[144:147], v[234:237], v[102:105]
	v_mfma_f32_16x16x32_bf16 v[98:101], v[172:175], v[234:237], v[98:101]
	v_mfma_f32_16x16x32_bf16 v[62:65], v[190:193], v[206:209], v[62:65]
	v_mfma_f32_16x16x32_bf16 v[58:61], v[198:201], v[206:209], v[58:61]
	v_mfma_f32_16x16x32_bf16 v[54:57], v[190:193], v[214:217], v[54:57]
	v_mfma_f32_16x16x32_bf16 v[50:53], v[198:201], v[214:217], v[50:53]
	v_mfma_f32_16x16x32_bf16 v[46:49], v[190:193], v[222:225], v[46:49]
	v_mfma_f32_16x16x32_bf16 v[42:45], v[198:201], v[222:225], v[42:45]
	v_mfma_f32_16x16x32_bf16 v[38:41], v[190:193], v[230:233], v[38:41]
	v_mfma_f32_16x16x32_bf16 v[34:37], v[198:201], v[230:233], v[34:37]
	v_mfma_f32_16x16x32_bf16 v[62:65], v[194:197], v[210:213], v[62:65]
	v_mfma_f32_16x16x32_bf16 v[58:61], v[202:205], v[210:213], v[58:61]
	v_mfma_f32_16x16x32_bf16 v[54:57], v[194:197], v[218:221], v[54:57]
	v_mfma_f32_16x16x32_bf16 v[50:53], v[202:205], v[218:221], v[50:53]
	v_mfma_f32_16x16x32_bf16 v[46:49], v[194:197], v[226:229], v[46:49]
	v_mfma_f32_16x16x32_bf16 v[42:45], v[202:205], v[226:229], v[42:45]
	v_mfma_f32_16x16x32_bf16 v[38:41], v[194:197], v[234:237], v[38:41]
	v_mfma_f32_16x16x32_bf16 v[34:37], v[202:205], v[234:237], v[34:37]
	s_barrier
	s_add_i32 s3, s3, s11
	v_lshl_add_u64 v[176:177], s[0:1], 0, v[4:5]
	s_mov_b32 m0, s3
	ds_read_b128 v[206:209], v166 offset:16384
	ds_read_b128 v[210:213], v166 offset:17408
	ds_read_b128 v[214:217], v166 offset:18432
	ds_read_b128 v[218:221], v166 offset:19456
	ds_read_b128 v[222:225], v166 offset:20480
	ds_read_b128 v[226:229], v166 offset:21504
	ds_read_b128 v[230:233], v166 offset:22528
	ds_read_b128 v[234:237], v166 offset:23552
	global_load_lds_dwordx4 v4, s[0:1]
	s_add_i32 m0, s3, 0x2000
	s_add_u32 s4, s0, 0x80000
	v_lshl_add_u64 v[238:239], s[0:1], 0, v[134:135]
	s_addc_u32 s5, s1, 0
	s_add_i32 s3, s6, s11
	global_load_lds_dwordx4 v134, s[0:1]
	s_mov_b32 m0, s3
	v_lshl_add_u64 v[242:243], s[14:15], 0, v[132:133]
	global_load_lds_dwordx4 v4, s[4:5]
	s_add_i32 m0, s3, 0x2000
	s_nop 0
	global_load_lds_dwordx4 v134, s[4:5]
	v_lshl_add_u64 v[240:241], s[14:15], 0, v[130:131]
	s_mov_b32 m0, s26
	s_nop 0
	global_load_lds_dwordx4 v130, s[14:15]
	s_mov_b32 m0, s27
	s_nop 0
	global_load_lds_dwordx4 v132, s[14:15]
	s_waitcnt vmcnt(24) lgkmcnt(0)
	s_barrier
	v_mfma_f32_16x16x32_bf16 v[94:97], v[140:143], v[206:209], v[94:97]
	v_mfma_f32_16x16x32_bf16 v[90:93], v[148:151], v[206:209], v[90:93]
	v_mfma_f32_16x16x32_bf16 v[86:89], v[140:143], v[214:217], v[86:89]
	v_mfma_f32_16x16x32_bf16 v[82:85], v[148:151], v[214:217], v[82:85]
	v_mfma_f32_16x16x32_bf16 v[78:81], v[140:143], v[222:225], v[78:81]
	v_mfma_f32_16x16x32_bf16 v[74:77], v[148:151], v[222:225], v[74:77]
	v_mfma_f32_16x16x32_bf16 v[70:73], v[140:143], v[230:233], v[70:73]
	v_mfma_f32_16x16x32_bf16 v[66:69], v[148:151], v[230:233], v[66:69]
	v_mfma_f32_16x16x32_bf16 v[94:97], v[144:147], v[210:213], v[94:97]
	v_mfma_f32_16x16x32_bf16 v[90:93], v[172:175], v[210:213], v[90:93]
	v_mfma_f32_16x16x32_bf16 v[86:89], v[144:147], v[218:221], v[86:89]
	v_mfma_f32_16x16x32_bf16 v[82:85], v[172:175], v[218:221], v[82:85]
	v_mfma_f32_16x16x32_bf16 v[78:81], v[144:147], v[226:229], v[78:81]
	v_mfma_f32_16x16x32_bf16 v[74:77], v[172:175], v[226:229], v[74:77]
	v_mfma_f32_16x16x32_bf16 v[70:73], v[144:147], v[234:237], v[70:73]
	v_mfma_f32_16x16x32_bf16 v[66:69], v[172:175], v[234:237], v[66:69]
	v_mfma_f32_16x16x32_bf16 v[30:33], v[190:193], v[206:209], v[30:33]
	v_mfma_f32_16x16x32_bf16 v[26:29], v[198:201], v[206:209], v[26:29]
	v_mfma_f32_16x16x32_bf16 v[22:25], v[190:193], v[214:217], v[22:25]
	v_mfma_f32_16x16x32_bf16 v[18:21], v[198:201], v[214:217], v[18:21]
	v_mfma_f32_16x16x32_bf16 v[14:17], v[190:193], v[222:225], v[14:17]
	v_mfma_f32_16x16x32_bf16 v[10:13], v[198:201], v[222:225], v[10:13]
	v_mfma_f32_16x16x32_bf16 v[6:9], v[190:193], v[230:233], v[6:9]
	v_mfma_f32_16x16x32_bf16 v[0:3], v[198:201], v[230:233], v[0:3]
	v_mfma_f32_16x16x32_bf16 v[30:33], v[194:197], v[210:213], v[30:33]
	v_mfma_f32_16x16x32_bf16 v[26:29], v[202:205], v[210:213], v[26:29]
	v_mfma_f32_16x16x32_bf16 v[22:25], v[194:197], v[218:221], v[22:25]
	v_mfma_f32_16x16x32_bf16 v[18:21], v[202:205], v[218:221], v[18:21]
	v_mfma_f32_16x16x32_bf16 v[14:17], v[194:197], v[226:229], v[14:17]
	v_mfma_f32_16x16x32_bf16 v[10:13], v[202:205], v[226:229], v[10:13]
	v_mfma_f32_16x16x32_bf16 v[6:9], v[194:197], v[234:237], v[6:9]
	v_mfma_f32_16x16x32_bf16 v[0:3], v[202:205], v[234:237], v[0:3]
	s_barrier
	s_branch .Lpeelmid_852
.LBB0_852:
	s_add_u32 s0, s22, 0xfff80080
	s_addc_u32 s1, s23, -1
	s_add_i32 s3, 0, 0x10000
	s_cmp_eq_u32 s28, 28
	s_cselect_b32 s15, s2, s1
	s_cselect_b32 s14, s8, s0
	v_add_u32_e32 v167, s3, v163
	s_cselect_b32 s1, s10, s25
	s_cselect_b32 s0, s24, s9
	s_add_i32 s6, 0, 0x14000
	ds_read_b128 v[140:143], v167
	ds_read_b128 v[144:147], v167 offset:1024
	ds_read_b128 v[148:151], v167 offset:2048
	ds_read_b128 v[172:175], v167 offset:3072
	v_add_u32_e32 v167, s6, v163
	ds_read_b128 v[190:193], v167
	ds_read_b128 v[194:197], v167 offset:1024
	ds_read_b128 v[198:201], v167 offset:2048
	ds_read_b128 v[202:205], v167 offset:3072
	s_add_i32 m0, s26, 0xc000
	ds_read_b128 v[206:209], v166
	ds_read_b128 v[210:213], v166 offset:1024
	ds_read_b128 v[214:217], v166 offset:2048
	ds_read_b128 v[218:221], v166 offset:3072
	ds_read_b128 v[222:225], v166 offset:4096
	ds_read_b128 v[226:229], v166 offset:5120
	ds_read_b128 v[230:233], v166 offset:6144
	ds_read_b128 v[234:237], v166 offset:7168
	global_load_lds_dwordx4 v136, s[22:23]
	s_add_i32 m0, s26, 0xe000
	s_nop 0
	global_load_lds_dwordx4 v138, s[22:23]
	s_waitcnt vmcnt(8) lgkmcnt(0)
	s_barrier
	v_mfma_f32_16x16x32_bf16 v[126:129], v[140:143], v[206:209], v[126:129]
	v_mfma_f32_16x16x32_bf16 v[122:125], v[148:151], v[206:209], v[122:125]
	v_mfma_f32_16x16x32_bf16 v[118:121], v[140:143], v[214:217], v[118:121]
	v_mfma_f32_16x16x32_bf16 v[114:117], v[148:151], v[214:217], v[114:117]
	v_mfma_f32_16x16x32_bf16 v[110:113], v[140:143], v[222:225], v[110:113]
	v_mfma_f32_16x16x32_bf16 v[106:109], v[148:151], v[222:225], v[106:109]
	v_mfma_f32_16x16x32_bf16 v[102:105], v[140:143], v[230:233], v[102:105]
	v_mfma_f32_16x16x32_bf16 v[98:101], v[148:151], v[230:233], v[98:101]
	v_mfma_f32_16x16x32_bf16 v[126:129], v[144:147], v[210:213], v[126:129]
	v_mfma_f32_16x16x32_bf16 v[122:125], v[172:175], v[210:213], v[122:125]
	v_mfma_f32_16x16x32_bf16 v[118:121], v[144:147], v[218:221], v[118:121]
	v_mfma_f32_16x16x32_bf16 v[114:117], v[172:175], v[218:221], v[114:117]
	v_mfma_f32_16x16x32_bf16 v[110:113], v[144:147], v[226:229], v[110:113]
	v_mfma_f32_16x16x32_bf16 v[106:109], v[172:175], v[226:229], v[106:109]
	v_mfma_f32_16x16x32_bf16 v[102:105], v[144:147], v[234:237], v[102:105]
	v_mfma_f32_16x16x32_bf16 v[98:101], v[172:175], v[234:237], v[98:101]
	v_mfma_f32_16x16x32_bf16 v[62:65], v[190:193], v[206:209], v[62:65]
	v_mfma_f32_16x16x32_bf16 v[58:61], v[198:201], v[206:209], v[58:61]
	v_mfma_f32_16x16x32_bf16 v[54:57], v[190:193], v[214:217], v[54:57]
	v_mfma_f32_16x16x32_bf16 v[50:53], v[198:201], v[214:217], v[50:53]
	v_mfma_f32_16x16x32_bf16 v[46:49], v[190:193], v[222:225], v[46:49]
	v_mfma_f32_16x16x32_bf16 v[42:45], v[198:201], v[222:225], v[42:45]
	v_mfma_f32_16x16x32_bf16 v[38:41], v[190:193], v[230:233], v[38:41]
	v_mfma_f32_16x16x32_bf16 v[34:37], v[198:201], v[230:233], v[34:37]
	v_mfma_f32_16x16x32_bf16 v[62:65], v[194:197], v[210:213], v[62:65]
	v_mfma_f32_16x16x32_bf16 v[58:61], v[202:205], v[210:213], v[58:61]
	v_mfma_f32_16x16x32_bf16 v[54:57], v[194:197], v[218:221], v[54:57]
	v_mfma_f32_16x16x32_bf16 v[50:53], v[202:205], v[218:221], v[50:53]
	v_mfma_f32_16x16x32_bf16 v[46:49], v[194:197], v[226:229], v[46:49]
	v_mfma_f32_16x16x32_bf16 v[42:45], v[202:205], v[226:229], v[42:45]
	v_mfma_f32_16x16x32_bf16 v[38:41], v[194:197], v[234:237], v[38:41]
	v_mfma_f32_16x16x32_bf16 v[34:37], v[202:205], v[234:237], v[34:37]
	s_barrier
	s_add_i32 s3, s3, s11
	v_lshl_add_u64 v[176:177], s[0:1], 0, v[4:5]
	s_mov_b32 m0, s3
	ds_read_b128 v[206:209], v166 offset:16384
	ds_read_b128 v[210:213], v166 offset:17408
	ds_read_b128 v[214:217], v166 offset:18432
	ds_read_b128 v[218:221], v166 offset:19456
	ds_read_b128 v[222:225], v166 offset:20480
	ds_read_b128 v[226:229], v166 offset:21504
	ds_read_b128 v[230:233], v166 offset:22528
	ds_read_b128 v[234:237], v166 offset:23552
	global_load_lds_dwordx4 v4, s[0:1]
	s_add_i32 m0, s3, 0x2000
	s_add_u32 s4, s0, 0x80000
	v_lshl_add_u64 v[238:239], s[0:1], 0, v[134:135]
	s_addc_u32 s5, s1, 0
	s_add_i32 s3, s6, s11
	global_load_lds_dwordx4 v134, s[0:1]
	s_mov_b32 m0, s3
	v_lshl_add_u64 v[242:243], s[14:15], 0, v[132:133]
	global_load_lds_dwordx4 v4, s[4:5]
	s_add_i32 m0, s3, 0x2000
	s_nop 0
	global_load_lds_dwordx4 v134, s[4:5]
	v_lshl_add_u64 v[240:241], s[14:15], 0, v[130:131]
	s_mov_b32 m0, s26
	s_nop 0
	global_load_lds_dwordx4 v130, s[14:15]
	s_mov_b32 m0, s27
	s_nop 0
	global_load_lds_dwordx4 v132, s[14:15]
	s_waitcnt vmcnt(8) lgkmcnt(0)
	s_barrier
	v_mfma_f32_16x16x32_bf16 v[94:97], v[140:143], v[206:209], v[94:97]
	v_mfma_f32_16x16x32_bf16 v[90:93], v[148:151], v[206:209], v[90:93]
	v_mfma_f32_16x16x32_bf16 v[86:89], v[140:143], v[214:217], v[86:89]
	v_mfma_f32_16x16x32_bf16 v[82:85], v[148:151], v[214:217], v[82:85]
	v_mfma_f32_16x16x32_bf16 v[78:81], v[140:143], v[222:225], v[78:81]
	v_mfma_f32_16x16x32_bf16 v[74:77], v[148:151], v[222:225], v[74:77]
	v_mfma_f32_16x16x32_bf16 v[70:73], v[140:143], v[230:233], v[70:73]
	v_mfma_f32_16x16x32_bf16 v[66:69], v[148:151], v[230:233], v[66:69]
	v_mfma_f32_16x16x32_bf16 v[94:97], v[144:147], v[210:213], v[94:97]
	v_mfma_f32_16x16x32_bf16 v[90:93], v[172:175], v[210:213], v[90:93]
	v_mfma_f32_16x16x32_bf16 v[86:89], v[144:147], v[218:221], v[86:89]
	v_mfma_f32_16x16x32_bf16 v[82:85], v[172:175], v[218:221], v[82:85]
	v_mfma_f32_16x16x32_bf16 v[78:81], v[144:147], v[226:229], v[78:81]
	v_mfma_f32_16x16x32_bf16 v[74:77], v[172:175], v[226:229], v[74:77]
	v_mfma_f32_16x16x32_bf16 v[70:73], v[144:147], v[234:237], v[70:73]
	v_mfma_f32_16x16x32_bf16 v[66:69], v[172:175], v[234:237], v[66:69]
	v_mfma_f32_16x16x32_bf16 v[30:33], v[190:193], v[206:209], v[30:33]
	v_mfma_f32_16x16x32_bf16 v[26:29], v[198:201], v[206:209], v[26:29]
	v_mfma_f32_16x16x32_bf16 v[22:25], v[190:193], v[214:217], v[22:25]
	v_mfma_f32_16x16x32_bf16 v[18:21], v[198:201], v[214:217], v[18:21]
	v_mfma_f32_16x16x32_bf16 v[14:17], v[190:193], v[222:225], v[14:17]
	v_mfma_f32_16x16x32_bf16 v[10:13], v[198:201], v[222:225], v[10:13]
	v_mfma_f32_16x16x32_bf16 v[6:9], v[190:193], v[230:233], v[6:9]
	v_mfma_f32_16x16x32_bf16 v[0:3], v[198:201], v[230:233], v[0:3]
	v_mfma_f32_16x16x32_bf16 v[30:33], v[194:197], v[210:213], v[30:33]
	v_mfma_f32_16x16x32_bf16 v[26:29], v[202:205], v[210:213], v[26:29]
	v_mfma_f32_16x16x32_bf16 v[22:25], v[194:197], v[218:221], v[22:25]
	v_mfma_f32_16x16x32_bf16 v[18:21], v[202:205], v[218:221], v[18:21]
	v_mfma_f32_16x16x32_bf16 v[14:17], v[194:197], v[226:229], v[14:17]
	v_mfma_f32_16x16x32_bf16 v[10:13], v[202:205], v[226:229], v[10:13]
	v_mfma_f32_16x16x32_bf16 v[6:9], v[194:197], v[234:237], v[6:9]
	v_mfma_f32_16x16x32_bf16 v[0:3], v[202:205], v[234:237], v[0:3]
	s_barrier
.Lpeelmid_852:
	s_add_i32 s3, 0, 0x18000
	v_add_u32_e32 v167, s3, v163
	s_add_i32 s6, 0, 0x1c000
	ds_read_b128 v[140:143], v167
	ds_read_b128 v[144:147], v167 offset:1024
	ds_read_b128 v[148:151], v167 offset:2048
	ds_read_b128 v[172:175], v167 offset:3072
	v_add_u32_e32 v167, s6, v163
	ds_read_b128 v[190:193], v167
	ds_read_b128 v[194:197], v167 offset:1024
	ds_read_b128 v[198:201], v167 offset:2048
	ds_read_b128 v[202:205], v167 offset:3072
	s_add_u32 s4, s14, 0x80000
	s_addc_u32 s5, s15, 0
	s_mov_b32 m0, s30
	ds_read_b128 v[206:209], v166 offset:32768
	ds_read_b128 v[210:213], v166 offset:33792
	ds_read_b128 v[214:217], v166 offset:34816
	ds_read_b128 v[218:221], v166 offset:35840
	ds_read_b128 v[222:225], v166 offset:36864
	ds_read_b128 v[226:229], v166 offset:37888
	ds_read_b128 v[230:233], v166 offset:38912
	ds_read_b128 v[234:237], v166 offset:39936
	global_load_lds_dwordx4 v130, s[4:5]
	v_lshl_add_u64 v[244:245], s[4:5], 0, v[132:133]
	s_mov_b32 m0, s31
	s_nop 0
	global_load_lds_dwordx4 v132, s[4:5]
	s_waitcnt vmcnt(8) lgkmcnt(0)
	s_barrier
	v_mfma_f32_16x16x32_bf16 v[126:129], v[140:143], v[206:209], v[126:129]
	v_mfma_f32_16x16x32_bf16 v[122:125], v[148:151], v[206:209], v[122:125]
	v_mfma_f32_16x16x32_bf16 v[118:121], v[140:143], v[214:217], v[118:121]
	v_mfma_f32_16x16x32_bf16 v[114:117], v[148:151], v[214:217], v[114:117]
	v_mfma_f32_16x16x32_bf16 v[110:113], v[140:143], v[222:225], v[110:113]
	v_mfma_f32_16x16x32_bf16 v[106:109], v[148:151], v[222:225], v[106:109]
	v_mfma_f32_16x16x32_bf16 v[102:105], v[140:143], v[230:233], v[102:105]
	v_mfma_f32_16x16x32_bf16 v[98:101], v[148:151], v[230:233], v[98:101]
	v_mfma_f32_16x16x32_bf16 v[126:129], v[144:147], v[210:213], v[126:129]
	v_mfma_f32_16x16x32_bf16 v[122:125], v[172:175], v[210:213], v[122:125]
	v_mfma_f32_16x16x32_bf16 v[118:121], v[144:147], v[218:221], v[118:121]
	v_mfma_f32_16x16x32_bf16 v[114:117], v[172:175], v[218:221], v[114:117]
	v_mfma_f32_16x16x32_bf16 v[110:113], v[144:147], v[226:229], v[110:113]
	v_mfma_f32_16x16x32_bf16 v[106:109], v[172:175], v[226:229], v[106:109]
	v_mfma_f32_16x16x32_bf16 v[102:105], v[144:147], v[234:237], v[102:105]
	v_mfma_f32_16x16x32_bf16 v[98:101], v[172:175], v[234:237], v[98:101]
	v_mfma_f32_16x16x32_bf16 v[62:65], v[190:193], v[206:209], v[62:65]
	v_mfma_f32_16x16x32_bf16 v[58:61], v[198:201], v[206:209], v[58:61]
	v_mfma_f32_16x16x32_bf16 v[54:57], v[190:193], v[214:217], v[54:57]
	v_mfma_f32_16x16x32_bf16 v[50:53], v[198:201], v[214:217], v[50:53]
	v_mfma_f32_16x16x32_bf16 v[46:49], v[190:193], v[222:225], v[46:49]
	v_mfma_f32_16x16x32_bf16 v[42:45], v[198:201], v[222:225], v[42:45]
	v_mfma_f32_16x16x32_bf16 v[38:41], v[190:193], v[230:233], v[38:41]
	v_mfma_f32_16x16x32_bf16 v[34:37], v[198:201], v[230:233], v[34:37]
	v_mfma_f32_16x16x32_bf16 v[62:65], v[194:197], v[210:213], v[62:65]
	v_mfma_f32_16x16x32_bf16 v[58:61], v[202:205], v[210:213], v[58:61]
	v_mfma_f32_16x16x32_bf16 v[54:57], v[194:197], v[218:221], v[54:57]
	v_mfma_f32_16x16x32_bf16 v[50:53], v[202:205], v[218:221], v[50:53]
	v_mfma_f32_16x16x32_bf16 v[46:49], v[194:197], v[226:229], v[46:49]
	v_mfma_f32_16x16x32_bf16 v[42:45], v[202:205], v[226:229], v[42:45]
	v_mfma_f32_16x16x32_bf16 v[38:41], v[194:197], v[234:237], v[38:41]
	v_mfma_f32_16x16x32_bf16 v[34:37], v[202:205], v[234:237], v[34:37]
	s_barrier
	s_add_i32 s3, s3, s11
	v_lshl_add_u64 v[176:177], v[176:177], 0, s[70:71]
	s_mov_b32 m0, s3
	ds_read_b128 v[206:209], v166 offset:49152
	ds_read_b128 v[210:213], v166 offset:50176
	ds_read_b128 v[214:217], v166 offset:51200
	ds_read_b128 v[218:221], v166 offset:52224
	ds_read_b128 v[222:225], v166 offset:53248
	ds_read_b128 v[226:229], v166 offset:54272
	ds_read_b128 v[230:233], v166 offset:55296
	ds_read_b128 v[234:237], v166 offset:56320
	global_load_lds_dwordx4 v[176:177], off
	s_add_i32 m0, s3, 0x2000
	s_add_u32 s0, s0, 0x80080
	v_lshl_add_u64 v[176:177], v[238:239], 0, s[70:71]
	s_addc_u32 s1, s1, 0
	s_add_i32 s3, s6, s11
	global_load_lds_dwordx4 v[176:177], off
	s_mov_b32 m0, s3
	s_nop 0
	global_load_lds_dwordx4 v4, s[0:1]
	s_add_i32 m0, s3, 0x2000
	s_nop 0
	global_load_lds_dwordx4 v134, s[0:1]
	v_lshl_add_u64 v[176:177], v[240:241], 0, s[70:71]
	s_mov_b32 m0, s34
	s_nop 0
	global_load_lds_dwordx4 v[176:177], off
	v_lshl_add_u64 v[176:177], v[242:243], 0, s[70:71]
	s_mov_b32 m0, s35
	s_nop 0
	global_load_lds_dwordx4 v[176:177], off
	s_waitcnt vmcnt(8) lgkmcnt(0)
	s_barrier
	v_mfma_f32_16x16x32_bf16 v[94:97], v[140:143], v[206:209], v[94:97]
	v_mfma_f32_16x16x32_bf16 v[90:93], v[148:151], v[206:209], v[90:93]
	v_mfma_f32_16x16x32_bf16 v[86:89], v[140:143], v[214:217], v[86:89]
	v_mfma_f32_16x16x32_bf16 v[82:85], v[148:151], v[214:217], v[82:85]
	v_mfma_f32_16x16x32_bf16 v[78:81], v[140:143], v[222:225], v[78:81]
	v_mfma_f32_16x16x32_bf16 v[74:77], v[148:151], v[222:225], v[74:77]
	v_mfma_f32_16x16x32_bf16 v[70:73], v[140:143], v[230:233], v[70:73]
	v_mfma_f32_16x16x32_bf16 v[66:69], v[148:151], v[230:233], v[66:69]
	v_mfma_f32_16x16x32_bf16 v[94:97], v[144:147], v[210:213], v[94:97]
	v_mfma_f32_16x16x32_bf16 v[90:93], v[172:175], v[210:213], v[90:93]
	v_mfma_f32_16x16x32_bf16 v[86:89], v[144:147], v[218:221], v[86:89]
	v_mfma_f32_16x16x32_bf16 v[82:85], v[172:175], v[218:221], v[82:85]
	v_mfma_f32_16x16x32_bf16 v[78:81], v[144:147], v[226:229], v[78:81]
	v_mfma_f32_16x16x32_bf16 v[74:77], v[172:175], v[226:229], v[74:77]
	v_mfma_f32_16x16x32_bf16 v[70:73], v[144:147], v[234:237], v[70:73]
	v_mfma_f32_16x16x32_bf16 v[66:69], v[172:175], v[234:237], v[66:69]
	v_mfma_f32_16x16x32_bf16 v[30:33], v[190:193], v[206:209], v[30:33]
	v_mfma_f32_16x16x32_bf16 v[26:29], v[198:201], v[206:209], v[26:29]
	v_mfma_f32_16x16x32_bf16 v[22:25], v[190:193], v[214:217], v[22:25]
	v_mfma_f32_16x16x32_bf16 v[18:21], v[198:201], v[214:217], v[18:21]
	v_mfma_f32_16x16x32_bf16 v[14:17], v[190:193], v[222:225], v[14:17]
	v_mfma_f32_16x16x32_bf16 v[10:13], v[198:201], v[222:225], v[10:13]
	v_mfma_f32_16x16x32_bf16 v[6:9], v[190:193], v[230:233], v[6:9]
	v_mfma_f32_16x16x32_bf16 v[0:3], v[198:201], v[230:233], v[0:3]
	v_mfma_f32_16x16x32_bf16 v[30:33], v[194:197], v[210:213], v[30:33]
	v_mfma_f32_16x16x32_bf16 v[26:29], v[202:205], v[210:213], v[26:29]
	v_mfma_f32_16x16x32_bf16 v[22:25], v[194:197], v[218:221], v[22:25]
	v_mfma_f32_16x16x32_bf16 v[18:21], v[202:205], v[218:221], v[18:21]
	v_mfma_f32_16x16x32_bf16 v[14:17], v[194:197], v[226:229], v[14:17]
	v_mfma_f32_16x16x32_bf16 v[10:13], v[202:205], v[226:229], v[10:13]
	v_mfma_f32_16x16x32_bf16 v[6:9], v[194:197], v[234:237], v[6:9]
	v_mfma_f32_16x16x32_bf16 v[0:3], v[202:205], v[234:237], v[0:3]
	s_barrier
	s_add_i32 s28, s28, 2
	s_add_u32 s22, s22, 0x100
	s_addc_u32 s23, s23, 0
	s_add_u32 s9, s9, 0x100
	s_addc_u32 s25, s25, 0
	s_cmp_gt_u32 s28, 29
	s_cbranch_scc0 .LBB0_852
	s_and_b64 vcc, exec, s[48:49]
	s_cbranch_vccz .LBB0_855
	s_barrier
